# strategy 7: wave reductions (diff_final, norm_rows, qk_norms, ret group-norm, xn_rows) use DPP row ops + permlane16/32_swap instead of ds_bpermute hops
# speedup vs baseline: 1.0068x; 1.0068x over previous
; __device__ __forceinline__ unsigned pk2(float lo, float hi) { return pg8::cvt_pk_bf16(lo, hi); }
; __device__ __forceinline__ float wave_sum(float v) {
; #pragma unroll
;     for (int o = 1; o < 64; o <<= 1) v += __shfl_xor(v, o);
;     return v;
; }
; __device__ __forceinline__ void xn_rows(const float* x, bfu* XB, float* RS, int gw, int NGW, int lane) {
;     for (int m = gw; m < M; m += NGW) {
;         const f32x4* xr = (const f32x4*)(x + (size_t)m * DM) + lane; f32x4 v[8]; float s = 0.f;
; #pragma unroll
;         for (int j = 0; j < 8; ++j) { v[j] = __builtin_nontemporal_load(xr + 64 * j); s += (v[j].x * v[j].x + v[j].y * v[j].y) + (v[j].z * v[j].z + v[j].w * v[j].w); }
;         const float rstd = 1.f / sqrtf(wave_sum(s) * (1.f / DM) + EPS);
;         v2u* o8 = (v2u*)(XB + (size_t)m * DM) + lane;
; #pragma unroll
;         for (int j = 0; j < 8; ++j) { v2u w; w.x = pk2(v[j].x, v[j].y); w.y = pk2(v[j].z, v[j].w); o8[64 * j] = w; }
;         if (lane == 0) RS[m] = rstd;
;     }
; }
.LBB0_67:
	s_waitcnt lgkmcnt(0)
	global_load_dwordx4 v[14:17], v[2:3], off offset:-4096 nt
	global_load_dwordx4 v[18:21], v[2:3], off offset:-3072 nt
	global_load_dwordx4 v[22:25], v[2:3], off offset:-2048 nt
	global_load_dwordx4 v[26:29], v[2:3], off offset:-1024 nt
	global_load_dwordx4 v[30:33], v[2:3], off nt
	global_load_dwordx4 v[34:37], v[2:3], off offset:1024 nt
	global_load_dwordx4 v[38:41], v[2:3], off offset:2048 nt
	global_load_dwordx4 v[42:45], v[2:3], off offset:3072 nt
	s_waitcnt vmcnt(7)
	v_mul_f32_e32 v13, v15, v15
	v_mul_f32_e32 v46, v17, v17
	s_waitcnt vmcnt(6)
	v_mul_f32_e32 v47, v19, v19
	v_mul_f32_e32 v48, v21, v21
	s_waitcnt vmcnt(5)
	v_mul_f32_e32 v49, v23, v23
	v_mul_f32_e32 v50, v25, v25
	v_fmac_f32_e32 v13, v14, v14
	v_fmac_f32_e32 v46, v16, v16
	v_fmac_f32_e32 v47, v18, v18
	v_fmac_f32_e32 v48, v20, v20
	s_waitcnt vmcnt(4)
	v_mul_f32_e32 v51, v27, v27
	v_mul_f32_e32 v52, v29, v29
	v_fmac_f32_e32 v49, v22, v22
	v_fmac_f32_e32 v50, v24, v24
	v_add_f32_e32 v13, v13, v46
	v_add_f32_e32 v46, v47, v48
	s_waitcnt vmcnt(3)
	v_mul_f32_e32 v53, v31, v31
	v_mul_f32_e32 v54, v33, v33
	v_fmac_f32_e32 v51, v26, v26
	v_fmac_f32_e32 v52, v28, v28
	v_add_f32_e32 v47, v49, v50
	v_add_f32_e32 v13, v13, v46
	s_waitcnt vmcnt(2)
	v_mul_f32_e32 v55, v35, v35
	v_mul_f32_e32 v56, v37, v37
	v_fmac_f32_e32 v53, v30, v30
	v_fmac_f32_e32 v54, v32, v32
	v_add_f32_e32 v48, v51, v52
	v_add_f32_e32 v13, v13, v47
	s_waitcnt vmcnt(1)
	v_mul_f32_e32 v57, v39, v39
	v_mul_f32_e32 v58, v41, v41
	v_fmac_f32_e32 v55, v34, v34
	v_fmac_f32_e32 v56, v36, v36
	v_add_f32_e32 v49, v53, v54
	v_add_f32_e32 v13, v13, v48
	s_waitcnt vmcnt(0)
	v_mul_f32_e32 v59, v43, v43
	v_mul_f32_e32 v60, v45, v45
	v_fmac_f32_e32 v57, v38, v38
	v_fmac_f32_e32 v58, v40, v40
	v_add_f32_e32 v50, v55, v56
	v_add_f32_e32 v13, v13, v49
	v_fmac_f32_e32 v59, v42, v42
	v_fmac_f32_e32 v60, v44, v44
	v_add_f32_e32 v51, v57, v58
	v_add_f32_e32 v13, v13, v50
	v_add_f32_e32 v52, v59, v60
	v_add_f32_e32 v13, v13, v51
	v_add_f32_e32 v13, v13, v52
	v_cvt_pk_bf16_f32 v14, v14, v15
	v_cvt_pk_bf16_f32 v15, v16, v17
	v_cvt_pk_bf16_f32 v16, v18, v19
	v_cvt_pk_bf16_f32 v19, v24, v25
	s_waitcnt lgkmcnt(0)
	s_nop 1
	v_add_f32_dpp v13, v13, v13 quad_perm:[1,0,3,2] row_mask:0xf bank_mask:0xf
	v_cvt_pk_bf16_f32 v17, v20, v21
	v_cvt_pk_bf16_f32 v20, v26, v27
	global_store_dwordx2 v[4:5], v[14:15], off
	global_store_dwordx2 v[4:5], v[16:17], off offset:512
	v_cvt_pk_bf16_f32 v18, v22, v23
	s_nop 1
	v_add_f32_dpp v13, v13, v13 quad_perm:[2,3,0,1] row_mask:0xf bank_mask:0xf
	v_cvt_pk_bf16_f32 v26, v38, v39
	v_cvt_pk_bf16_f32 v16, v42, v43
	v_cvt_pk_bf16_f32 v17, v44, v45
	v_cvt_pk_bf16_f32 v21, v28, v29
	s_nop 1
	v_add_f32_dpp v13, v13, v13 row_half_mirror row_mask:0xf bank_mask:0xf
	v_cvt_pk_bf16_f32 v22, v30, v31
	v_cvt_pk_bf16_f32 v23, v32, v33
	v_cvt_pk_bf16_f32 v24, v34, v35
	v_cvt_pk_bf16_f32 v25, v36, v37
	s_nop 1
	v_add_f32_dpp v13, v13, v13 row_mirror row_mask:0xf bank_mask:0xf
	v_cvt_pk_bf16_f32 v27, v40, v41
	global_store_dwordx2 v[4:5], v[18:19], off offset:1024
	global_store_dwordx2 v[4:5], v[20:21], off offset:1536
	global_store_dwordx2 v[4:5], v[22:23], off offset:2048
	global_store_dwordx2 v[4:5], v[24:25], off offset:2560
	global_store_dwordx2 v[4:5], v[26:27], off offset:3072
	global_store_dwordx2 v[4:5], v[16:17], off offset:3584
	v_mov_b32_e32 v14, v13
	s_nop 1
	v_permlane16_swap_b32_e32 v13, v14
	v_add_f32_e32 v13, v13, v14
	v_mov_b32_e32 v14, v13
	s_nop 1
	v_permlane32_swap_b32_e32 v13, v14
	v_add_f32_e32 v13, v13, v14
	s_and_saveexec_b64 s[24:25], s[4:5]
	s_cbranch_execz .LBB0_66
	s_waitcnt lgkmcnt(0)
	v_fmamk_f32 v13, v13, 0x3a000000, v0
	v_mul_f32_e32 v14, 0x4f800000, v13
	v_cmp_gt_f32_e32 vcc, s15, v13
	s_nop 1
	v_cndmask_b32_e32 v13, v13, v14, vcc
	v_sqrt_f32_e32 v14, v13
	s_nop 0
	v_add_u32_e32 v15, -1, v14
	v_fma_f32 v17, -v15, v14, v13
	v_add_u32_e32 v16, 1, v14
	v_cmp_ge_f32_e64 s[6:7], 0, v17
	s_nop 1
	v_cndmask_b32_e64 v15, v14, v15, s[6:7]
	v_fma_f32 v14, -v16, v14, v13
	v_cmp_lt_f32_e64 s[6:7], 0, v14
	s_nop 1
	v_cndmask_b32_e64 v14, v15, v16, s[6:7]
	v_mul_f32_e32 v15, 0x37800000, v14
	v_cndmask_b32_e32 v14, v14, v15, vcc
	v_cmp_class_f32_e32 vcc, v13, v9
	s_nop 1
	v_cndmask_b32_e32 v13, v14, v13, vcc
	v_div_scale_f32 v14, s[6:7], v13, v13, 1.0
	v_rcp_f32_e32 v15, v14
	s_nop 0
	v_fma_f32 v16, -v14, v15, 1.0
	v_fmac_f32_e32 v15, v16, v15
	v_div_scale_f32 v16, vcc, 1.0, v13, 1.0
	v_mul_f32_e32 v17, v16, v15
	v_fma_f32 v18, -v14, v17, v16
	v_fmac_f32_e32 v17, v18, v15
	v_fma_f32 v14, -v14, v17, v16
	v_div_fmas_f32 v14, v14, v15, v17
	v_div_fixup_f32 v13, v14, v13, 1.0
	global_store_dword v1, v13, s[16:17]
	s_branch .LBB0_66

; __device__ __forceinline__ float wave_sum(float v) {
; #pragma unroll
;     for (int o = 1; o < 64; o <<= 1) v += __shfl_xor(v, o);
;     return v;
; }
; __device__ __forceinline__ void qk_norms(LAS unsigned char* lds, const bfu* PROJ, unsigned* nw) {
;     ...
;     for (int mb = gw; mb < M; mb += 4 * NGW) {
;         v4u w[4][3];
; #pragma unroll
;         for (int r = 0; r < 4; ++r) { const int m = mb + r * NGW; const bfu* rp = PROJ + (size_t)(m < M ? m : mb) * INW + C_DQ + lane * 8;
; #pragma unroll
;             for (int ld = 0; ld < 3; ++ld) w[r][ld] = *(const v4u*)(rp + ld * 512); }
; #pragma unroll
;         for (int r = 0; r < 4; ++r) { const int m = mb + r * NGW; if (m >= M) break; float s[3];
; #pragma unroll
;             for (int ld = 0; ld < 3; ++ld) { float a = 0.f;
; #pragma unroll
;                 for (int j = 0; j < 4; ++j) { const float lo = bflo(w[r][ld][j]), hi = bfhi(w[r][ld][j]); a += lo * lo + hi * hi; }
;                 a += __shfl_xor(a, 1); a += __shfl_xor(a, 2); a += __shfl_xor(a, 4); s[ld] = a; }
;             if (m >= SEQ) { m1[0] = fmaxf(m1[0], s[0]); m1[1] = fmaxf(m1[1], s[1]); m1[2] = fmaxf(m1[2], s[2]); }
;             else          { m0[0] = fmaxf(m0[0], s[0]); m0[1] = fmaxf(m0[1], s[1]); m0[2] = fmaxf(m0[2], s[2]); } }
.LBB0_204:
	s_add_i32 s42, s22, s54
	s_cmpk_lt_i32 s42, 0x4000
	s_cselect_b64 s[38:39], -1, 0
	s_and_b64 s[26:27], s[38:39], exec
	s_cselect_b32 s23, s42, s22
	s_mul_hi_i32 s27, s23, 0x3200
	s_mulk_i32 s23, 0x3200
	s_add_u32 s26, s40, s23
	s_addc_u32 s27, s41, s27
	s_add_i32 s44, s55, s22
	s_cmpk_lt_i32 s44, 0x4000
	s_cselect_b64 s[36:37], -1, 0
	v_lshl_add_u64 v[2:3], s[26:27], 0, v[0:1]
	s_and_b64 s[26:27], s[36:37], exec
	s_cselect_b32 s23, s44, s22
	s_mul_hi_i32 s27, s23, 0x3200
	s_mulk_i32 s23, 0x3200
	s_mov_b64 s[46:47], 0x1800
	s_add_u32 s26, s40, s23
	s_mul_i32 s43, s3, 24
	v_lshl_add_u64 v[4:5], v[2:3], 0, s[46:47]
	v_add_co_u32_e32 v2, vcc, s62, v2
	s_addc_u32 s27, s41, s27
	s_add_i32 s43, s43, s22
	v_addc_co_u32_e32 v3, vcc, 0, v3, vcc
	s_cmpk_lt_i32 s43, 0x4000
	global_load_dwordx4 v[34:37], v[2:3], off offset:2048
	global_load_dwordx4 v[30:33], v[4:5], off offset:1024
	global_load_dwordx4 v[26:29], v[4:5], off offset:2048
	v_lshl_add_u64 v[2:3], s[26:27], 0, v[0:1]
	s_cselect_b64 s[26:27], -1, 0
	s_and_b64 s[34:35], s[26:27], exec
	s_cselect_b32 s23, s43, s22
	s_mul_hi_i32 s35, s23, 0x3200
	s_mulk_i32 s23, 0x3200
	v_lshl_add_u64 v[4:5], v[2:3], 0, s[46:47]
	v_add_co_u32_e32 v2, vcc, s62, v2
	s_add_u32 s34, s40, s23
	s_nop 0
	v_addc_co_u32_e32 v3, vcc, 0, v3, vcc
	s_addc_u32 s35, s41, s35
	global_load_dwordx4 v[22:25], v[2:3], off offset:2048
	global_load_dwordx4 v[18:21], v[4:5], off offset:1024
	global_load_dwordx4 v[14:17], v[4:5], off offset:2048
	v_lshl_add_u64 v[2:3], s[34:35], 0, v[0:1]
	s_mul_i32 s34, s22, 0x3200
	s_mul_hi_i32 s23, s22, 0x3200
	s_add_u32 s34, s40, s34
	v_lshl_add_u64 v[4:5], v[2:3], 0, s[46:47]
	v_add_co_u32_e32 v2, vcc, s62, v2
	s_addc_u32 s35, s41, s23
	s_nop 0
	v_addc_co_u32_e32 v3, vcc, 0, v3, vcc
	v_lshl_add_u64 v[58:59], s[34:35], 0, v[0:1]
	v_lshl_add_u64 v[42:43], v[58:59], 0, s[46:47]
	v_add_co_u32_e32 v58, vcc, s62, v58
	global_load_dwordx4 v[10:13], v[2:3], off offset:2048
	global_load_dwordx4 v[6:9], v[4:5], off offset:1024
	s_nop 0
	global_load_dwordx4 v[2:5], v[4:5], off offset:2048
	v_addc_co_u32_e32 v59, vcc, 0, v59, vcc
	global_load_dwordx4 v[38:41], v[42:43], off offset:2048
	s_nop 0
	global_load_dwordx4 v[42:45], v[42:43], off offset:1024
	s_mov_b64 s[34:35], -1
	global_load_dwordx4 v[58:61], v[58:59], off offset:2048
	s_cmpk_lt_i32 s22, 0x2000
	s_waitcnt vmcnt(0)
	v_lshlrev_b32_e32 v62, 16, v58
	v_and_b32_e32 v58, 0xffff0000, v58
	v_mul_f32_e32 v58, v58, v58
	v_fmac_f32_e32 v58, v62, v62
	v_lshlrev_b32_e32 v62, 16, v59
	v_and_b32_e32 v59, 0xffff0000, v59
	v_mul_f32_e32 v59, v59, v59
	v_fmac_f32_e32 v59, v62, v62
	v_add_f32_e32 v58, v58, v59
	v_lshlrev_b32_e32 v59, 16, v60
	v_and_b32_e32 v60, 0xffff0000, v60
	v_mul_f32_e32 v60, v60, v60
	v_fmac_f32_e32 v60, v59, v59
	v_add_f32_e32 v58, v60, v58
	v_and_b32_e32 v60, 0xffff0000, v61
	v_lshlrev_b32_e32 v59, 16, v61
	v_mul_f32_e32 v60, v60, v60
	v_fmac_f32_e32 v60, v59, v59
	v_add_f32_e32 v58, v60, v58
	s_waitcnt lgkmcnt(0)
	s_nop 1
	v_add_f32_dpp v58, v58, v58 quad_perm:[1,0,3,2] row_mask:0xf bank_mask:0xf
	s_nop 1
	v_add_f32_dpp v58, v58, v58 quad_perm:[2,3,0,1] row_mask:0xf bank_mask:0xf
	s_nop 1
	v_add_f32_dpp v58, v58, v58 row_half_mirror row_mask:0xf bank_mask:0xf
	v_lshlrev_b32_e32 v59, 16, v42
	v_and_b32_e32 v42, 0xffff0000, v42
	v_mul_f32_e32 v42, v42, v42
	v_fmac_f32_e32 v42, v59, v59
	v_lshlrev_b32_e32 v59, 16, v43
	v_and_b32_e32 v43, 0xffff0000, v43
	v_mul_f32_e32 v43, v43, v43
	v_fmac_f32_e32 v43, v59, v59
	v_add_f32_e32 v42, v42, v43
	v_lshlrev_b32_e32 v43, 16, v44
	v_and_b32_e32 v44, 0xffff0000, v44
	v_mul_f32_e32 v44, v44, v44
	v_fmac_f32_e32 v44, v43, v43
	v_add_f32_e32 v42, v44, v42
	v_and_b32_e32 v44, 0xffff0000, v45
	v_lshlrev_b32_e32 v43, 16, v45
	v_mul_f32_e32 v44, v44, v44
	v_fmac_f32_e32 v44, v43, v43
	v_add_f32_e32 v42, v44, v42
	s_waitcnt lgkmcnt(0)
	s_nop 1
	v_add_f32_dpp v42, v42, v42 quad_perm:[1,0,3,2] row_mask:0xf bank_mask:0xf
	s_nop 1
	v_add_f32_dpp v42, v42, v42 quad_perm:[2,3,0,1] row_mask:0xf bank_mask:0xf
	s_nop 1
	v_add_f32_dpp v42, v42, v42 row_half_mirror row_mask:0xf bank_mask:0xf
	v_lshlrev_b32_e32 v43, 16, v38
	v_and_b32_e32 v38, 0xffff0000, v38
	v_mul_f32_e32 v38, v38, v38
	v_fmac_f32_e32 v38, v43, v43
	v_lshlrev_b32_e32 v43, 16, v39
	v_and_b32_e32 v39, 0xffff0000, v39
	v_mul_f32_e32 v39, v39, v39
	v_fmac_f32_e32 v39, v43, v43
	v_add_f32_e32 v38, v38, v39
	v_lshlrev_b32_e32 v39, 16, v40
	v_and_b32_e32 v40, 0xffff0000, v40
	v_mul_f32_e32 v40, v40, v40
	v_fmac_f32_e32 v40, v39, v39
	v_add_f32_e32 v38, v40, v38
	v_and_b32_e32 v40, 0xffff0000, v41
	v_lshlrev_b32_e32 v39, 16, v41
	v_mul_f32_e32 v40, v40, v40
	v_fmac_f32_e32 v40, v39, v39
	v_add_f32_e32 v38, v40, v38
	s_waitcnt lgkmcnt(0)
	s_nop 1
	v_add_f32_dpp v38, v38, v38 quad_perm:[1,0,3,2] row_mask:0xf bank_mask:0xf
	s_nop 1
	v_add_f32_dpp v38, v38, v38 quad_perm:[2,3,0,1] row_mask:0xf bank_mask:0xf
	s_nop 1
	v_add_f32_dpp v38, v38, v38 row_half_mirror row_mask:0xf bank_mask:0xf
	s_cbranch_scc0 .LBB0_206
	v_max_f32_e32 v39, v58, v58
	v_max_f32_e32 v40, v52, v52
	v_max_f32_e32 v39, v40, v39
	v_max_f32_e32 v40, v42, v42
	v_max_f32_e32 v41, v54, v54
	v_max_f32_e32 v40, v41, v40
	v_max_f32_e32 v41, v38, v38
	v_max_f32_e32 v43, v53, v53
	v_max_f32_e32 v41, v43, v41
	s_mov_b64 s[34:35], 0

; __device__ __forceinline__ float wave_sum(float v) {
; #pragma unroll
;     for (int o = 1; o < 64; o <<= 1) v += __shfl_xor(v, o);
;     return v;
; }
; __device__ __forceinline__ void qk_norms(LAS unsigned char* lds, const bfu* PROJ, unsigned* nw) {
;     ...
;         for (int r = 0; r < 4; ++r) { const int m = mb + r * NGW; if (m >= M) break; float s[3];
; #pragma unroll
;             for (int ld = 0; ld < 3; ++ld) { float a = 0.f;
; #pragma unroll
;                 for (int j = 0; j < 4; ++j) { const float lo = bflo(w[r][ld][j]), hi = bfhi(w[r][ld][j]); a += lo * lo + hi * hi; }
;                 a += __shfl_xor(a, 1); a += __shfl_xor(a, 2); a += __shfl_xor(a, 4); s[ld] = a; }
;             if (m >= SEQ) { m1[0] = fmaxf(m1[0], s[0]); m1[1] = fmaxf(m1[1], s[1]); m1[2] = fmaxf(m1[2], s[2]); }
;             else          { m0[0] = fmaxf(m0[0], s[0]); m0[1] = fmaxf(m0[1], s[1]); m0[2] = fmaxf(m0[2], s[2]); } }
.LBB0_209:
	v_lshlrev_b32_e32 v38, 16, v34
	v_and_b32_e32 v34, 0xffff0000, v34
	v_mul_f32_e32 v34, v34, v34
	v_fmac_f32_e32 v34, v38, v38
	v_lshlrev_b32_e32 v38, 16, v35
	v_and_b32_e32 v35, 0xffff0000, v35
	v_mul_f32_e32 v35, v35, v35
	v_fmac_f32_e32 v35, v38, v38
	v_add_f32_e32 v34, v34, v35
	v_lshlrev_b32_e32 v35, 16, v36
	v_and_b32_e32 v36, 0xffff0000, v36
	v_mul_f32_e32 v36, v36, v36
	v_fmac_f32_e32 v36, v35, v35
	v_add_f32_e32 v34, v36, v34
	v_and_b32_e32 v36, 0xffff0000, v37
	v_lshlrev_b32_e32 v35, 16, v37
	v_mul_f32_e32 v36, v36, v36
	v_fmac_f32_e32 v36, v35, v35
	v_add_f32_e32 v34, v36, v34
	v_lshlrev_b32_e32 v36, 16, v30
	v_and_b32_e32 v30, 0xffff0000, v30
	v_mul_f32_e32 v30, v30, v30
	v_fmac_f32_e32 v30, v36, v36
	v_lshlrev_b32_e32 v36, 16, v31
	v_and_b32_e32 v31, 0xffff0000, v31
	v_mul_f32_e32 v31, v31, v31
	v_fmac_f32_e32 v31, v36, v36
	v_add_f32_e32 v30, v30, v31
	v_lshlrev_b32_e32 v31, 16, v32
	v_and_b32_e32 v32, 0xffff0000, v32
	v_mul_f32_e32 v32, v32, v32
	v_fmac_f32_e32 v32, v31, v31
	v_add_f32_e32 v30, v32, v30
	v_and_b32_e32 v32, 0xffff0000, v33
	v_lshlrev_b32_e32 v31, 16, v33
	v_mul_f32_e32 v32, v32, v32
	v_fmac_f32_e32 v32, v31, v31
	v_add_f32_e32 v30, v32, v30
	v_lshlrev_b32_e32 v32, 16, v26
	v_and_b32_e32 v26, 0xffff0000, v26
	v_mul_f32_e32 v26, v26, v26
	v_fmac_f32_e32 v26, v32, v32
	v_lshlrev_b32_e32 v32, 16, v27
	v_and_b32_e32 v27, 0xffff0000, v27
	v_mul_f32_e32 v27, v27, v27
	v_fmac_f32_e32 v27, v32, v32
	v_add_f32_e32 v26, v26, v27
	v_lshlrev_b32_e32 v27, 16, v28
	v_and_b32_e32 v28, 0xffff0000, v28
	v_mul_f32_e32 v28, v28, v28
	v_fmac_f32_e32 v28, v27, v27
	v_add_f32_e32 v26, v28, v26
	v_and_b32_e32 v28, 0xffff0000, v29
	v_lshlrev_b32_e32 v27, 16, v29
	v_mul_f32_e32 v28, v28, v28
	v_fmac_f32_e32 v28, v27, v27
	v_add_f32_e32 v26, v28, v26
	s_cmpk_gt_i32 s42, 0x1fff
	s_mov_b64 s[34:35], -1
	v_add_f32_dpp v28, v34, v34 quad_perm:[1,0,3,2] row_mask:0xf bank_mask:0xf
	v_add_f32_dpp v30, v30, v30 quad_perm:[1,0,3,2] row_mask:0xf bank_mask:0xf
	s_waitcnt lgkmcnt(0)
	v_add_f32_dpp v26, v26, v26 quad_perm:[1,0,3,2] row_mask:0xf bank_mask:0xf
	v_add_f32_dpp v28, v28, v28 quad_perm:[2,3,0,1] row_mask:0xf bank_mask:0xf
	v_add_f32_dpp v30, v30, v30 quad_perm:[2,3,0,1] row_mask:0xf bank_mask:0xf
	s_waitcnt lgkmcnt(0)
	v_add_f32_dpp v26, v26, v26 quad_perm:[2,3,0,1] row_mask:0xf bank_mask:0xf
	v_add_f32_dpp v28, v28, v28 row_half_mirror row_mask:0xf bank_mask:0xf
	v_add_f32_dpp v27, v30, v30 row_half_mirror row_mask:0xf bank_mask:0xf
	s_waitcnt lgkmcnt(0)
	v_add_f32_dpp v26, v26, v26 row_half_mirror row_mask:0xf bank_mask:0xf
	s_cbranch_scc1 .LBB0_211
	v_max_f32_e32 v29, v28, v28
	v_max_f32_e32 v30, v52, v52
	v_max_f32_e32 v29, v30, v29
	v_max_f32_e32 v30, v27, v27
	v_max_f32_e32 v31, v54, v54
	v_max_f32_e32 v30, v31, v30
	v_max_f32_e32 v31, v26, v26
	v_max_f32_e32 v32, v53, v53
	v_max_f32_e32 v31, v32, v31
	s_mov_b64 s[34:35], 0

; __device__ __forceinline__ float wave_sum(float v) {
; #pragma unroll
;     for (int o = 1; o < 64; o <<= 1) v += __shfl_xor(v, o);
;     return v;
; }
; __device__ __forceinline__ void qk_norms(LAS unsigned char* lds, const bfu* PROJ, unsigned* nw) {
;     ...
;         for (int r = 0; r < 4; ++r) { const int m = mb + r * NGW; if (m >= M) break; float s[3];
; #pragma unroll
;             for (int ld = 0; ld < 3; ++ld) { float a = 0.f;
; #pragma unroll
;                 for (int j = 0; j < 4; ++j) { const float lo = bflo(w[r][ld][j]), hi = bfhi(w[r][ld][j]); a += lo * lo + hi * hi; }
;                 a += __shfl_xor(a, 1); a += __shfl_xor(a, 2); a += __shfl_xor(a, 4); s[ld] = a; }
;             if (m >= SEQ) { m1[0] = fmaxf(m1[0], s[0]); m1[1] = fmaxf(m1[1], s[1]); m1[2] = fmaxf(m1[2], s[2]); }
;             else          { m0[0] = fmaxf(m0[0], s[0]); m0[1] = fmaxf(m0[1], s[1]); m0[2] = fmaxf(m0[2], s[2]); } }
.LBB0_214:
	v_lshlrev_b32_e32 v26, 16, v22
	v_and_b32_e32 v22, 0xffff0000, v22
	v_mul_f32_e32 v22, v22, v22
	v_fmac_f32_e32 v22, v26, v26
	v_lshlrev_b32_e32 v26, 16, v23
	v_and_b32_e32 v23, 0xffff0000, v23
	v_mul_f32_e32 v23, v23, v23
	v_fmac_f32_e32 v23, v26, v26
	v_add_f32_e32 v22, v22, v23
	v_lshlrev_b32_e32 v23, 16, v24
	v_and_b32_e32 v24, 0xffff0000, v24
	v_mul_f32_e32 v24, v24, v24
	v_fmac_f32_e32 v24, v23, v23
	v_add_f32_e32 v22, v24, v22
	v_and_b32_e32 v24, 0xffff0000, v25
	v_lshlrev_b32_e32 v23, 16, v25
	v_mul_f32_e32 v24, v24, v24
	v_fmac_f32_e32 v24, v23, v23
	v_add_f32_e32 v22, v24, v22
	v_lshlrev_b32_e32 v24, 16, v18
	v_and_b32_e32 v18, 0xffff0000, v18
	v_mul_f32_e32 v18, v18, v18
	v_fmac_f32_e32 v18, v24, v24
	v_lshlrev_b32_e32 v24, 16, v19
	v_and_b32_e32 v19, 0xffff0000, v19
	v_mul_f32_e32 v19, v19, v19
	v_fmac_f32_e32 v19, v24, v24
	v_add_f32_e32 v18, v18, v19
	v_lshlrev_b32_e32 v19, 16, v20
	v_and_b32_e32 v20, 0xffff0000, v20
	v_mul_f32_e32 v20, v20, v20
	v_fmac_f32_e32 v20, v19, v19
	v_add_f32_e32 v18, v20, v18
	v_and_b32_e32 v20, 0xffff0000, v21
	v_lshlrev_b32_e32 v19, 16, v21
	v_mul_f32_e32 v20, v20, v20
	v_fmac_f32_e32 v20, v19, v19
	v_add_f32_e32 v18, v20, v18
	v_lshlrev_b32_e32 v20, 16, v14
	v_and_b32_e32 v14, 0xffff0000, v14
	v_mul_f32_e32 v14, v14, v14
	v_fmac_f32_e32 v14, v20, v20
	v_lshlrev_b32_e32 v20, 16, v15
	v_and_b32_e32 v15, 0xffff0000, v15
	v_mul_f32_e32 v15, v15, v15
	v_fmac_f32_e32 v15, v20, v20
	v_add_f32_e32 v14, v14, v15
	v_lshlrev_b32_e32 v15, 16, v16
	v_and_b32_e32 v16, 0xffff0000, v16
	v_mul_f32_e32 v16, v16, v16
	v_fmac_f32_e32 v16, v15, v15
	v_add_f32_e32 v14, v16, v14
	v_and_b32_e32 v16, 0xffff0000, v17
	v_lshlrev_b32_e32 v15, 16, v17
	v_mul_f32_e32 v16, v16, v16
	v_fmac_f32_e32 v16, v15, v15
	v_add_f32_e32 v14, v16, v14
	s_mov_b64 s[34:35], -1
	s_cmpk_gt_i32 s44, 0x1fff
	v_add_f32_dpp v16, v22, v22 quad_perm:[1,0,3,2] row_mask:0xf bank_mask:0xf
	v_add_f32_dpp v18, v18, v18 quad_perm:[1,0,3,2] row_mask:0xf bank_mask:0xf
	s_waitcnt lgkmcnt(0)
	v_add_f32_dpp v14, v14, v14 quad_perm:[1,0,3,2] row_mask:0xf bank_mask:0xf
	v_add_f32_dpp v16, v16, v16 quad_perm:[2,3,0,1] row_mask:0xf bank_mask:0xf
	v_add_f32_dpp v18, v18, v18 quad_perm:[2,3,0,1] row_mask:0xf bank_mask:0xf
	s_waitcnt lgkmcnt(0)
	v_add_f32_dpp v14, v14, v14 quad_perm:[2,3,0,1] row_mask:0xf bank_mask:0xf
	v_add_f32_dpp v16, v16, v16 row_half_mirror row_mask:0xf bank_mask:0xf
	v_add_f32_dpp v17, v18, v18 row_half_mirror row_mask:0xf bank_mask:0xf
	s_waitcnt lgkmcnt(0)
	v_add_f32_dpp v14, v14, v14 row_half_mirror row_mask:0xf bank_mask:0xf
	v_max_f32_e32 v16, v16, v16
	v_max_f32_e32 v15, v17, v17
	v_max_f32_e32 v14, v14, v14
	s_cbranch_scc1 .LBB0_216
	v_max_f32_e32 v17, v52, v52
	v_max_f32_e32 v19, v17, v16
	v_max_f32_e32 v17, v54, v54
	v_max_f32_e32 v18, v17, v15
	v_max_f32_e32 v17, v53, v53
	v_max_f32_e32 v17, v17, v14
	s_mov_b64 s[34:35], 0

; __device__ __forceinline__ float wave_sum(float v) {
; #pragma unroll
;     for (int o = 1; o < 64; o <<= 1) v += __shfl_xor(v, o);
;     return v;
; }
; __device__ __forceinline__ void qk_norms(LAS unsigned char* lds, const bfu* PROJ, unsigned* nw) {
;     ...
;         for (int r = 0; r < 4; ++r) { const int m = mb + r * NGW; if (m >= M) break; float s[3];
; #pragma unroll
;             for (int ld = 0; ld < 3; ++ld) { float a = 0.f;
; #pragma unroll
;                 for (int j = 0; j < 4; ++j) { const float lo = bflo(w[r][ld][j]), hi = bfhi(w[r][ld][j]); a += lo * lo + hi * hi; }
;                 a += __shfl_xor(a, 1); a += __shfl_xor(a, 2); a += __shfl_xor(a, 4); s[ld] = a; }
;             if (m >= SEQ) { m1[0] = fmaxf(m1[0], s[0]); m1[1] = fmaxf(m1[1], s[1]); m1[2] = fmaxf(m1[2], s[2]); }
;             else          { m0[0] = fmaxf(m0[0], s[0]); m0[1] = fmaxf(m0[1], s[1]); m0[2] = fmaxf(m0[2], s[2]); } }
.LBB0_219:
	v_lshlrev_b32_e32 v14, 16, v10
	v_and_b32_e32 v10, 0xffff0000, v10
	v_mul_f32_e32 v10, v10, v10
	v_fmac_f32_e32 v10, v14, v14
	v_lshlrev_b32_e32 v14, 16, v11
	v_and_b32_e32 v11, 0xffff0000, v11
	v_mul_f32_e32 v11, v11, v11
	v_fmac_f32_e32 v11, v14, v14
	v_add_f32_e32 v10, v10, v11
	v_lshlrev_b32_e32 v11, 16, v12
	v_and_b32_e32 v12, 0xffff0000, v12
	v_mul_f32_e32 v12, v12, v12
	v_fmac_f32_e32 v12, v11, v11
	v_add_f32_e32 v10, v12, v10
	v_and_b32_e32 v12, 0xffff0000, v13
	v_lshlrev_b32_e32 v11, 16, v13
	v_mul_f32_e32 v12, v12, v12
	v_fmac_f32_e32 v12, v11, v11
	v_add_f32_e32 v10, v12, v10
	v_lshlrev_b32_e32 v12, 16, v6
	v_and_b32_e32 v6, 0xffff0000, v6
	v_mul_f32_e32 v6, v6, v6
	v_fmac_f32_e32 v6, v12, v12
	v_lshlrev_b32_e32 v12, 16, v7
	v_and_b32_e32 v7, 0xffff0000, v7
	v_mul_f32_e32 v7, v7, v7
	v_fmac_f32_e32 v7, v12, v12
	v_add_f32_e32 v6, v6, v7
	v_lshlrev_b32_e32 v7, 16, v8
	v_and_b32_e32 v8, 0xffff0000, v8
	v_mul_f32_e32 v8, v8, v8
	v_fmac_f32_e32 v8, v7, v7
	v_add_f32_e32 v6, v8, v6
	v_and_b32_e32 v8, 0xffff0000, v9
	v_lshlrev_b32_e32 v7, 16, v9
	v_mul_f32_e32 v8, v8, v8
	v_fmac_f32_e32 v8, v7, v7
	v_add_f32_e32 v6, v8, v6
	v_lshlrev_b32_e32 v8, 16, v2
	v_and_b32_e32 v2, 0xffff0000, v2
	v_mul_f32_e32 v2, v2, v2
	v_fmac_f32_e32 v2, v8, v8
	v_lshlrev_b32_e32 v8, 16, v3
	v_and_b32_e32 v3, 0xffff0000, v3
	v_mul_f32_e32 v3, v3, v3
	v_fmac_f32_e32 v3, v8, v8
	v_add_f32_e32 v2, v2, v3
	v_lshlrev_b32_e32 v3, 16, v4
	v_and_b32_e32 v4, 0xffff0000, v4
	v_mul_f32_e32 v4, v4, v4
	v_fmac_f32_e32 v4, v3, v3
	v_add_f32_e32 v2, v4, v2
	v_and_b32_e32 v4, 0xffff0000, v5
	v_lshlrev_b32_e32 v3, 16, v5
	v_mul_f32_e32 v4, v4, v4
	v_fmac_f32_e32 v4, v3, v3
	v_add_f32_e32 v2, v4, v2
	s_mov_b64 s[26:27], -1
	s_cmpk_gt_i32 s43, 0x1fff
	v_add_f32_dpp v4, v10, v10 quad_perm:[1,0,3,2] row_mask:0xf bank_mask:0xf
	v_add_f32_dpp v6, v6, v6 quad_perm:[1,0,3,2] row_mask:0xf bank_mask:0xf
	s_waitcnt lgkmcnt(0)
	v_add_f32_dpp v2, v2, v2 quad_perm:[1,0,3,2] row_mask:0xf bank_mask:0xf
	v_add_f32_dpp v4, v4, v4 quad_perm:[2,3,0,1] row_mask:0xf bank_mask:0xf
	v_add_f32_dpp v6, v6, v6 quad_perm:[2,3,0,1] row_mask:0xf bank_mask:0xf
	s_waitcnt lgkmcnt(0)
	v_add_f32_dpp v2, v2, v2 quad_perm:[2,3,0,1] row_mask:0xf bank_mask:0xf
	v_add_f32_dpp v4, v4, v4 row_half_mirror row_mask:0xf bank_mask:0xf
	v_add_f32_dpp v5, v6, v6 row_half_mirror row_mask:0xf bank_mask:0xf
	s_waitcnt lgkmcnt(0)
	v_add_f32_dpp v2, v2, v2 row_half_mirror row_mask:0xf bank_mask:0xf
	v_max_f32_e32 v4, v4, v4
	v_max_f32_e32 v3, v5, v5
	v_max_f32_e32 v2, v2, v2
	s_cbranch_scc1 .LBB0_221
	v_max_f32_e32 v5, v52, v52
	v_max_f32_e32 v6, v54, v54
	v_max_f32_e32 v7, v53, v53
	v_max_f32_e32 v5, v5, v4
	v_max_f32_e32 v6, v6, v3
	v_max_f32_e32 v7, v7, v2
	s_mov_b64 s[26:27], 0

; #define LAS __attribute__((address_space(3)))
; __device__ __forceinline__ float ret_log2gamma(int h) { return log2f(1.f - exp2f(-5.f - (float)h)); }
; __device__ __forceinline__ void ret_unit(LAS unsigned char* lds, const bfu* PROJ, const bfu* RT, const float* gn_g, bfu* CAT, int u) {
;     int tid = threadIdx.x; asm volatile("" : "+v"(tid)); const int lane = tid & 63, wid = __builtin_amdgcn_readfirstlane(tid >> 6); (void)lane; (void)wid;
;     const int bh = u >> 6, i = u & 63, b = bh / 6, h = bh % 6; const size_t row0 = (size_t)b * SEQ + (size_t)i * 128; const float lg = ret_log2gamma(h);
;     LAS bfu* Qs = (LAS bfu*)lds; LAS bfu* Ks = (LAS bfu*)(lds + TILE_B); LAS bfu* Vt = (LAS bfu*)(lds + 2 * TILE_B); LAS bfu* Rt = (LAS bfu*)(lds + 3 * TILE_B);
;     const bfu* P0 = PROJ + row0 * INW + h * 128;
;     stage_nat(Qs, P0 + C_RQ, INW, tid); stage_nat(Ks, P0 + C_RK, INW, tid); stage_tr<false>(Vt, P0 + C_RV, INW, tid, 0.f); stage_nat(Rt, RT + (size_t)u * 16384, 128, tid);
.LBB0_410:
	s_or_b64 exec, exec, s[40:41]
	s_mov_b32 s22, 21
	s_barrier
	s_ashr_i32 s23, s22, 31
	s_lshl_b64 s[22:23], s[22:23], 3
	s_add_u32 s22, s0, s22
	s_addc_u32 s23, s1, s23
	s_load_dwordx2 s[48:49], s[22:23], 0x0
	s_mov_b32 s22, 21
	s_ashr_i32 s23, s22, 31
	s_lshl_b64 s[22:23], s[22:23], 3
	s_add_u32 s22, s0, s22
	s_addc_u32 s23, s1, s23
	s_load_dwordx2 s[40:41], s[22:23], 0x0
	s_mov_b32 s22, 3
	s_ashr_i32 s23, s22, 31
	s_lshl_b64 s[22:23], s[22:23], 3
	s_add_u32 s22, s0, s22
	s_addc_u32 s23, s1, s23
	s_load_dwordx2 s[22:23], s[22:23], 0x0
	v_mov_b32_e32 v10, v232
	v_readlane_b32 s91, v255, 54
	s_waitcnt lgkmcnt(0)
	s_add_u32 s20, s22, s36
	s_mov_b32 s22, 21
	s_addc_u32 s35, s23, s37
	s_ashr_i32 s23, s22, 31
	s_lshl_b64 s[22:23], s[22:23], 3
	s_add_u32 s22, s0, s22
	s_addc_u32 s23, s1, s23
	s_load_dwordx2 s[44:45], s[22:23], 0x0
	s_mul_hi_i32 s23, s34, 0x2aaaaaab
	s_lshr_b32 s46, s23, 31
	s_add_i32 s46, s23, s46
	s_mul_i32 s23, s46, 6
	s_sub_i32 s23, s34, s23
	v_cvt_f32_i32_e32 v0, s23
	s_ashr_i32 s47, s46, 31
	s_lshl_b32 s34, s92, 7
	s_lshl_b64 s[46:47], s[46:47], 13
	v_sub_f32_e32 v0, 0xc0a00000, v0
	v_cmp_gt_f32_e32 vcc, s64, v0
	s_and_b32 s34, s34, 0x1f80
	s_or_b32 s46, s46, s34
	v_cndmask_b32_e32 v2, 0, v241, vcc
	v_add_f32_e32 v0, v0, v2
	v_exp_f32_e32 v0, v0
	s_and_b64 s[50:51], vcc, exec
	s_cselect_b32 s34, 0xffffffc0, 0
	s_mul_hi_u32 s50, s46, 0x3200
	v_ldexp_f32 v0, v0, s34
	s_mul_i32 s34, s47, 0x3200
	s_add_i32 s50, s50, s34
	s_mul_i32 s34, s46, 0x3200
	s_add_u32 s34, s48, s34
	s_addc_u32 s48, s49, s50
	s_lshl_b32 s50, s23, 7
	s_ashr_i32 s51, s50, 31
	s_lshl_b64 s[52:53], s[50:51], 1
	s_add_u32 s23, s34, s52
	s_addc_u32 s34, s48, s53
	v_sub_f32_e32 v11, 1.0, v0
	s_add_u32 s56, s23, 0x1ce00000
	v_lshlrev_b32_e32 v0, 4, v10
	s_addc_u32 s57, s34, 0
	v_and_b32_e32 v0, 0xf0, v0
	v_lshl_add_u64 v[16:17], s[56:57], 0, v[0:1]
	v_ashrrev_i32_e32 v2, 4, v10
	v_mad_i64_i32 v[18:19], s[48:49], v2, s61, v[16:17]
	global_load_dwordx4 v[120:123], v[18:19], off
	v_add_u32_e32 v26, 0, v0
	v_mul_lo_u32 v27, v2, s65
	v_add_u32_e32 v28, v26, v27
	s_ashr_i32 s93, s92, 31
	v_ashrrev_i32_e32 v3, 31, v2
	v_readfirstlane_b32 s22, v10
	v_bfe_u32 v71, v10, 4, 2
	v_lshlrev_b32_e32 v69, 4, v71
	v_add_u32_e32 v4, 0x200, v10
	v_ashrrev_i32_e32 v4, 4, v4
	v_mad_i64_i32 v[20:21], s[48:49], v4, s61, v[16:17]
	global_load_dwordx4 v[124:127], v[20:21], off
	v_mul_lo_u32 v29, v4, s65
	v_add_u32_e32 v30, v26, v29
	v_ashrrev_i32_e32 v5, 31, v4
	v_add_u32_e32 v6, 0x400, v10
	v_ashrrev_i32_e32 v6, 4, v6
	v_mad_i64_i32 v[22:23], s[48:49], v6, s61, v[16:17]
	global_load_dwordx4 v[128:131], v[22:23], off
	v_add_u32_e32 v8, 0x600, v10
	v_mul_lo_u32 v31, v6, s65
	v_ashrrev_i32_e32 v8, 4, v8
	v_add_u32_e32 v32, v26, v31
	v_mad_i64_i32 v[24:25], s[48:49], v8, s61, v[16:17]
	s_lshl_b64 s[48:49], s[92:93], 15
	s_add_u32 s40, s40, s48
	s_addc_u32 s41, s41, s49
	v_ashrrev_i32_e32 v7, 31, v6
	v_ashrrev_i32_e32 v9, 31, v8
	s_ashr_i32 s34, s22, 2
	s_mov_b32 s22, 0x800000
	v_cmp_gt_f32_e32 vcc, s22, v11
	s_and_b64 s[22:23], vcc, exec
	s_cselect_b32 s22, 32, 0
	v_bfi_b32 v66, -16, s34, v10
	global_load_dwordx4 v[132:135], v[24:25], off
	v_mul_lo_u32 v12, v8, s65
	v_add_u32_e32 v13, v26, v12
	v_mov_b32_e32 v119, v13
	global_load_dwordx4 v[136:139], v[18:19], off offset:1536
	global_load_dwordx4 v[140:143], v[20:21], off offset:1536
	global_load_dwordx4 v[144:147], v[22:23], off offset:1536
	global_load_dwordx4 v[148:151], v[24:25], off offset:1536
	v_and_b32_e32 v13, 0x7f, v10
	v_mul_u32_u24_e32 v14, 0x1900, v13
	v_lshlrev_b32_e32 v14, 1, v14
	v_mov_b32_e32 v15, v1
	v_lshl_add_u64 v[18:19], s[56:57], 0, v[14:15]
	v_and_b32_e32 v14, -8, v2
	v_ashrrev_i32_e32 v15, 31, v14
	v_lshl_add_u64 v[16:17], v[14:15], 1, v[18:19]
	v_mul_lo_u32 v14, v14, s65
	v_lshlrev_b32_e32 v13, 1, v13
	v_add3_u32 v20, s70, v14, v13
	global_load_dwordx4 v[152:155], v[16:17], off offset:3072
	v_lshlrev_b64 v[2:3], 8, v[2:3]
	v_mov_b32_e32 v156, v20
	v_and_b32_e32 v14, -8, v4
	v_ashrrev_i32_e32 v15, 31, v14
	v_lshl_add_u64 v[16:17], v[14:15], 1, v[18:19]
	v_mul_lo_u32 v14, v14, s65
	v_add3_u32 v20, s70, v14, v13
	global_load_dwordx4 v[158:161], v[16:17], off offset:3072
	v_mov_b32_e32 v157, v20
	v_and_b32_e32 v14, -8, v6
	v_ashrrev_i32_e32 v15, 31, v14
	v_lshl_add_u64 v[16:17], v[14:15], 1, v[18:19]
	v_mul_lo_u32 v14, v14, s65
	v_add3_u32 v20, s70, v14, v13
	global_load_dwordx4 v[162:165], v[16:17], off offset:3072
	v_and_b32_e32 v14, -8, v8
	v_ashrrev_i32_e32 v15, 31, v14
	v_lshl_add_u64 v[16:17], v[14:15], 1, v[18:19]
	v_mul_lo_u32 v14, v14, s65
	v_add3_u32 v13, s70, v14, v13
	global_load_dwordx4 v[166:169], v[16:17], off offset:3072
	v_mov_b32_e32 v170, v13
	v_lshl_add_u64 v[14:15], s[40:41], 0, v[0:1]
	s_mov_b64 s[40:41], 0x33600000
	v_lshl_add_u64 v[18:19], v[14:15], 0, s[40:41]
	v_lshl_add_u64 v[2:3], v[18:19], 0, v[2:3]
	global_load_dwordx4 v[172:175], v[2:3], off
	v_readlane_b32 s40, v255, 29
	s_nop 1
	v_add_u32_e32 v0, s40, v0
	v_add_u32_e32 v2, v0, v27
	v_add_u32_e32 v13, v0, v29
	v_mov_b32_e32 v171, v2
	v_lshlrev_b64 v[2:3], 8, v[4:5]
	v_lshl_add_u64 v[2:3], v[18:19], 0, v[2:3]
	global_load_dwordx4 v[176:179], v[2:3], off
	v_lshlrev_b64 v[2:3], 8, v[6:7]
	v_lshl_add_u64 v[2:3], v[18:19], 0, v[2:3]
	global_load_dwordx4 v[180:183], v[2:3], off
	v_add_u32_e32 v6, v0, v31
	v_add_u32_e32 v0, v0, v12
	v_lshlrev_b64 v[2:3], 8, v[8:9]
	v_lshl_add_u64 v[2:3], v[18:19], 0, v[2:3]
	global_load_dwordx4 v[184:187], v[2:3], off
	s_waitcnt vmcnt(15)
	ds_write_b128 v28, v[120:123]
	s_waitcnt vmcnt(14)
	ds_write_b128 v30, v[124:127]
	s_waitcnt vmcnt(13)
	ds_write_b128 v32, v[128:131]
	s_waitcnt vmcnt(12)
; #define LAS __attribute__((address_space(3)))
; #define ZERO8(a) do { _Pragma("unroll") for (int t_ = 0; t_ < 8; ++t_) a[t_] = (f32x4){0.f, 0.f, 0.f, 0.f}; } while (0)
; __device__ __forceinline__ void wave_mma(f32x4 (&acc)[8], const LAS bfu* As, const LAS bfu* Bs, int m0, int fr, int fq) {
; #pragma unroll
;     for (int ks = 0; ks < 4; ++ks) { const bf16x8 a = *(const LAS bf16x8*)(As + (m0 + fr) * TS + ks * 32 + fq * 8);
; #pragma unroll
;         for (int t = 0; t < 8; ++t) { const bf16x8 b = *(const LAS bf16x8*)(Bs + (t * 16 + fr) * TS + ks * 32 + fq * 8); acc[t] = __builtin_amdgcn_mfma_f32_16x16x32_bf16(b, a, acc[t], 0, 0, 0); } }
; }
; __device__ __forceinline__ void ret_unit(LAS unsigned char* lds, const bfu* PROJ, const bfu* RT, const float* gn_g, bfu* CAT, int u) {
;     ...
;     stage_nat(Qs, P0 + C_RQ, INW, tid); stage_nat(Ks, P0 + C_RK, INW, tid); stage_tr<false>(Vt, P0 + C_RV, INW, tid, 0.f); stage_nat(Rt, RT + (size_t)u * 16384, 128, tid);
;     __syncthreads();
;     const int fr = lane & 15, fq = lane >> 4, m0 = wid * 16, c = m0 + fr;
;     f32x4 acc[8], cr[8]; ZERO8(acc); ZERO8(cr);
;     wave_mma(cr, Qs, Rt, m0, fr, fq);
;     wave_mma(acc, Qs, Ks, m0, fr, fq);
	ds_write_b128 v119, v[132:135]
	s_waitcnt vmcnt(11)
	ds_write_b128 v28, v[136:139] offset:34816
	s_waitcnt vmcnt(10)
	ds_write_b128 v30, v[140:143] offset:34816
	s_waitcnt vmcnt(9)
	ds_write_b128 v32, v[144:147] offset:34816
	s_waitcnt vmcnt(8)
	ds_write_b128 v119, v[148:151] offset:34816
	s_waitcnt vmcnt(7)
	ds_write_b16 v156, v152
	ds_write_b16_d16_hi v156, v152 offset:272
	ds_write_b16 v156, v153 offset:544
	ds_write_b16_d16_hi v156, v153 offset:816
	ds_write_b16 v156, v154 offset:1088
	ds_write_b16_d16_hi v156, v154 offset:1360
	ds_write_b16 v156, v155 offset:1632
	ds_write_b16_d16_hi v156, v155 offset:1904
	s_waitcnt vmcnt(6)
	ds_write_b16 v157, v158
	ds_write_b16_d16_hi v157, v158 offset:272
	ds_write_b16 v157, v159 offset:544
	ds_write_b16_d16_hi v157, v159 offset:816
	ds_write_b16 v157, v160 offset:1088
	ds_write_b16_d16_hi v157, v160 offset:1360
	ds_write_b16 v157, v161 offset:1632
	ds_write_b16_d16_hi v157, v161 offset:1904
	s_waitcnt vmcnt(5)
	ds_write_b16 v20, v162
	ds_write_b16_d16_hi v20, v162 offset:272
	ds_write_b16 v20, v163 offset:544
	ds_write_b16_d16_hi v20, v163 offset:816
	ds_write_b16 v20, v164 offset:1088
	ds_write_b16_d16_hi v20, v164 offset:1360
	ds_write_b16 v20, v165 offset:1632
	ds_write_b16_d16_hi v20, v165 offset:1904
	s_waitcnt vmcnt(4)
	ds_write_b16 v170, v166
	ds_write_b16_d16_hi v170, v166 offset:272
	ds_write_b16 v170, v167 offset:544
	ds_write_b16_d16_hi v170, v167 offset:816
	ds_write_b16 v170, v168 offset:1088
	ds_write_b16_d16_hi v170, v168 offset:1360
	ds_write_b16 v170, v169 offset:1632
	ds_write_b16_d16_hi v170, v169 offset:1904
	s_waitcnt vmcnt(3)
	ds_write_b128 v171, v[172:175]
	s_waitcnt vmcnt(2)
	ds_write_b128 v13, v[176:179]
	s_waitcnt vmcnt(1)
	ds_write_b128 v6, v[180:183]
	s_waitcnt vmcnt(0)
	ds_write_b128 v0, v[184:187]
	v_ldexp_f32 v0, v11, s22
	v_log_f32_e32 v0, v0
	v_cndmask_b32_e32 v2, 0, v242, vcc
	s_waitcnt lgkmcnt(0)
	s_barrier
	v_sub_f32_e32 v67, v0, v2
	v_and_b32_e32 v2, 15, v10
	v_mul_lo_u32 v0, v66, s65
	v_add_u32_e32 v73, 0, v0
	v_mul_u32_u24_e32 v70, 0x110, v2
	v_add_u32_e32 v62, v73, v69
	v_add3_u32 v63, s40, v69, v70
	ds_read_b128 v[46:49], v62
	ds_read_b128 v[2:5], v63
	ds_read_b128 v[6:9], v63 offset:4352
	ds_read_b128 v[10:13], v63 offset:8704
	ds_read_b128 v[14:17], v63 offset:13056
	ds_read_b128 v[18:21], v63 offset:17408
	ds_read_b128 v[22:25], v63 offset:21760
	ds_read_b128 v[26:29], v63 offset:26112
	ds_read_b128 v[30:33], v63 offset:30464
	ds_read_b128 v[38:41], v62 offset:64
	ds_read_b128 v[34:37], v63 offset:64
	s_waitcnt lgkmcnt(9)
	v_mfma_f32_16x16x32_bf16 v[2:5], v[2:5], v[46:49], 0
	v_add3_u32 v72, 0, v69, v70
	v_lshlrev_b32_e32 v0, 3, v71
	s_waitcnt lgkmcnt(0)
	v_mfma_f32_16x16x32_bf16 v[2:5], v[34:37], v[38:41], v[2:5]
	ds_read_b128 v[34:37], v63 offset:4416
	v_mfma_f32_16x16x32_bf16 v[6:9], v[6:9], v[46:49], 0
	s_waitcnt lgkmcnt(0)
	v_mfma_f32_16x16x32_bf16 v[6:9], v[34:37], v[38:41], v[6:9]
	ds_read_b128 v[34:37], v63 offset:8768
	v_mfma_f32_16x16x32_bf16 v[10:13], v[10:13], v[46:49], 0
	s_waitcnt lgkmcnt(0)
	v_mfma_f32_16x16x32_bf16 v[10:13], v[34:37], v[38:41], v[10:13]
	ds_read_b128 v[34:37], v63 offset:13120
	v_mfma_f32_16x16x32_bf16 v[14:17], v[14:17], v[46:49], 0
	s_waitcnt lgkmcnt(0)
	v_mfma_f32_16x16x32_bf16 v[14:17], v[34:37], v[38:41], v[14:17]
	ds_read_b128 v[34:37], v63 offset:17472
	v_mfma_f32_16x16x32_bf16 v[18:21], v[18:21], v[46:49], 0
	s_waitcnt lgkmcnt(0)
	v_mfma_f32_16x16x32_bf16 v[18:21], v[34:37], v[38:41], v[18:21]
	ds_read_b128 v[34:37], v63 offset:21824
	v_mfma_f32_16x16x32_bf16 v[22:25], v[22:25], v[46:49], 0
	s_waitcnt lgkmcnt(0)
	v_mfma_f32_16x16x32_bf16 v[22:25], v[34:37], v[38:41], v[22:25]
	ds_read_b128 v[34:37], v63 offset:26176
	v_mfma_f32_16x16x32_bf16 v[26:29], v[26:29], v[46:49], 0
	s_waitcnt lgkmcnt(0)
	v_mfma_f32_16x16x32_bf16 v[26:29], v[34:37], v[38:41], v[26:29]
	ds_read_b128 v[34:37], v63 offset:30528
	v_mfma_f32_16x16x32_bf16 v[30:33], v[30:33], v[46:49], 0
	s_waitcnt lgkmcnt(0)
	v_mfma_f32_16x16x32_bf16 v[30:33], v[34:37], v[38:41], v[30:33]
	ds_read_b128 v[42:45], v62 offset:128
	ds_read_b128 v[34:37], v63 offset:128
	s_waitcnt lgkmcnt(0)
	v_mfma_f32_16x16x32_bf16 v[2:5], v[34:37], v[42:45], v[2:5]
	ds_read_b128 v[34:37], v63 offset:4480
	s_waitcnt lgkmcnt(0)
	v_mfma_f32_16x16x32_bf16 v[6:9], v[34:37], v[42:45], v[6:9]
	ds_read_b128 v[34:37], v63 offset:8832
	s_waitcnt lgkmcnt(0)
	v_mfma_f32_16x16x32_bf16 v[50:53], v[34:37], v[42:45], v[10:13]
	s_nop 2
	ds_read_b128 v[10:13], v63 offset:13184
	s_waitcnt lgkmcnt(0)
	v_mfma_f32_16x16x32_bf16 v[14:17], v[10:13], v[42:45], v[14:17]
	ds_read_b128 v[10:13], v63 offset:17536
	s_waitcnt lgkmcnt(0)
	v_mfma_f32_16x16x32_bf16 v[18:21], v[10:13], v[42:45], v[18:21]
	ds_read_b128 v[10:13], v63 offset:21888
	s_waitcnt lgkmcnt(0)
	v_mfma_f32_16x16x32_bf16 v[22:25], v[10:13], v[42:45], v[22:25]
	ds_read_b128 v[10:13], v63 offset:26240
	s_waitcnt lgkmcnt(0)
	v_mfma_f32_16x16x32_bf16 v[54:57], v[10:13], v[42:45], v[26:29]
	ds_read_b128 v[10:13], v63 offset:30592
	s_waitcnt lgkmcnt(0)
	v_mfma_f32_16x16x32_bf16 v[58:61], v[10:13], v[42:45], v[30:33]
	ds_read_b128 v[34:37], v62 offset:192
	ds_read_b128 v[10:13], v63 offset:192
	ds_read_b128 v[74:77], v72 offset:52224
	ds_read_b128 v[78:81], v72 offset:56576
	ds_read_b128 v[82:85], v72 offset:60928
	s_waitcnt lgkmcnt(3)
	v_mfma_f32_16x16x32_bf16 v[10:13], v[10:13], v[34:37], v[2:5]
	ds_read_b128 v[86:89], v72 offset:65280
	s_nop 1
	ds_read_b128 v[2:5], v63 offset:4544
	s_waitcnt lgkmcnt(0)
	v_mfma_f32_16x16x32_bf16 v[30:33], v[2:5], v[34:37], v[6:9]
	ds_read_b128 v[2:5], v63 offset:8896
	s_nop 1
	ds_read_b128 v[6:9], v63 offset:13248
	s_waitcnt lgkmcnt(0)
; #define LAS __attribute__((address_space(3)))
; __device__ __forceinline__ float fexp2(float x) { return __builtin_amdgcn_exp2f(x); }
; __device__ __forceinline__ void wave_mma(f32x4 (&acc)[8], const LAS bfu* As, const LAS bfu* Bs, int m0, int fr, int fq) {
; #pragma unroll
;     for (int ks = 0; ks < 4; ++ks) { const bf16x8 a = *(const LAS bf16x8*)(As + (m0 + fr) * TS + ks * 32 + fq * 8);
; #pragma unroll
;         for (int t = 0; t < 8; ++t) { const bf16x8 b = *(const LAS bf16x8*)(Bs + (t * 16 + fr) * TS + ks * 32 + fq * 8); acc[t] = __builtin_amdgcn_mfma_f32_16x16x32_bf16(b, a, acc[t], 0, 0, 0); } }
; }
; __device__ __forceinline__ void ret_unit(LAS unsigned char* lds, const bfu* PROJ, const bfu* RT, const float* gn_g, bfu* CAT, int u) {
;     ...
;     wave_mma(cr, Qs, Rt, m0, fr, fq);
;     wave_mma(acc, Qs, Ks, m0, fr, fq);
;     __syncthreads();
; #pragma unroll
;     for (int t = 0; t < 8; ++t) { float p[4];
; #pragma unroll
;         for (int j = 0; j < 4; ++j) { const int e = 16 * t + 4 * fq + j; p[j] = (c >= e) ? acc[t][j] * fexp2(lg * (float)(c - e)) : 0.f; }
	v_mfma_f32_16x16x32_bf16 v[14:17], v[6:9], v[34:37], v[14:17]
	ds_read_b128 v[6:9], v63 offset:17600
	v_mfma_f32_16x16x32_bf16 v[2:5], v[2:5], v[34:37], v[50:53]
	s_nop 2
	ds_read_b128 v[50:53], v72 offset:34816
	s_waitcnt lgkmcnt(1)
	v_mfma_f32_16x16x32_bf16 v[26:29], v[6:9], v[34:37], v[18:21]
	ds_read_b128 v[6:9], v63 offset:21952
	s_nop 1
	ds_read_b128 v[18:21], v63 offset:26304
	s_waitcnt lgkmcnt(1)
	v_mfma_f32_16x16x32_bf16 v[6:9], v[6:9], v[34:37], v[22:25]
	s_nop 2
	ds_read_b128 v[22:25], v63 offset:30656
	s_waitcnt lgkmcnt(1)
	v_mfma_f32_16x16x32_bf16 v[18:21], v[18:21], v[34:37], v[54:57]
	s_nop 2
	ds_read_b128 v[54:57], v72 offset:39168
	s_waitcnt lgkmcnt(1)
	v_mfma_f32_16x16x32_bf16 v[22:25], v[22:25], v[34:37], v[58:61]
	ds_read_b128 v[62:65], v72 offset:47872
	s_nop 1
	ds_read_b128 v[58:61], v72 offset:43520
	v_mfma_f32_16x16x32_bf16 v[50:53], v[50:53], v[46:49], 0
	s_waitcnt lgkmcnt(2)
	v_mfma_f32_16x16x32_bf16 v[54:57], v[54:57], v[46:49], 0
	s_waitcnt lgkmcnt(0)
	v_mfma_f32_16x16x32_bf16 v[58:61], v[58:61], v[46:49], 0
	v_mfma_f32_16x16x32_bf16 v[62:65], v[62:65], v[46:49], 0
	v_mfma_f32_16x16x32_bf16 v[74:77], v[74:77], v[46:49], 0
	v_mfma_f32_16x16x32_bf16 v[78:81], v[78:81], v[46:49], 0
	v_mfma_f32_16x16x32_bf16 v[82:85], v[82:85], v[46:49], 0
	v_mfma_f32_16x16x32_bf16 v[46:49], v[86:89], v[46:49], 0
	ds_read_b128 v[86:89], v72 offset:34880
	s_waitcnt lgkmcnt(0)
	v_mfma_f32_16x16x32_bf16 v[50:53], v[86:89], v[38:41], v[50:53]
	ds_read_b128 v[86:89], v72 offset:39232
	s_waitcnt lgkmcnt(0)
	v_mfma_f32_16x16x32_bf16 v[54:57], v[86:89], v[38:41], v[54:57]
	ds_read_b128 v[86:89], v72 offset:43584
	s_waitcnt lgkmcnt(0)
	v_mfma_f32_16x16x32_bf16 v[58:61], v[86:89], v[38:41], v[58:61]
	ds_read_b128 v[86:89], v72 offset:47936
	s_waitcnt lgkmcnt(0)
	v_mfma_f32_16x16x32_bf16 v[62:65], v[86:89], v[38:41], v[62:65]
	ds_read_b128 v[86:89], v72 offset:52288
	s_waitcnt lgkmcnt(0)
	v_mfma_f32_16x16x32_bf16 v[74:77], v[86:89], v[38:41], v[74:77]
	ds_read_b128 v[86:89], v72 offset:56640
	s_waitcnt lgkmcnt(0)
	v_mfma_f32_16x16x32_bf16 v[78:81], v[86:89], v[38:41], v[78:81]
	ds_read_b128 v[86:89], v72 offset:60992
	s_waitcnt lgkmcnt(0)
	v_mfma_f32_16x16x32_bf16 v[82:85], v[86:89], v[38:41], v[82:85]
	ds_read_b128 v[86:89], v72 offset:65344
	s_waitcnt lgkmcnt(0)
	v_mfma_f32_16x16x32_bf16 v[38:41], v[86:89], v[38:41], v[46:49]
	s_nop 2
	ds_read_b128 v[46:49], v72 offset:34944
	s_waitcnt lgkmcnt(0)
	v_mfma_f32_16x16x32_bf16 v[46:49], v[46:49], v[42:45], v[50:53]
	s_nop 2
	ds_read_b128 v[50:53], v72 offset:39296
	s_waitcnt lgkmcnt(0)
	v_mfma_f32_16x16x32_bf16 v[50:53], v[50:53], v[42:45], v[54:57]
	s_nop 2
	ds_read_b128 v[54:57], v72 offset:43648
	s_waitcnt lgkmcnt(0)
	v_mfma_f32_16x16x32_bf16 v[54:57], v[54:57], v[42:45], v[58:61]
	s_nop 2
	ds_read_b128 v[58:61], v72 offset:48000
	s_waitcnt lgkmcnt(0)
	v_mfma_f32_16x16x32_bf16 v[86:89], v[58:61], v[42:45], v[62:65]
	ds_read_b128 v[58:61], v72 offset:52352
	s_waitcnt lgkmcnt(0)
	v_mfma_f32_16x16x32_bf16 v[74:77], v[58:61], v[42:45], v[74:77]
	ds_read_b128 v[58:61], v72 offset:56704
	s_waitcnt lgkmcnt(0)
	v_mfma_f32_16x16x32_bf16 v[78:81], v[58:61], v[42:45], v[78:81]
	ds_read_b128 v[58:61], v72 offset:61056
	s_waitcnt lgkmcnt(0)
	v_mfma_f32_16x16x32_bf16 v[82:85], v[58:61], v[42:45], v[82:85]
	ds_read_b128 v[58:61], v72 offset:65408
	s_waitcnt lgkmcnt(0)
	v_mfma_f32_16x16x32_bf16 v[90:93], v[58:61], v[42:45], v[38:41]
	s_nop 2
	ds_read_b128 v[38:41], v72 offset:35008
	s_waitcnt lgkmcnt(0)
	v_mfma_f32_16x16x32_bf16 v[62:65], v[38:41], v[34:37], v[46:49]
	ds_read_b128 v[38:41], v72 offset:39360
	s_waitcnt lgkmcnt(0)
	v_mfma_f32_16x16x32_bf16 v[58:61], v[38:41], v[34:37], v[50:53]
	ds_read_b128 v[38:41], v72 offset:43712
	s_waitcnt lgkmcnt(0)
	v_mfma_f32_16x16x32_bf16 v[54:57], v[38:41], v[34:37], v[54:57]
	ds_read_b128 v[38:41], v72 offset:48064
	s_waitcnt lgkmcnt(0)
	v_mfma_f32_16x16x32_bf16 v[50:53], v[38:41], v[34:37], v[86:89]
	ds_read_b128 v[38:41], v72 offset:52416
	s_waitcnt lgkmcnt(0)
	v_mfma_f32_16x16x32_bf16 v[46:49], v[38:41], v[34:37], v[74:77]
	ds_read_b128 v[38:41], v72 offset:56768
	s_nop 1
	ds_read_b128 v[74:77], v72 offset:65472
	s_waitcnt lgkmcnt(1)
	v_mfma_f32_16x16x32_bf16 v[42:45], v[38:41], v[34:37], v[78:81]
	ds_read_b128 v[38:41], v72 offset:61120
	v_lshlrev_b32_e32 v72, 2, v71
	v_add_u32_e32 v71, v73, v0
	v_sub_u32_e32 v73, v66, v72
	v_cvt_f32_i32_e32 v73, v73
	v_cmp_ge_i32_e32 vcc, v66, v72
	s_waitcnt lgkmcnt(0)
	v_mfma_f32_16x16x32_bf16 v[38:41], v[38:41], v[34:37], v[82:85]
	v_mul_f32_e32 v73, v67, v73
	v_exp_f32_e32 v73, v73
	v_mfma_f32_16x16x32_bf16 v[34:37], v[74:77], v[34:37], v[90:93]
	v_or_b32_e32 v75, 3, v72
	v_mul_f32_e32 v62, v73, v62
	v_cndmask_b32_e32 v73, 0, v62, vcc
	v_xad_u32 v62, v72, -1, v66
	v_cvt_f32_i32_e32 v62, v62
	v_cmp_gt_i32_e32 vcc, v66, v72
	v_or_b32_e32 v76, 2, v72
	s_barrier
; #define LAS __attribute__((address_space(3)))
; __device__ __forceinline__ unsigned pk2(float lo, float hi) { return pg8::cvt_pk_bf16(lo, hi); }
; __device__ __forceinline__ float fexp2(float x) { return __builtin_amdgcn_exp2f(x); }
; __device__ __forceinline__ void ret_unit(LAS unsigned char* lds, const bfu* PROJ, const bfu* RT, const float* gn_g, bfu* CAT, int u) {
;     ...
; #pragma unroll
;     for (int t = 0; t < 8; ++t) { float p[4];
; #pragma unroll
;         for (int j = 0; j < 4; ++j) { const int e = 16 * t + 4 * fq + j; p[j] = (c >= e) ? acc[t][j] * fexp2(lg * (float)(c - e)) : 0.f; }
;         v2u w; w.x = pk2(p[0], p[1]); w.y = pk2(p[2], p[3]); *(LAS v2u*)(Ks + c * TS + 16 * t + 4 * fq) = w; }
	v_mul_f32_e32 v62, v67, v62
	v_exp_f32_e32 v62, v62
	v_add_u32_e32 v78, v71, v0
	v_add3_u32 v82, s70, v69, v70
	v_mul_f32_e32 v62, v62, v63
	v_cndmask_b32_e32 v74, 0, v62, vcc
	v_sub_u32_e32 v62, v66, v76
	v_sub_u32_e32 v63, v66, v75
	v_cvt_f32_i32_e32 v62, v62
	v_cvt_f32_i32_e32 v63, v63
	v_cmp_ge_i32_e32 vcc, v66, v76
	v_or_b32_e32 v76, 18, v72
	v_mul_f32_e32 v62, v67, v62
	v_mul_f32_e32 v63, v67, v63
	v_exp_f32_e32 v62, v62
	v_exp_f32_e32 v63, v63
	s_nop 0
	v_pk_mul_f32 v[62:63], v[62:63], v[64:65]
	s_nop 0
	v_cvt_pk_bf16_f32 v62, v62, v63
	v_cndmask_b32_e32 v63, 0, v62, vcc
	v_lshrrev_b32_e32 v62, 16, v62
	v_cmp_ge_i32_e32 vcc, v66, v75
	v_cvt_pk_bf16_f32 v64, v73, v74
	v_or_b32_e32 v73, 17, v72
	v_cndmask_b32_e32 v62, 0, v62, vcc
	v_or_b32_e32 v74, 16, v72
	v_perm_b32 v65, v62, v63, s72
	v_sub_u32_e32 v62, v66, v74
	v_sub_u32_e32 v63, v66, v73
	v_cvt_f32_i32_e32 v62, v62
	v_cvt_f32_i32_e32 v63, v63
	v_or_b32_e32 v75, 19, v72
	v_cmp_ge_i32_e32 vcc, v66, v74
	v_mul_f32_e32 v62, v67, v62
	v_mul_f32_e32 v63, v67, v63
	v_exp_f32_e32 v62, v62
	v_exp_f32_e32 v63, v63
	s_nop 0
	v_pk_mul_f32 v[58:59], v[62:63], v[58:59]
	v_sub_u32_e32 v62, v66, v76
	v_sub_u32_e32 v63, v66, v75
	v_cvt_f32_i32_e32 v62, v62
	v_cvt_f32_i32_e32 v63, v63
	v_cvt_pk_bf16_f32 v58, v58, v59
	v_cndmask_b32_e32 v59, 0, v58, vcc
	v_mul_f32_e32 v62, v67, v62
	v_mul_f32_e32 v63, v67, v63
	v_exp_f32_e32 v62, v62
	v_exp_f32_e32 v63, v63
	v_lshrrev_b32_e32 v58, 16, v58
	v_cmp_ge_i32_e32 vcc, v66, v73
	v_pk_mul_f32 v[60:61], v[62:63], v[60:61]
	s_nop 0
	v_cndmask_b32_e32 v58, 0, v58, vcc
	v_perm_b32 v62, v58, v59, s72
	v_cvt_pk_bf16_f32 v58, v60, v61
	v_cmp_ge_i32_e32 vcc, v66, v76
	s_nop 1
	v_cndmask_b32_e32 v59, 0, v58, vcc
	v_lshrrev_b32_e32 v58, 16, v58
	v_cmp_ge_i32_e32 vcc, v66, v75
	s_nop 1
	v_cndmask_b32_e32 v58, 0, v58, vcc
	v_perm_b32 v63, v58, v59, s72
	v_add_u32_e32 v58, 0x8800, v71
	ds_write2_b64 v58, v[64:65], v[62:63] offset1:4
	v_or_b32_e32 v59, 33, v72
	v_or_b32_e32 v62, 32, v72
	v_sub_u32_e32 v60, v66, v62
	v_sub_u32_e32 v61, v66, v59
	v_cvt_f32_i32_e32 v60, v60
	v_cvt_f32_i32_e32 v61, v61
	v_or_b32_e32 v63, 35, v72
	v_or_b32_e32 v64, 34, v72
	v_mul_f32_e32 v60, v67, v60
	v_mul_f32_e32 v61, v67, v61
	v_exp_f32_e32 v60, v60
	v_exp_f32_e32 v61, v61
	v_cmp_ge_i32_e32 vcc, v66, v62
	v_or_b32_e32 v62, 50, v72
	v_pk_mul_f32 v[54:55], v[60:61], v[54:55]
	v_sub_u32_e32 v60, v66, v64
	v_sub_u32_e32 v61, v66, v63
	v_cvt_f32_i32_e32 v60, v60
	v_cvt_f32_i32_e32 v61, v61
	v_cvt_pk_bf16_f32 v54, v54, v55
	v_cndmask_b32_e32 v55, 0, v54, vcc
	v_mul_f32_e32 v60, v67, v60
	v_mul_f32_e32 v61, v67, v61
	v_exp_f32_e32 v60, v60
	v_exp_f32_e32 v61, v61
	v_lshrrev_b32_e32 v54, 16, v54
	v_cmp_ge_i32_e32 vcc, v66, v59
	v_or_b32_e32 v59, 49, v72
	v_pk_mul_f32 v[56:57], v[60:61], v[56:57]
	v_cndmask_b32_e32 v54, 0, v54, vcc
	v_perm_b32 v54, v54, v55, s72
	v_cvt_pk_bf16_f32 v55, v56, v57
	v_cmp_ge_i32_e32 vcc, v66, v64
	v_or_b32_e32 v60, 48, v72
	v_sub_u32_e32 v57, v66, v59
	v_cndmask_b32_e32 v56, 0, v55, vcc
	v_lshrrev_b32_e32 v55, 16, v55
	v_cmp_ge_i32_e32 vcc, v66, v63
	v_cvt_f32_i32_e32 v57, v57
	v_or_b32_e32 v61, 51, v72
	v_cndmask_b32_e32 v55, 0, v55, vcc
	v_perm_b32 v55, v55, v56, s72
	v_sub_u32_e32 v56, v66, v60
	v_cvt_f32_i32_e32 v56, v56
	v_mul_f32_e32 v57, v67, v57
	v_exp_f32_e32 v57, v57
	v_cmp_ge_i32_e32 vcc, v66, v60
	v_mul_f32_e32 v56, v67, v56
	v_exp_f32_e32 v56, v56
	s_nop 0
	v_pk_mul_f32 v[50:51], v[56:57], v[50:51]
	v_sub_u32_e32 v56, v66, v62
	v_sub_u32_e32 v57, v66, v61
	v_cvt_f32_i32_e32 v56, v56
	v_cvt_f32_i32_e32 v57, v57
	v_cvt_pk_bf16_f32 v50, v50, v51
	v_cndmask_b32_e32 v51, 0, v50, vcc
	v_mul_f32_e32 v56, v67, v56
	v_mul_f32_e32 v57, v67, v57
	v_exp_f32_e32 v56, v56
	v_exp_f32_e32 v57, v57
	v_lshrrev_b32_e32 v50, 16, v50
	v_cmp_ge_i32_e32 vcc, v66, v59
	v_pk_mul_f32 v[52:53], v[56:57], v[52:53]
	s_nop 0
	v_cndmask_b32_e32 v50, 0, v50, vcc
	v_perm_b32 v50, v50, v51, s72
	v_cvt_pk_bf16_f32 v51, v52, v53
	v_cmp_ge_i32_e32 vcc, v66, v62
	v_or_b32_e32 v53, 64, v72
	s_nop 0
	v_cndmask_b32_e32 v52, 0, v51, vcc
	v_lshrrev_b32_e32 v51, 16, v51
	v_cmp_ge_i32_e32 vcc, v66, v61
	s_nop 1
	v_cndmask_b32_e32 v51, 0, v51, vcc
	v_perm_b32 v51, v51, v52, s72
	v_or_b32_e32 v52, 0x41, v72
	ds_write2_b64 v58, v[54:55], v[50:51] offset0:8 offset1:12
	v_sub_u32_e32 v50, v66, v53
	v_sub_u32_e32 v51, v66, v52
	v_cvt_f32_i32_e32 v50, v50
	v_cvt_f32_i32_e32 v51, v51
	v_or_b32_e32 v54, 0x43, v72
	v_or_b32_e32 v55, 0x42, v72
	v_mul_f32_e32 v50, v67, v50
	v_mul_f32_e32 v51, v67, v51
	v_exp_f32_e32 v50, v50
	v_exp_f32_e32 v51, v51
	v_cmp_ge_i32_e32 vcc, v66, v53
	v_or_b32_e32 v53, 0x52, v72
	v_pk_mul_f32 v[46:47], v[50:51], v[46:47]
	v_sub_u32_e32 v50, v66, v55
	v_sub_u32_e32 v51, v66, v54
	v_cvt_f32_i32_e32 v50, v50
	v_cvt_f32_i32_e32 v51, v51
	v_cvt_pk_bf16_f32 v46, v46, v47
	v_cndmask_b32_e32 v47, 0, v46, vcc
	v_mul_f32_e32 v50, v67, v50
	v_mul_f32_e32 v51, v67, v51
	v_exp_f32_e32 v50, v50
	v_exp_f32_e32 v51, v51
	v_lshrrev_b32_e32 v46, 16, v46
	v_cmp_ge_i32_e32 vcc, v66, v52
	v_or_b32_e32 v52, 0x53, v72
	v_pk_mul_f32 v[48:49], v[50:51], v[48:49]
	v_cndmask_b32_e32 v46, 0, v46, vcc
	v_perm_b32 v46, v46, v47, s72
	v_cvt_pk_bf16_f32 v47, v48, v49
	v_cmp_ge_i32_e32 vcc, v66, v55
	v_or_b32_e32 v50, 0x51, v72
	v_or_b32_e32 v51, 0x50, v72
	v_cndmask_b32_e32 v48, 0, v47, vcc
	v_lshrrev_b32_e32 v47, 16, v47
	v_cmp_ge_i32_e32 vcc, v66, v54
	v_sub_u32_e32 v49, v66, v50
	v_cvt_f32_i32_e32 v49, v49
	v_cndmask_b32_e32 v47, 0, v47, vcc
	v_perm_b32 v47, v47, v48, s72
	v_sub_u32_e32 v48, v66, v51
	v_cvt_f32_i32_e32 v48, v48
	v_mul_f32_e32 v49, v67, v49
	v_exp_f32_e32 v49, v49
	v_cmp_ge_i32_e32 vcc, v66, v51
; #define LAS __attribute__((address_space(3)))
; #define LDS_WAIT() asm volatile("s_waitcnt lgkmcnt(0)" ::: "memory")
; __device__ __forceinline__ unsigned pk2(float lo, float hi) { return pg8::cvt_pk_bf16(lo, hi); }
; __device__ __forceinline__ float fexp2(float x) { return __builtin_amdgcn_exp2f(x); }
; #define ZERO8(a) do { _Pragma("unroll") for (int t_ = 0; t_ < 8; ++t_) a[t_] = (f32x4){0.f, 0.f, 0.f, 0.f}; } while (0)
; __device__ __forceinline__ void ret_unit(LAS unsigned char* lds, const bfu* PROJ, const bfu* RT, const float* gn_g, bfu* CAT, int u) {
;     ...
;     for (int t = 0; t < 8; ++t) { float p[4];
; #pragma unroll
;         for (int j = 0; j < 4; ++j) { const int e = 16 * t + 4 * fq + j; p[j] = (c >= e) ? acc[t][j] * fexp2(lg * (float)(c - e)) : 0.f; }
;         v2u w; w.x = pk2(p[0], p[1]); w.y = pk2(p[2], p[3]); *(LAS v2u*)(Ks + c * TS + 16 * t + 4 * fq) = w; }
;     LDS_WAIT(); asm volatile("" ::: "memory");
;     ZERO8(acc);
;     wave_mma(acc, Ks, Vt, m0, fr, fq);
	v_mul_f32_e32 v48, v67, v48
	v_exp_f32_e32 v48, v48
	s_nop 0
	v_pk_mul_f32 v[42:43], v[48:49], v[42:43]
	v_sub_u32_e32 v48, v66, v53
	v_sub_u32_e32 v49, v66, v52
	v_cvt_f32_i32_e32 v48, v48
	v_cvt_f32_i32_e32 v49, v49
	v_cvt_pk_bf16_f32 v42, v42, v43
	v_cndmask_b32_e32 v43, 0, v42, vcc
	v_mul_f32_e32 v48, v67, v48
	v_mul_f32_e32 v49, v67, v49
	v_exp_f32_e32 v48, v48
	v_exp_f32_e32 v49, v49
	v_lshrrev_b32_e32 v42, 16, v42
	v_cmp_ge_i32_e32 vcc, v66, v50
	v_pk_mul_f32 v[44:45], v[48:49], v[44:45]
	s_nop 0
	v_cndmask_b32_e32 v42, 0, v42, vcc
	v_perm_b32 v42, v42, v43, s72
	v_cvt_pk_bf16_f32 v43, v44, v45
	v_cmp_ge_i32_e32 vcc, v66, v53
	v_or_b32_e32 v45, 0x60, v72
	s_nop 0
	v_cndmask_b32_e32 v44, 0, v43, vcc
	v_lshrrev_b32_e32 v43, 16, v43
	v_cmp_ge_i32_e32 vcc, v66, v52
	s_nop 1
	v_cndmask_b32_e32 v43, 0, v43, vcc
	v_perm_b32 v43, v43, v44, s72
	v_or_b32_e32 v44, 0x61, v72
	ds_write2_b64 v58, v[46:47], v[42:43] offset0:16 offset1:20
	v_sub_u32_e32 v42, v66, v45
	v_sub_u32_e32 v43, v66, v44
	v_cvt_f32_i32_e32 v42, v42
	v_cvt_f32_i32_e32 v43, v43
	v_or_b32_e32 v46, 0x63, v72
	v_or_b32_e32 v47, 0x62, v72
	v_mul_f32_e32 v42, v67, v42
	v_mul_f32_e32 v43, v67, v43
	v_exp_f32_e32 v42, v42
	v_exp_f32_e32 v43, v43
	v_cmp_ge_i32_e32 vcc, v66, v45
	v_or_b32_e32 v45, 0x72, v72
	v_pk_mul_f32 v[38:39], v[42:43], v[38:39]
	v_sub_u32_e32 v42, v66, v47
	v_sub_u32_e32 v43, v66, v46
	v_cvt_f32_i32_e32 v42, v42
	v_cvt_f32_i32_e32 v43, v43
	v_cvt_pk_bf16_f32 v38, v38, v39
	v_cndmask_b32_e32 v39, 0, v38, vcc
	v_mul_f32_e32 v42, v67, v42
	v_mul_f32_e32 v43, v67, v43
	v_exp_f32_e32 v42, v42
	v_exp_f32_e32 v43, v43
	v_lshrrev_b32_e32 v38, 16, v38
	v_cmp_ge_i32_e32 vcc, v66, v44
	v_or_b32_e32 v44, 0x73, v72
	v_pk_mul_f32 v[40:41], v[42:43], v[40:41]
	v_cndmask_b32_e32 v38, 0, v38, vcc
	v_perm_b32 v38, v38, v39, s72
	v_cvt_pk_bf16_f32 v39, v40, v41
	v_cmp_ge_i32_e32 vcc, v66, v47
	v_or_b32_e32 v42, 0x71, v72
	v_or_b32_e32 v43, 0x70, v72
	v_cndmask_b32_e32 v40, 0, v39, vcc
	v_lshrrev_b32_e32 v39, 16, v39
	v_cmp_ge_i32_e32 vcc, v66, v46
	v_sub_u32_e32 v41, v66, v42
	v_cvt_f32_i32_e32 v41, v41
	v_cndmask_b32_e32 v39, 0, v39, vcc
	v_perm_b32 v39, v39, v40, s72
	v_sub_u32_e32 v40, v66, v43
	v_cvt_f32_i32_e32 v40, v40
	v_mul_f32_e32 v41, v67, v41
	v_exp_f32_e32 v41, v41
	v_cmp_ge_i32_e32 vcc, v66, v43
	v_mul_f32_e32 v40, v67, v40
	v_exp_f32_e32 v40, v40
	s_nop 0
	v_pk_mul_f32 v[34:35], v[40:41], v[34:35]
	v_sub_u32_e32 v40, v66, v45
	v_sub_u32_e32 v41, v66, v44
	v_cvt_f32_i32_e32 v40, v40
	v_cvt_f32_i32_e32 v41, v41
	v_cvt_pk_bf16_f32 v34, v34, v35
	v_cndmask_b32_e32 v35, 0, v34, vcc
	v_mul_f32_e32 v40, v67, v40
	v_mul_f32_e32 v41, v67, v41
	v_exp_f32_e32 v40, v40
	v_exp_f32_e32 v41, v41
	v_lshrrev_b32_e32 v34, 16, v34
	v_cmp_ge_i32_e32 vcc, v66, v42
	v_pk_mul_f32 v[36:37], v[40:41], v[36:37]
	s_nop 0
	v_cndmask_b32_e32 v34, 0, v34, vcc
	v_perm_b32 v34, v34, v35, s72
	v_cvt_pk_bf16_f32 v35, v36, v37
	v_cmp_ge_i32_e32 vcc, v66, v45
	s_nop 1
	v_cndmask_b32_e32 v36, 0, v35, vcc
	v_lshrrev_b32_e32 v35, 16, v35
	v_cmp_ge_i32_e32 vcc, v66, v44
	s_nop 1
	v_cndmask_b32_e32 v35, 0, v35, vcc
	v_perm_b32 v35, v35, v36, s72
	ds_write2_b64 v58, v[38:39], v[34:35] offset0:24 offset1:28
	s_waitcnt lgkmcnt(0)
	ds_read_b128 v[34:37], v78 offset:34816
	ds_read_b128 v[38:41], v82
	ds_read_b128 v[42:45], v82 offset:4352
	ds_read_b128 v[46:49], v82 offset:8704
	ds_read_b128 v[50:53], v82 offset:13056
	ds_read_b128 v[54:57], v82 offset:17408
	ds_read_b128 v[58:61], v82 offset:21760
	ds_read_b128 v[62:65], v82 offset:26112
	ds_read_b128 v[70:73], v82 offset:30464
	s_waitcnt lgkmcnt(7)
	v_mfma_f32_16x16x32_bf16 v[38:41], v[38:41], v[34:37], 0
	s_waitcnt lgkmcnt(6)
	v_mfma_f32_16x16x32_bf16 v[42:45], v[42:45], v[34:37], 0
	s_waitcnt lgkmcnt(5)
	v_mfma_f32_16x16x32_bf16 v[46:49], v[46:49], v[34:37], 0
	s_waitcnt lgkmcnt(4)
	v_mfma_f32_16x16x32_bf16 v[50:53], v[50:53], v[34:37], 0
	s_waitcnt lgkmcnt(3)
	v_mfma_f32_16x16x32_bf16 v[54:57], v[54:57], v[34:37], 0
	s_waitcnt lgkmcnt(2)
	v_mfma_f32_16x16x32_bf16 v[58:61], v[58:61], v[34:37], 0
	s_waitcnt lgkmcnt(1)
	v_mfma_f32_16x16x32_bf16 v[62:65], v[62:65], v[34:37], 0
	s_waitcnt lgkmcnt(0)
	v_mfma_f32_16x16x32_bf16 v[34:37], v[70:73], v[34:37], 0
	ds_read_b128 v[70:73], v78 offset:34880
	ds_read_b128 v[74:77], v82 offset:64
	s_waitcnt lgkmcnt(0)
	v_mfma_f32_16x16x32_bf16 v[38:41], v[74:77], v[70:73], v[38:41]
	ds_read_b128 v[74:77], v82 offset:4416
	s_waitcnt lgkmcnt(0)
	v_mfma_f32_16x16x32_bf16 v[42:45], v[74:77], v[70:73], v[42:45]
	ds_read_b128 v[74:77], v82 offset:8768
	s_waitcnt lgkmcnt(0)
	v_mfma_f32_16x16x32_bf16 v[46:49], v[74:77], v[70:73], v[46:49]
	ds_read_b128 v[74:77], v82 offset:13120
	s_waitcnt lgkmcnt(0)
	v_mfma_f32_16x16x32_bf16 v[50:53], v[74:77], v[70:73], v[50:53]
	ds_read_b128 v[74:77], v82 offset:17472
	s_waitcnt lgkmcnt(0)
	v_mfma_f32_16x16x32_bf16 v[54:57], v[74:77], v[70:73], v[54:57]
	ds_read_b128 v[74:77], v82 offset:21824
	s_waitcnt lgkmcnt(0)
	v_mfma_f32_16x16x32_bf16 v[58:61], v[74:77], v[70:73], v[58:61]
	ds_read_b128 v[74:77], v82 offset:26176
	s_waitcnt lgkmcnt(0)
	v_mfma_f32_16x16x32_bf16 v[62:65], v[74:77], v[70:73], v[62:65]
	ds_read_b128 v[74:77], v82 offset:30528
	s_waitcnt lgkmcnt(0)
	v_mfma_f32_16x16x32_bf16 v[34:37], v[74:77], v[70:73], v[34:37]
	ds_read_b128 v[70:73], v78 offset:34944
	ds_read_b128 v[74:77], v82 offset:128
	s_waitcnt lgkmcnt(0)
	v_mfma_f32_16x16x32_bf16 v[38:41], v[74:77], v[70:73], v[38:41]
	ds_read_b128 v[74:77], v82 offset:4480
	s_waitcnt lgkmcnt(0)
	v_mfma_f32_16x16x32_bf16 v[42:45], v[74:77], v[70:73], v[42:45]
	ds_read_b128 v[74:77], v82 offset:8832
	s_waitcnt lgkmcnt(0)
; __device__ __forceinline__ float fexp2(float x) { return __builtin_amdgcn_exp2f(x); }
; __device__ __forceinline__ void ret_unit(LAS unsigned char* lds, const bfu* PROJ, const bfu* RT, const float* gn_g, bfu* CAT, int u) {
;     ...
;     wave_mma(acc, Ks, Vt, m0, fr, fq);
;     const float xi = fexp2(lg * (float)(c + 1)); float s = 0.f;
; #pragma unroll
;     for (int t = 0; t < 8; ++t) { acc[t] = acc[t] + cr[t] * xi; s += (acc[t][0] + acc[t][1]) + (acc[t][2] + acc[t][3]); }
;     s += __shfl_xor(s, 16); s += __shfl_xor(s, 32); const float mu = s * (1.f / 128.f); float q = 0.f;
	v_mfma_f32_16x16x32_bf16 v[46:49], v[74:77], v[70:73], v[46:49]
	ds_read_b128 v[74:77], v82 offset:13184
	s_waitcnt lgkmcnt(0)
	v_mfma_f32_16x16x32_bf16 v[50:53], v[74:77], v[70:73], v[50:53]
	ds_read_b128 v[74:77], v82 offset:17536
	s_waitcnt lgkmcnt(0)
	v_mfma_f32_16x16x32_bf16 v[54:57], v[74:77], v[70:73], v[54:57]
	ds_read_b128 v[74:77], v82 offset:21888
	s_waitcnt lgkmcnt(0)
	v_mfma_f32_16x16x32_bf16 v[58:61], v[74:77], v[70:73], v[58:61]
	ds_read_b128 v[74:77], v82 offset:26240
	s_waitcnt lgkmcnt(0)
	v_mfma_f32_16x16x32_bf16 v[62:65], v[74:77], v[70:73], v[62:65]
	ds_read_b128 v[74:77], v82 offset:30592
	s_waitcnt lgkmcnt(0)
	v_mfma_f32_16x16x32_bf16 v[34:37], v[74:77], v[70:73], v[34:37]
	ds_read_b128 v[70:73], v78 offset:35008
	ds_read_b128 v[74:77], v82 offset:192
	s_waitcnt lgkmcnt(0)
	v_mfma_f32_16x16x32_bf16 v[38:41], v[74:77], v[70:73], v[38:41]
	ds_read_b128 v[74:77], v82 offset:4544
	s_waitcnt lgkmcnt(0)
	v_mfma_f32_16x16x32_bf16 v[74:77], v[74:77], v[70:73], v[42:45]
	s_nop 2
	ds_read_b128 v[42:45], v82 offset:8896
	s_waitcnt lgkmcnt(0)
	v_mfma_f32_16x16x32_bf16 v[78:81], v[42:45], v[70:73], v[46:49]
	ds_read_b128 v[42:45], v82 offset:13248
	s_waitcnt lgkmcnt(0)
	v_mfma_f32_16x16x32_bf16 v[48:51], v[42:45], v[70:73], v[50:53]
	ds_read_b128 v[42:45], v82 offset:17600
	s_waitcnt lgkmcnt(0)
	v_mfma_f32_16x16x32_bf16 v[52:55], v[42:45], v[70:73], v[54:57]
	ds_read_b128 v[42:45], v82 offset:21952
	s_waitcnt lgkmcnt(0)
	v_mfma_f32_16x16x32_bf16 v[56:59], v[42:45], v[70:73], v[58:61]
	ds_read_b128 v[42:45], v82 offset:26304
	s_waitcnt lgkmcnt(0)
	v_mfma_f32_16x16x32_bf16 v[60:63], v[42:45], v[70:73], v[62:65]
	ds_read_b128 v[42:45], v82 offset:30656
	s_waitcnt lgkmcnt(0)
	v_mfma_f32_16x16x32_bf16 v[70:73], v[42:45], v[70:73], v[34:37]
	s_nop 2
	v_add_u32_e32 v34, 1, v66
	v_cvt_f32_i32_e32 v34, v34
	v_mul_f32_e32 v34, v67, v34
	v_exp_f32_e32 v64, v34
	v_ashrrev_i32_e32 v67, 31, v66
	v_pk_fma_f32 v[46:47], v[64:65], v[10:11], v[38:39] op_sel_hi:[0,1,1]
	v_pk_fma_f32 v[42:43], v[64:65], v[30:31], v[74:75] op_sel_hi:[0,1,1]
	v_pk_fma_f32 v[44:45], v[64:65], v[12:13], v[40:41] op_sel_hi:[0,1,1]
	v_pk_fma_f32 v[40:41], v[64:65], v[32:33], v[76:77] op_sel_hi:[0,1,1]
	v_mov_b32_e32 v10, v46
	v_mov_b32_e32 v11, v42
	v_mov_b32_e32 v12, v47
	v_mov_b32_e32 v13, v43
	v_pk_add_f32 v[10:11], v[10:11], v[12:13]
	v_mov_b32_e32 v12, v44
	v_mov_b32_e32 v13, v40
	v_mov_b32_e32 v30, v45
	v_mov_b32_e32 v31, v41
	v_pk_fma_f32 v[38:39], v[64:65], v[2:3], v[78:79] op_sel_hi:[0,1,1]
	v_pk_fma_f32 v[36:37], v[64:65], v[4:5], v[80:81] op_sel_hi:[0,1,1]
	v_pk_add_f32 v[12:13], v[12:13], v[30:31]
	v_pk_mov_b32 v[2:3], v[38:39], v[36:37] op_sel:[1,0]
	v_mov_b32_e32 v4, v38
	v_mov_b32_e32 v5, v37
	v_pk_add_f32 v[10:11], v[10:11], v[12:13]
	v_pk_add_f32 v[2:3], v[2:3], v[4:5]
	v_add_f32_e32 v10, 0, v10
	v_pk_add_f32 v[2:3], v[2:3], v[2:3] op_sel:[0,1] op_sel_hi:[1,0]
	v_pk_fma_f32 v[32:33], v[64:65], v[16:17], v[50:51] op_sel_hi:[0,1,1]
	v_pk_fma_f32 v[34:35], v[64:65], v[14:15], v[48:49] op_sel_hi:[0,1,1]
	v_pk_fma_f32 v[28:29], v[64:65], v[28:29], v[54:55] op_sel_hi:[0,1,1]
	v_pk_fma_f32 v[30:31], v[64:65], v[26:27], v[52:53] op_sel_hi:[0,1,1]
	v_add_f32_e32 v10, v10, v11
	v_add_f32_e32 v4, v34, v35
	v_add_f32_e32 v12, v32, v33
	v_mov_b32_e32 v11, v30
	v_mov_b32_e32 v3, v31
	v_mov_b32_e32 v5, v28
	v_mov_b32_e32 v13, v29
	v_pk_add_f32 v[2:3], v[10:11], v[2:3]
	v_pk_add_f32 v[4:5], v[4:5], v[12:13]
	v_pk_fma_f32 v[26:27], v[64:65], v[6:7], v[56:57] op_sel_hi:[0,1,1]
	v_pk_fma_f32 v[16:17], v[64:65], v[8:9], v[58:59] op_sel_hi:[0,1,1]
	v_pk_add_f32 v[2:3], v[2:3], v[4:5]
	v_pk_mov_b32 v[4:5], v[26:27], v[16:17] op_sel:[1,0]
	v_mov_b32_e32 v6, v26
	v_mov_b32_e32 v7, v17
	v_pk_add_f32 v[4:5], v[4:5], v[6:7]
	v_pk_add_f32 v[2:3], v[2:3], v[2:3] op_sel:[0,1] op_sel_hi:[1,0]
	v_pk_add_f32 v[4:5], v[4:5], v[4:5] op_sel:[0,1] op_sel_hi:[1,0]
	v_pk_fma_f32 v[10:11], v[64:65], v[20:21], v[62:63] op_sel_hi:[0,1,1]
	v_pk_fma_f32 v[12:13], v[64:65], v[18:19], v[60:61] op_sel_hi:[0,1,1]
	v_pk_fma_f32 v[6:7], v[64:65], v[24:25], v[72:73] op_sel_hi:[0,1,1]
	v_pk_fma_f32 v[8:9], v[64:65], v[22:23], v[70:71] op_sel_hi:[0,1,1]
	v_add_f32_e32 v14, v12, v13
	v_add_f32_e32 v18, v10, v11
	v_mov_b32_e32 v3, v8
	v_mov_b32_e32 v5, v9
	v_mov_b32_e32 v15, v6
	v_mov_b32_e32 v19, v7
	v_pk_add_f32 v[2:3], v[2:3], v[4:5]
	v_pk_add_f32 v[4:5], v[14:15], v[18:19]
	s_nop 0
	v_pk_add_f32 v[2:3], v[2:3], v[4:5]
	v_and_b32_e32 v4, 64, v240
	v_add_f32_e32 v2, v2, v3
	v_xor_b32_e32 v3, 16, v240
	v_add_u32_e32 v4, 64, v4
	v_cmp_lt_i32_e32 vcc, v3, v4
	s_nop 1
	v_cndmask_b32_e32 v3, v240, v3, vcc
	v_lshlrev_b32_e32 v20, 2, v3
	s_waitcnt lgkmcnt(0)
	v_mov_b32_e32 v3, v2
	s_nop 1
	v_permlane16_swap_b32_e32 v2, v3
	v_add_f32_e32 v2, v2, v3
	v_xor_b32_e32 v3, 32, v240
	v_cmp_lt_i32_e32 vcc, v3, v4
	s_nop 1
	v_cndmask_b32_e32 v3, v240, v3, vcc
	v_lshlrev_b32_e32 v21, 2, v3
	s_waitcnt lgkmcnt(0)
; __device__ __forceinline__ void ret_unit(LAS unsigned char* lds, const bfu* PROJ, const bfu* RT, const float* gn_g, bfu* CAT, int u) {
;     ...
;     s += __shfl_xor(s, 16); s += __shfl_xor(s, 32); const float mu = s * (1.f / 128.f); float q = 0.f;
; #pragma unroll
;     for (int t = 0; t < 8; ++t) { acc[t] = acc[t] - mu; q += (acc[t][0] * acc[t][0] + acc[t][1] * acc[t][1]) + (acc[t][2] * acc[t][2] + acc[t][3] * acc[t][3]); }
;     q += __shfl_xor(q, 16); q += __shfl_xor(q, 32); const float rstd = 1.f / sqrtf(q * (1.f / 128.f) + EPS);
;     const bfu* gp = P0 + (size_t)c * INW + C_RG + 4 * fq; bfu* op = CAT + (row0 + c) * DM + h * 128 + 4 * fq; const float* gg = gn_g + h * 128 + 4 * fq;
; #pragma unroll
;     for (int t = 0; t < 8; ++t) { const v2u gw = *(const v2u*)(gp + 16 * t); const f32x4 g4 = *(const f32x4*)(gg + 16 * t);
	v_mov_b32_e32 v3, v2
	v_mov_b32_e32 v22, v2
	s_nop 1
	v_permlane32_swap_b32_e32 v22, v3
	v_add_f32_e32 v22, v22, v3
	v_fmamk_f32 v47, v22, 0xbc000000, v47
	v_fmamk_f32 v43, v22, 0xbc000000, v43
	v_fmamk_f32 v45, v22, 0xbc000000, v45
	v_fmac_f32_e32 v46, 0xbc000000, v22
	v_fmamk_f32 v41, v22, 0xbc000000, v41
	v_fmac_f32_e32 v42, 0xbc000000, v22
	v_mov_b32_e32 v4, v47
	v_mov_b32_e32 v5, v43
	v_fmac_f32_e32 v44, 0xbc000000, v22
	v_fmac_f32_e32 v40, 0xbc000000, v22
	v_mov_b32_e32 v2, v46
	v_mov_b32_e32 v3, v42
	v_pk_mul_f32 v[4:5], v[4:5], v[4:5]
	v_mov_b32_e32 v14, v45
	v_mov_b32_e32 v15, v41
	v_pk_fma_f32 v[2:3], v[2:3], v[2:3], v[4:5]
	v_mov_b32_e32 v4, v44
	v_mov_b32_e32 v5, v40
	v_pk_mul_f32 v[14:15], v[14:15], v[14:15]
	v_fmamk_f32 v39, v22, 0xbc000000, v39
	v_pk_fma_f32 v[4:5], v[4:5], v[4:5], v[14:15]
	v_fmac_f32_e32 v38, 0xbc000000, v22
	v_pk_add_f32 v[2:3], v[2:3], v[4:5]
	v_fmamk_f32 v37, v22, 0xbc000000, v37
	v_fmac_f32_e32 v36, 0xbc000000, v22
	v_pk_add_f32 v[2:3], v[2:3], v[2:3] op_sel_hi:[0,1]
	v_pk_mul_f32 v[4:5], v[36:37], v[36:37]
	v_pk_mul_f32 v[14:15], v[38:39], v[38:39]
	v_fmac_f32_e32 v34, 0xbc000000, v22
	v_pk_mov_b32 v[18:19], v[14:15], v[4:5] op_sel:[1,0]
	v_mov_b32_e32 v15, v5
	v_fmac_f32_e32 v32, 0xbc000000, v22
	v_fmamk_f32 v35, v22, 0xbc000000, v35
	v_mul_f32_e32 v2, v34, v34
	v_pk_add_f32 v[4:5], v[18:19], v[14:15]
	v_fmamk_f32 v33, v22, 0xbc000000, v33
	v_pk_fma_f32 v[14:15], v[34:35], v[34:35], v[2:3] op_sel_hi:[1,1,0]
	v_mul_f32_e32 v2, v32, v32
	v_pk_add_f32 v[4:5], v[4:5], v[4:5] op_sel_hi:[0,1]
	v_pk_fma_f32 v[18:19], v[32:33], v[32:33], v[2:3] op_sel_hi:[1,1,0]
	v_fmamk_f32 v29, v22, 0xbc000000, v29
	v_fmac_f32_e32 v28, 0xbc000000, v22
	v_fmamk_f32 v31, v22, 0xbc000000, v31
	v_fmac_f32_e32 v30, 0xbc000000, v22
	v_mul_f32_e32 v14, v30, v30
	v_mul_f32_e32 v18, v31, v31
	v_mul_f32_e32 v4, v28, v28
	v_mul_f32_e32 v2, v29, v29
	v_pk_add_f32 v[14:15], v[14:15], v[18:19]
	v_pk_add_f32 v[2:3], v[4:5], v[2:3]
	v_fmamk_f32 v27, v22, 0xbc000000, v27
	v_pk_add_f32 v[2:3], v[14:15], v[2:3]
	v_fmac_f32_e32 v26, 0xbc000000, v22
	v_fmamk_f32 v17, v22, 0xbc000000, v17
	v_fmac_f32_e32 v16, 0xbc000000, v22
	v_pk_add_f32 v[2:3], v[2:3], v[2:3] op_sel_hi:[0,1]
	v_pk_mul_f32 v[4:5], v[16:17], v[16:17]
	v_pk_mul_f32 v[14:15], v[26:27], v[26:27]
	v_fmac_f32_e32 v12, 0xbc000000, v22
	v_pk_mov_b32 v[18:19], v[14:15], v[4:5] op_sel:[1,0]
	v_mov_b32_e32 v15, v5
	v_fmac_f32_e32 v10, 0xbc000000, v22
	v_fmamk_f32 v13, v22, 0xbc000000, v13
	v_mul_f32_e32 v2, v12, v12
	v_pk_add_f32 v[4:5], v[18:19], v[14:15]
	v_fmamk_f32 v11, v22, 0xbc000000, v11
	v_pk_fma_f32 v[14:15], v[12:13], v[12:13], v[2:3] op_sel_hi:[1,1,0]
	v_mul_f32_e32 v2, v10, v10
	v_pk_add_f32 v[4:5], v[4:5], v[4:5] op_sel_hi:[0,1]
	v_pk_fma_f32 v[18:19], v[10:11], v[10:11], v[2:3] op_sel_hi:[1,1,0]
	v_fmamk_f32 v7, v22, 0xbc000000, v7
	v_fmac_f32_e32 v6, 0xbc000000, v22
	v_fmamk_f32 v9, v22, 0xbc000000, v9
	v_fmac_f32_e32 v8, 0xbc000000, v22
	v_mul_f32_e32 v14, v8, v8
	v_mul_f32_e32 v18, v9, v9
	v_mul_f32_e32 v4, v6, v6
	v_mul_f32_e32 v2, v7, v7
	v_pk_add_f32 v[14:15], v[14:15], v[18:19]
	v_pk_add_f32 v[2:3], v[4:5], v[2:3]
	s_nop 0
	v_pk_add_f32 v[2:3], v[14:15], v[2:3]
	s_nop 0
	v_add_f32_e32 v2, v2, v3
	s_waitcnt lgkmcnt(0)
	v_mov_b32_e32 v3, v2
	s_nop 1
	v_permlane16_swap_b32_e32 v2, v3
	v_add_f32_e32 v2, v2, v3
	v_mov_b32_e32 v3, v2
	s_nop 1
	v_permlane32_swap_b32_e32 v2, v3
	v_add_f32_e32 v2, v2, v3
	v_fmamk_f32 v2, v2, 0x3c000000, v236
	v_cmp_gt_f32_e32 vcc, s68, v2
	v_mul_f32_e32 v3, 0x4f800000, v2
	s_nop 0
	v_cndmask_b32_e32 v2, v2, v3, vcc
	v_sqrt_f32_e32 v3, v2
	s_nop 0
	v_add_u32_e32 v4, -1, v3
	v_fma_f32 v5, -v4, v3, v2
	v_cmp_ge_f32_e64 s[40:41], 0, v5
	v_add_u32_e32 v5, 1, v3
	s_nop 0
	v_cndmask_b32_e64 v4, v3, v4, s[40:41]
	v_fma_f32 v3, -v5, v3, v2
	v_cmp_lt_f32_e64 s[40:41], 0, v3
	s_nop 1
	v_cndmask_b32_e64 v3, v4, v5, s[40:41]
	v_mul_f32_e32 v4, 0x37800000, v3
	v_cndmask_b32_e32 v3, v3, v4, vcc
	v_cmp_class_f32_e32 vcc, v2, v234
	s_nop 1
	v_cndmask_b32_e32 v2, v3, v2, vcc
	v_div_scale_f32 v3, s[22:23], v2, v2, 1.0
	v_rcp_f32_e32 v4, v3
	s_nop 0
	v_fma_f32 v5, -v3, v4, 1.0
	v_fmac_f32_e32 v4, v5, v4
	v_div_scale_f32 v5, vcc, 1.0, v2, 1.0
	v_mul_f32_e32 v14, v5, v4
	v_fma_f32 v15, -v3, v14, v5
	v_fmac_f32_e32 v14, v15, v4
	v_fma_f32 v3, -v3, v14, v5
	v_div_fmas_f32 v3, v3, v4, v14
	v_lshl_add_u64 v[4:5], s[46:47], 0, v[66:67]
	v_div_fixup_f32 v14, v3, v2, 1.0
	v_mov_b64_e32 v[2:3], s[56:57]
	v_lshlrev_b64 v[4:5], 12, v[4:5]
	v_mad_i64_i32 v[2:3], s[22:23], v66, s61, v[2:3]
	v_lshl_add_u64 v[4:5], s[44:45], 0, v[4:5]
	v_lshl_add_u64 v[2:3], v[2:3], 0, v[0:1]
	s_mov_b64 s[22:23], 0x1200
	v_lshl_add_u64 v[4:5], v[4:5], 0, s[52:53]
	v_lshl_add_u64 v[20:21], v[2:3], 0, s[22:23]
	v_lshl_add_u64 v[22:23], v[4:5], 0, v[0:1]
	s_mov_b64 s[22:23], 0x29600000
	v_lshl_add_u64 v[18:19], v[22:23], 0, s[22:23]
	s_lshl_b64 s[22:23], s[50:51], 2
	v_add_co_u32_e32 v2, vcc, s62, v2
	s_add_u32 s40, s20, s22
	s_nop 0
	v_addc_co_u32_e32 v3, vcc, 0, v3, vcc
	s_addc_u32 s41, s35, s23
	global_load_dwordx2 v[120:121], v[2:3], off offset:512
	global_load_dwordx4 v[122:125], v69, s[40:41]
	global_load_dwordx2 v[126:127], v[20:21], off offset:32
	global_load_dwordx4 v[128:131], v69, s[40:41] offset:64
	global_load_dwordx2 v[132:133], v[20:21], off offset:64
	global_load_dwordx4 v[134:137], v69, s[40:41] offset:128
	global_load_dwordx2 v[138:139], v[20:21], off offset:96
	global_load_dwordx4 v[140:143], v69, s[40:41] offset:192
	global_load_dwordx2 v[144:145], v[20:21], off offset:128
	global_load_dwordx4 v[146:149], v69, s[40:41] offset:256
	global_load_dwordx2 v[150:151], v[20:21], off offset:160
	global_load_dwordx4 v[152:155], v69, s[40:41] offset:320
	global_load_dwordx2 v[156:157], v[20:21], off offset:192
	global_load_dwordx4 v[158:161], v69, s[40:41] offset:384
	global_load_dwordx2 v[162:163], v[20:21], off offset:224
	global_load_dwordx4 v[164:167], v69, s[40:41] offset:448
	s_nop 0
	s_mov_b32 s20, 0x29600000
	s_waitcnt vmcnt(0)
; __device__ __forceinline__ unsigned pk2(float lo, float hi) { return pg8::cvt_pk_bf16(lo, hi); }
; __device__ __forceinline__ float silu_f(float g) { return g * frcp(1.f + fexp2(-LOG2E * g)); }
; __device__ __forceinline__ void ret_unit(LAS unsigned char* lds, const bfu* PROJ, const bfu* RT, const float* gn_g, bfu* CAT, int u) {
;     ...
;     for (int t = 0; t < 8; ++t) { const v2u gw = *(const v2u*)(gp + 16 * t); const f32x4 g4 = *(const f32x4*)(gg + 16 * t);
;         const float o0 = silu_f(bflo(gw.x)) * acc[t][0] * rstd * g4.x, o1 = silu_f(bfhi(gw.x)) * acc[t][1] * rstd * g4.y, o2 = silu_f(bflo(gw.y)) * acc[t][2] * rstd * g4.z, o3 = silu_f(bfhi(gw.y)) * acc[t][3] * rstd * g4.w;
;         v2u w; w.x = pk2(o0, o1); w.y = pk2(o2, o3); *(v2u*)(op + 16 * t) = w; }
	v_lshlrev_b32_e32 v48, 16, v120
	v_mul_f32_e32 v0, 0xbfb8aa3b, v48
	v_exp_f32_e32 v0, v0
	v_and_b32_e32 v49, 0xffff0000, v120
	v_lshlrev_b32_e32 v24, 16, v121
	v_and_b32_e32 v25, 0xffff0000, v121
	v_add_f32_e32 v0, 1.0, v0
	v_rcp_f32_e32 v50, v0
	v_mul_f32_e32 v0, 0xbfb8aa3b, v49
	v_exp_f32_e32 v0, v0
	s_nop 0
	v_add_f32_e32 v0, 1.0, v0
	v_rcp_f32_e32 v51, v0
	v_mul_f32_e32 v0, 0xbfb8aa3b, v24
	v_exp_f32_e32 v0, v0
	v_pk_mul_f32 v[48:49], v[50:51], v[48:49]
	s_nop 0
	v_pk_mul_f32 v[46:47], v[46:47], v[48:49]
	v_add_f32_e32 v0, 1.0, v0
	v_pk_mul_f32 v[46:47], v[46:47], v[14:15] op_sel_hi:[1,0]
	v_pk_mul_f32 v[2:3], v[122:123], v[46:47]
	v_rcp_f32_e32 v46, v0
	v_mul_f32_e32 v0, 0xbfb8aa3b, v25
	v_exp_f32_e32 v0, v0
	v_cvt_pk_bf16_f32 v2, v2, v3
	v_add_f32_e32 v0, 1.0, v0
	v_rcp_f32_e32 v47, v0
	s_nop 0
	v_pk_mul_f32 v[24:25], v[46:47], v[24:25]
	s_nop 0
	v_pk_mul_f32 v[24:25], v[44:45], v[24:25]
	s_nop 0
	v_pk_mul_f32 v[24:25], v[24:25], v[14:15] op_sel_hi:[1,0]
	s_nop 0
	v_pk_mul_f32 v[4:5], v[124:125], v[24:25]
	s_nop 0
	v_cvt_pk_bf16_f32 v3, v4, v5
	v_add_co_u32_e32 v4, vcc, s20, v22
	s_nop 1
	v_addc_co_u32_e32 v5, vcc, 0, v23, vcc
	global_store_dwordx2 v[4:5], v[2:3], off
	s_nop 0
	v_lshlrev_b32_e32 v24, 16, v126
	v_mul_f32_e32 v0, 0xbfb8aa3b, v24
	v_exp_f32_e32 v0, v0
	v_and_b32_e32 v25, 0xffff0000, v126
	v_lshlrev_b32_e32 v22, 16, v127
	v_and_b32_e32 v23, 0xffff0000, v127
	v_add_f32_e32 v0, 1.0, v0
	v_rcp_f32_e32 v44, v0
	v_mul_f32_e32 v0, 0xbfb8aa3b, v25
	v_exp_f32_e32 v0, v0
	s_nop 0
	v_add_f32_e32 v0, 1.0, v0
	v_rcp_f32_e32 v45, v0
	v_mul_f32_e32 v0, 0xbfb8aa3b, v22
	v_exp_f32_e32 v0, v0
	v_pk_mul_f32 v[24:25], v[44:45], v[24:25]
	s_nop 0
	v_pk_mul_f32 v[24:25], v[42:43], v[24:25]
	v_add_f32_e32 v0, 1.0, v0
	v_pk_mul_f32 v[24:25], v[24:25], v[14:15] op_sel_hi:[1,0]
	v_pk_mul_f32 v[2:3], v[128:129], v[24:25]
	v_rcp_f32_e32 v24, v0
	v_mul_f32_e32 v0, 0xbfb8aa3b, v23
	v_exp_f32_e32 v0, v0
	v_cvt_pk_bf16_f32 v2, v2, v3
	v_add_f32_e32 v0, 1.0, v0
	v_rcp_f32_e32 v25, v0
	s_nop 0
	v_pk_mul_f32 v[22:23], v[24:25], v[22:23]
	s_nop 0
	v_pk_mul_f32 v[22:23], v[40:41], v[22:23]
	s_nop 0
	v_pk_mul_f32 v[22:23], v[22:23], v[14:15] op_sel_hi:[1,0]
	s_nop 0
	v_pk_mul_f32 v[4:5], v[130:131], v[22:23]
	s_nop 0
	v_cvt_pk_bf16_f32 v3, v4, v5
	global_store_dwordx2 v[18:19], v[2:3], off offset:32
	s_nop 0
	v_lshlrev_b32_e32 v24, 16, v132
	v_mul_f32_e32 v0, 0xbfb8aa3b, v24
	v_exp_f32_e32 v0, v0
	v_and_b32_e32 v25, 0xffff0000, v132
	v_lshlrev_b32_e32 v22, 16, v133
	v_and_b32_e32 v23, 0xffff0000, v133
	v_add_f32_e32 v0, 1.0, v0
	v_rcp_f32_e32 v40, v0
	v_mul_f32_e32 v0, 0xbfb8aa3b, v25
	v_exp_f32_e32 v0, v0
	s_nop 0
	v_add_f32_e32 v0, 1.0, v0
	v_rcp_f32_e32 v41, v0
	v_mul_f32_e32 v0, 0xbfb8aa3b, v22
	v_exp_f32_e32 v0, v0
	v_pk_mul_f32 v[24:25], v[40:41], v[24:25]
	s_nop 0
	v_pk_mul_f32 v[24:25], v[38:39], v[24:25]
	v_add_f32_e32 v0, 1.0, v0
	v_pk_mul_f32 v[24:25], v[24:25], v[14:15] op_sel_hi:[1,0]
	v_pk_mul_f32 v[2:3], v[134:135], v[24:25]
	v_rcp_f32_e32 v24, v0
	v_mul_f32_e32 v0, 0xbfb8aa3b, v23
	v_exp_f32_e32 v0, v0
	v_cvt_pk_bf16_f32 v2, v2, v3
	v_add_f32_e32 v0, 1.0, v0
	v_rcp_f32_e32 v25, v0
	s_nop 0
	v_pk_mul_f32 v[22:23], v[24:25], v[22:23]
	s_nop 0
	v_pk_mul_f32 v[22:23], v[36:37], v[22:23]
	s_nop 0
	v_pk_mul_f32 v[22:23], v[22:23], v[14:15] op_sel_hi:[1,0]
	s_nop 0
	v_pk_mul_f32 v[4:5], v[136:137], v[22:23]
	s_nop 0
	v_cvt_pk_bf16_f32 v3, v4, v5
	global_store_dwordx2 v[18:19], v[2:3], off offset:64
	s_nop 0
	v_lshlrev_b32_e32 v24, 16, v138
	v_mul_f32_e32 v0, 0xbfb8aa3b, v24
	v_exp_f32_e32 v0, v0
	v_and_b32_e32 v25, 0xffff0000, v138
	v_lshlrev_b32_e32 v22, 16, v139
	v_and_b32_e32 v23, 0xffff0000, v139
	v_add_f32_e32 v0, 1.0, v0
	v_rcp_f32_e32 v36, v0
	v_mul_f32_e32 v0, 0xbfb8aa3b, v25
	v_exp_f32_e32 v0, v0
	s_nop 0
	v_add_f32_e32 v0, 1.0, v0
	v_rcp_f32_e32 v37, v0
	v_mul_f32_e32 v0, 0xbfb8aa3b, v22
	v_exp_f32_e32 v0, v0
	v_pk_mul_f32 v[24:25], v[36:37], v[24:25]
	s_nop 0
	v_pk_mul_f32 v[24:25], v[34:35], v[24:25]
	v_add_f32_e32 v0, 1.0, v0
	v_pk_mul_f32 v[24:25], v[24:25], v[14:15] op_sel_hi:[1,0]
	v_pk_mul_f32 v[2:3], v[140:141], v[24:25]
	v_rcp_f32_e32 v24, v0
	v_mul_f32_e32 v0, 0xbfb8aa3b, v23
	v_exp_f32_e32 v0, v0
	v_cvt_pk_bf16_f32 v2, v2, v3
	v_add_f32_e32 v0, 1.0, v0
	v_rcp_f32_e32 v25, v0
	s_nop 0
	v_pk_mul_f32 v[22:23], v[24:25], v[22:23]
	s_nop 0
	v_pk_mul_f32 v[22:23], v[32:33], v[22:23]
	s_nop 0
	v_pk_mul_f32 v[22:23], v[22:23], v[14:15] op_sel_hi:[1,0]
	s_nop 0
	v_pk_mul_f32 v[4:5], v[142:143], v[22:23]
	s_nop 0
	v_cvt_pk_bf16_f32 v3, v4, v5
	global_store_dwordx2 v[18:19], v[2:3], off offset:96
; __device__ __forceinline__ unsigned pk2(float lo, float hi) { return pg8::cvt_pk_bf16(lo, hi); }
; __device__ __forceinline__ float silu_f(float g) { return g * frcp(1.f + fexp2(-LOG2E * g)); }
; __device__ __forceinline__ void ret_unit(LAS unsigned char* lds, const bfu* PROJ, const bfu* RT, const float* gn_g, bfu* CAT, int u) {
;     ...
;     for (int t = 0; t < 8; ++t) { const v2u gw = *(const v2u*)(gp + 16 * t); const f32x4 g4 = *(const f32x4*)(gg + 16 * t);
;         const float o0 = silu_f(bflo(gw.x)) * acc[t][0] * rstd * g4.x, o1 = silu_f(bfhi(gw.x)) * acc[t][1] * rstd * g4.y, o2 = silu_f(bflo(gw.y)) * acc[t][2] * rstd * g4.z, o3 = silu_f(bfhi(gw.y)) * acc[t][3] * rstd * g4.w;
;         v2u w; w.x = pk2(o0, o1); w.y = pk2(o2, o3); *(v2u*)(op + 16 * t) = w; }
;     __syncthreads();
	s_nop 0
	v_lshlrev_b32_e32 v24, 16, v144
	v_mul_f32_e32 v0, 0xbfb8aa3b, v24
	v_exp_f32_e32 v0, v0
	v_and_b32_e32 v25, 0xffff0000, v144
	v_lshlrev_b32_e32 v22, 16, v145
	v_and_b32_e32 v23, 0xffff0000, v145
	v_add_f32_e32 v0, 1.0, v0
	v_rcp_f32_e32 v32, v0
	v_mul_f32_e32 v0, 0xbfb8aa3b, v25
	v_exp_f32_e32 v0, v0
	s_nop 0
	v_add_f32_e32 v0, 1.0, v0
	v_rcp_f32_e32 v33, v0
	v_mul_f32_e32 v0, 0xbfb8aa3b, v22
	v_exp_f32_e32 v0, v0
	v_pk_mul_f32 v[24:25], v[32:33], v[24:25]
	s_nop 0
	v_pk_mul_f32 v[24:25], v[30:31], v[24:25]
	v_add_f32_e32 v0, 1.0, v0
	v_pk_mul_f32 v[24:25], v[24:25], v[14:15] op_sel_hi:[1,0]
	v_pk_mul_f32 v[2:3], v[146:147], v[24:25]
	v_rcp_f32_e32 v24, v0
	v_mul_f32_e32 v0, 0xbfb8aa3b, v23
	v_exp_f32_e32 v0, v0
	v_cvt_pk_bf16_f32 v2, v2, v3
	v_add_f32_e32 v0, 1.0, v0
	v_rcp_f32_e32 v25, v0
	s_nop 0
	v_pk_mul_f32 v[22:23], v[24:25], v[22:23]
	s_nop 0
	v_pk_mul_f32 v[22:23], v[28:29], v[22:23]
	s_nop 0
	v_pk_mul_f32 v[22:23], v[22:23], v[14:15] op_sel_hi:[1,0]
	s_nop 0
	v_pk_mul_f32 v[4:5], v[148:149], v[22:23]
	s_nop 0
	v_cvt_pk_bf16_f32 v3, v4, v5
	global_store_dwordx2 v[18:19], v[2:3], off offset:128
	s_nop 0
	v_lshlrev_b32_e32 v24, 16, v150
	v_mul_f32_e32 v0, 0xbfb8aa3b, v24
	v_exp_f32_e32 v0, v0
	v_and_b32_e32 v25, 0xffff0000, v150
	v_lshlrev_b32_e32 v22, 16, v151
	v_and_b32_e32 v23, 0xffff0000, v151
	v_add_f32_e32 v0, 1.0, v0
	v_rcp_f32_e32 v28, v0
	v_mul_f32_e32 v0, 0xbfb8aa3b, v25
	v_exp_f32_e32 v0, v0
	s_nop 0
	v_add_f32_e32 v0, 1.0, v0
	v_rcp_f32_e32 v29, v0
	v_mul_f32_e32 v0, 0xbfb8aa3b, v22
	v_exp_f32_e32 v0, v0
	v_pk_mul_f32 v[24:25], v[28:29], v[24:25]
	s_nop 0
	v_pk_mul_f32 v[24:25], v[26:27], v[24:25]
	v_add_f32_e32 v0, 1.0, v0
	v_pk_mul_f32 v[24:25], v[14:15], v[24:25] op_sel_hi:[0,1]
	v_pk_mul_f32 v[2:3], v[152:153], v[24:25]
	v_rcp_f32_e32 v24, v0
	v_mul_f32_e32 v0, 0xbfb8aa3b, v23
	v_exp_f32_e32 v0, v0
	v_cvt_pk_bf16_f32 v2, v2, v3
	v_add_f32_e32 v0, 1.0, v0
	v_rcp_f32_e32 v25, v0
	s_nop 0
	v_pk_mul_f32 v[22:23], v[24:25], v[22:23]
	s_nop 0
	v_pk_mul_f32 v[16:17], v[16:17], v[22:23]
	s_nop 0
	v_pk_mul_f32 v[16:17], v[14:15], v[16:17] op_sel_hi:[0,1]
	v_pk_mul_f32 v[4:5], v[154:155], v[16:17]
	s_nop 0
	v_cvt_pk_bf16_f32 v3, v4, v5
	global_store_dwordx2 v[18:19], v[2:3], off offset:160
	s_nop 0
	v_lshlrev_b32_e32 v22, 16, v156
	v_mul_f32_e32 v0, 0xbfb8aa3b, v22
	v_exp_f32_e32 v0, v0
	v_and_b32_e32 v23, 0xffff0000, v156
	v_add_f32_e32 v0, 1.0, v0
	v_rcp_f32_e32 v24, v0
	v_mul_f32_e32 v0, 0xbfb8aa3b, v23
	v_exp_f32_e32 v0, v0
	s_nop 0
	v_add_f32_e32 v0, 1.0, v0
	v_rcp_f32_e32 v25, v0
	s_nop 0
	v_pk_mul_f32 v[22:23], v[24:25], v[22:23]
	s_nop 0
	v_pk_mul_f32 v[12:13], v[12:13], v[22:23]
	s_nop 0
	v_pk_mul_f32 v[12:13], v[14:15], v[12:13] op_sel_hi:[0,1]
	v_pk_mul_f32 v[2:3], v[158:159], v[12:13]
	v_lshlrev_b32_e32 v12, 16, v157
	v_mul_f32_e32 v0, 0xbfb8aa3b, v12
	v_exp_f32_e32 v0, v0
	v_and_b32_e32 v13, 0xffff0000, v157
	v_cvt_pk_bf16_f32 v2, v2, v3
	v_add_f32_e32 v0, 1.0, v0
	v_rcp_f32_e32 v16, v0
	v_mul_f32_e32 v0, 0xbfb8aa3b, v13
	v_exp_f32_e32 v0, v0
	s_nop 0
	v_add_f32_e32 v0, 1.0, v0
	v_rcp_f32_e32 v17, v0
	s_nop 0
	v_pk_mul_f32 v[12:13], v[16:17], v[12:13]
	s_nop 0
	v_pk_mul_f32 v[10:11], v[10:11], v[12:13]
	s_nop 0
	v_pk_mul_f32 v[10:11], v[14:15], v[10:11] op_sel_hi:[0,1]
	v_pk_mul_f32 v[4:5], v[160:161], v[10:11]
	s_nop 0
	v_cvt_pk_bf16_f32 v3, v4, v5
	global_store_dwordx2 v[18:19], v[2:3], off offset:192
	s_nop 0
	v_lshlrev_b32_e32 v12, 16, v162
	v_mul_f32_e32 v0, 0xbfb8aa3b, v12
	v_exp_f32_e32 v0, v0
	v_and_b32_e32 v13, 0xffff0000, v162
	v_add_f32_e32 v0, 1.0, v0
	v_rcp_f32_e32 v16, v0
	v_mul_f32_e32 v0, 0xbfb8aa3b, v13
	v_exp_f32_e32 v0, v0
	s_nop 0
	v_add_f32_e32 v0, 1.0, v0
	v_rcp_f32_e32 v17, v0
	s_nop 0
	v_pk_mul_f32 v[12:13], v[16:17], v[12:13]
	s_nop 0
	v_pk_mul_f32 v[8:9], v[8:9], v[12:13]
	s_nop 0
	v_pk_mul_f32 v[8:9], v[14:15], v[8:9] op_sel_hi:[0,1]
	v_pk_mul_f32 v[2:3], v[164:165], v[8:9]
	v_lshlrev_b32_e32 v8, 16, v163
	v_mul_f32_e32 v0, 0xbfb8aa3b, v8
	v_exp_f32_e32 v0, v0
	v_and_b32_e32 v9, 0xffff0000, v163
	v_cvt_pk_bf16_f32 v2, v2, v3
	v_add_f32_e32 v0, 1.0, v0
	v_rcp_f32_e32 v10, v0
	v_mul_f32_e32 v0, 0xbfb8aa3b, v9
	v_exp_f32_e32 v0, v0
	s_nop 0
	v_add_f32_e32 v0, 1.0, v0
	v_rcp_f32_e32 v11, v0
	s_nop 0
	v_pk_mul_f32 v[8:9], v[10:11], v[8:9]
	s_nop 0
	v_pk_mul_f32 v[6:7], v[6:7], v[8:9]
	s_nop 0
	v_pk_mul_f32 v[6:7], v[14:15], v[6:7] op_sel_hi:[0,1]
	v_pk_mul_f32 v[4:5], v[166:167], v[6:7]
	s_nop 0
	v_cvt_pk_bf16_f32 v3, v4, v5
	global_store_dwordx2 v[18:19], v[2:3], off offset:224
	s_barrier

; __device__ __forceinline__ unsigned pk2(float lo, float hi) { return pg8::cvt_pk_bf16(lo, hi); }
; __device__ __forceinline__ void diff_final(const bfu* D0, const bfu* D1, float lam, const float* sg, float omli, bfu* CAT, int gw, int NGW, int lane) {
;     ...
;     for (int it = gw * 2 + half; it < M * 6; it += NGW * 2) { const int row = it / 6, h = it - row * 6;
;         const v2u a_ = __builtin_nontemporal_load((const v2u*)(D0 + (size_t)row * 768 + h * 128 + l32 * 4)), b_ = __builtin_nontemporal_load((const v2u*)(D1 + (size_t)row * 768 + h * 128 + l32 * 4));
;         const f32x4 v = (f32x4){bflo(a_.x), bfhi(a_.x), bflo(a_.y), bfhi(a_.y)} - (f32x4){bflo(b_.x), bfhi(b_.x), bflo(b_.y), bfhi(b_.y)} * lam; float s = (v.x * v.x + v.y * v.y) + (v.z * v.z + v.w * v.w);
; #pragma unroll
;         for (int o = 1; o < 32; o <<= 1) s += __shfl_xor(s, o);
;         const float r = omli / sqrtf(s * (1.f / 128.f) + EPS); const f32x4 g4 = *(const f32x4*)(sg + h * 128 + l32 * 4);
;         v2u w; w.x = pk2(v.x * r * g4.x, v.y * r * g4.y); w.y = pk2(v.z * r * g4.z, v.w * r * g4.w); *(v2u*)(CAT + (size_t)row * DM + 768 + h * 128 + l32 * 4) = w; }
.LBB0_501:
	s_mov_b32 s22, 0x2aaaaaab
	v_mul_hi_i32 v16, v10, s22
	v_lshrrev_b32_e32 v17, 31, v16
	v_mov_b64_e32 v[12:13], s[40:41]
	v_add_u32_e32 v16, v16, v17
	v_mad_i64_i32 v[12:13], s[22:23], v16, s66, v[12:13]
	s_movk_i32 s22, 0xfd00
	s_nop 0
	v_mad_u64_u32 v[18:19], s[22:23], v16, s22, v[4:5]
	v_ashrrev_i32_e32 v19, 31, v18
	v_mov_b64_e32 v[14:15], s[44:45]
	v_lshlrev_b64 v[20:21], 1, v[18:19]
	v_mad_i64_i32 v[14:15], s[22:23], v16, s66, v[14:15]
	v_lshl_add_u64 v[12:13], v[12:13], 0, v[20:21]
	v_lshl_add_u64 v[14:15], v[14:15], 0, v[20:21]
	v_lshl_add_u64 v[12:13], v[12:13], 0, v[0:1]
	v_lshl_add_u64 v[14:15], v[14:15], 0, v[0:1]
	global_load_dwordx2 v[22:23], v[12:13], off nt
	global_load_dwordx2 v[24:25], v[14:15], off nt
	v_ashrrev_i32_e32 v17, 31, v16
	v_lshlrev_b64 v[12:13], 12, v[16:17]
	v_lshl_add_u64 v[14:15], v[18:19], 2, v[2:3]
	v_lshl_add_u64 v[16:17], s[34:35], 0, v[12:13]
	global_load_dwordx4 v[12:15], v[14:15], off
	s_xor_b32 s47, s20, 0x80000000
	v_lshl_add_u64 v[16:17], v[16:17], 0, v[20:21]
	v_add_u32_e32 v10, s55, v10
	s_mov_b32 s22, 0x17fff
	v_cmp_lt_i32_e32 vcc, s22, v10
	s_or_b64 s[36:37], vcc, s[36:37]
	v_lshl_add_u64 v[16:17], v[16:17], 0, v[0:1]
	v_add_u32_e32 v4, s91, v4
	s_waitcnt vmcnt(2)
	v_lshlrev_b32_e32 v18, 16, v22
	v_and_b32_e32 v19, 0xffff0000, v22
	v_lshlrev_b32_e32 v20, 16, v23
	v_and_b32_e32 v21, 0xffff0000, v23
	s_waitcnt vmcnt(1)
	v_lshlrev_b32_e32 v22, 16, v24
	v_and_b32_e32 v23, 0xffff0000, v24
	v_lshlrev_b32_e32 v24, 16, v25
	v_and_b32_e32 v25, 0xffff0000, v25
	v_pk_fma_f32 v[18:19], s[26:27], v[22:23], v[18:19] neg_lo:[1,0,0] neg_hi:[1,0,0]
	v_pk_fma_f32 v[20:21], s[46:47], v[24:25], v[20:21]
	v_pk_mul_f32 v[24:25], v[18:19], v[18:19]
	v_pk_mul_f32 v[22:23], v[20:21], v[20:21]
	s_nop 0
	v_pk_mov_b32 v[26:27], v[24:25], v[22:23] op_sel:[1,0]
	v_mov_b32_e32 v25, v23
	v_pk_add_f32 v[22:23], v[26:27], v[24:25]
	s_nop 0
	v_add_f32_e32 v22, v22, v23
	s_waitcnt lgkmcnt(0)
	s_nop 1
	v_add_f32_dpp v22, v22, v22 quad_perm:[1,0,3,2] row_mask:0xf bank_mask:0xf
	s_nop 1
	v_add_f32_dpp v22, v22, v22 quad_perm:[2,3,0,1] row_mask:0xf bank_mask:0xf
	s_nop 1
	v_add_f32_dpp v22, v22, v22 row_half_mirror row_mask:0xf bank_mask:0xf
	s_nop 1
	v_add_f32_dpp v22, v22, v22 row_mirror row_mask:0xf bank_mask:0xf
	v_mov_b32_e32 v23, v22
	s_nop 1
	v_permlane16_swap_b32_e32 v22, v23
	v_add_f32_e32 v22, v22, v23
	v_fmamk_f32 v22, v22, 0x3c000000, v236
	v_mul_f32_e32 v23, 0x4f800000, v22
	v_cmp_gt_f32_e32 vcc, s68, v22
	s_nop 1
	v_cndmask_b32_e32 v22, v22, v23, vcc
	v_sqrt_f32_e32 v23, v22
	s_nop 0
	v_add_u32_e32 v24, -1, v23
	v_add_u32_e32 v25, 1, v23
	v_fma_f32 v26, -v24, v23, v22
	v_fma_f32 v27, -v25, v23, v22
	v_cmp_ge_f32_e64 s[38:39], 0, v26
	s_nop 1
	v_cndmask_b32_e64 v23, v23, v24, s[38:39]
	v_cmp_lt_f32_e64 s[38:39], 0, v27
	s_nop 1
	v_cndmask_b32_e64 v23, v23, v25, s[38:39]
	v_mul_f32_e32 v24, 0x37800000, v23
	v_cndmask_b32_e32 v23, v23, v24, vcc
	v_cmp_class_f32_e32 vcc, v22, v234
	s_nop 1
	v_cndmask_b32_e32 v22, v23, v22, vcc
	v_div_scale_f32 v23, s[22:23], v22, v22, v11
	v_rcp_f32_e32 v25, v23
	v_div_scale_f32 v24, vcc, v11, v22, v11
	v_fma_f32 v26, -v23, v25, 1.0
	v_fmac_f32_e32 v25, v26, v25
	v_mul_f32_e32 v26, v24, v25
	v_fma_f32 v27, -v23, v26, v24
	v_fmac_f32_e32 v26, v27, v25
	v_fma_f32 v23, -v23, v26, v24
	v_div_fmas_f32 v23, v23, v25, v26
	v_div_fixup_f32 v22, v23, v22, v11
	v_pk_mul_f32 v[18:19], v[18:19], v[22:23] op_sel_hi:[1,0]
	v_pk_mul_f32 v[20:21], v[20:21], v[22:23] op_sel_hi:[1,0]
	v_add_co_u32_e32 v16, vcc, 0x29600000, v16
	s_waitcnt vmcnt(0)
	v_pk_mul_f32 v[12:13], v[12:13], v[18:19]
	v_pk_mul_f32 v[14:15], v[14:15], v[20:21]
	v_addc_co_u32_e32 v17, vcc, 0, v17, vcc
	v_cvt_pk_bf16_f32 v12, v12, v13
	v_cvt_pk_bf16_f32 v13, v14, v15
	global_store_dwordx2 v[16:17], v[12:13], off offset:1536
	s_andn2_b64 exec, exec, s[36:37]
	s_cbranch_execnz .LBB0_501

; template <bool FINAL, bool DUMMY = false> __device__ __forceinline__ void norm_rows(const bfu* F, bfu* XB, const float* g1, float* RS, float* xout, int gw, int NGW, int lane, bfu* dummy = nullptr) {
;     ...
;         f32x4 f[8], x[8]; float s = 0.f;
; #pragma unroll
;         for (int j = 0; j < 4; ++j) {
;             f[2 * j] = (f32x4){bflo(fw[j].x), bfhi(fw[j].x), bflo(fw[j].y), bfhi(fw[j].y)}; f[2 * j + 1] = (f32x4){bflo(fw[j].z), bfhi(fw[j].z), bflo(fw[j].w), bfhi(fw[j].w)};
;             x[2 * j] = (f32x4){bflo(xw[j].x), bfhi(xw[j].x), bflo(xw[j].y), bfhi(xw[j].y)}; x[2 * j + 1] = (f32x4){bflo(xw[j].z), bfhi(xw[j].z), bflo(xw[j].w), bfhi(xw[j].w)}; }
;         const int mn = m + NGW;
;         if (mn < M) {
; #pragma unroll
;             for (int j = 0; j < 4; ++j) { fw[j] = __builtin_nontemporal_load((const v4u*)(F + (size_t)mn * DM) + lane + 64 * j); xw[j] = ((const v4u*)(XB + (size_t)mn * DM) + lane)[64 * j]; }
;         }
; #pragma unroll
;         for (int k = 0; k < 8; ++k) s += (f[k].x * f[k].x + f[k].y * f[k].y) + (f[k].z * f[k].z + f[k].w * f[k].w);
;         const float rstd1 = 1.f / sqrtf(wave_sum(s) * (1.f / DM) + EPS);
.LBB0_638:
	v_lshlrev_b32_e32 v73, 16, v64
	v_and_b32_e32 v107, 0xffff0000, v64
	v_and_b32_e32 v106, 0xffff0000, v62
	v_lshlrev_b32_e32 v109, 16, v65
	v_and_b32_e32 v65, 0xffff0000, v65
	v_and_b32_e32 v64, 0xffff0000, v63
	v_lshlrev_b32_e32 v72, 16, v62
	v_lshlrev_b32_e32 v108, 16, v63
	v_lshlrev_b32_e32 v110, 16, v56
	v_and_b32_e32 v111, 0xffff0000, v56
	v_lshlrev_b32_e32 v112, 16, v57
	v_and_b32_e32 v113, 0xffff0000, v57
	v_lshlrev_b32_e32 v98, 16, v52
	v_and_b32_e32 v99, 0xffff0000, v52
	v_lshlrev_b32_e32 v100, 16, v53
	v_and_b32_e32 v101, 0xffff0000, v53
	v_lshlrev_b32_e32 v75, 16, v49
	v_lshlrev_b32_e32 v74, 16, v48
	v_and_b32_e32 v77, 0xffff0000, v49
	v_and_b32_e32 v76, 0xffff0000, v48
	v_lshlrev_b32_e32 v86, 16, v42
	v_and_b32_e32 v87, 0xffff0000, v42
	v_lshlrev_b32_e32 v88, 16, v43
	v_and_b32_e32 v89, 0xffff0000, v43
	v_lshlrev_b32_e32 v52, 16, v34
	v_and_b32_e32 v53, 0xffff0000, v34
	v_lshlrev_b32_e32 v56, 16, v35
	v_and_b32_e32 v57, 0xffff0000, v35
	v_lshlrev_b32_e32 v42, 16, v36
	v_and_b32_e32 v43, 0xffff0000, v36
	v_lshlrev_b32_e32 v48, 16, v37
	v_and_b32_e32 v49, 0xffff0000, v37
	v_pk_mul_f32 v[34:35], v[106:107], v[106:107]
	v_pk_mul_f32 v[36:37], v[64:65], v[64:65]
	v_pk_fma_f32 v[34:35], v[72:73], v[72:73], v[34:35]
	v_pk_fma_f32 v[36:37], v[108:109], v[108:109], v[36:37]
	v_and_b32_e32 v93, 0xffff0000, v59
	v_and_b32_e32 v92, 0xffff0000, v58
	v_pk_add_f32 v[34:35], v[34:35], v[36:37]
	v_lshlrev_b32_e32 v91, 16, v59
	v_lshlrev_b32_e32 v90, 16, v58
	v_lshlrev_b32_e32 v94, 16, v60
	v_and_b32_e32 v95, 0xffff0000, v60
	v_lshlrev_b32_e32 v96, 16, v61
	v_lshlrev_b32_e32 v82, 16, v46
	v_pk_add_f32 v[34:35], v[34:35], v[34:35] op_sel_hi:[0,1]
	v_pk_mul_f32 v[36:37], v[92:93], v[92:93]
	v_lshlrev_b32_e32 v114, 16, v54
	v_and_b32_e32 v115, 0xffff0000, v54
	v_lshlrev_b32_e32 v62, 16, v55
	v_and_b32_e32 v63, 0xffff0000, v55
	v_and_b32_e32 v97, 0xffff0000, v61
	v_lshlrev_b32_e32 v102, 16, v50
	v_and_b32_e32 v103, 0xffff0000, v50
	v_lshlrev_b32_e32 v104, 16, v51
	v_and_b32_e32 v105, 0xffff0000, v51
	v_lshlrev_b32_e32 v50, 16, v38
	v_and_b32_e32 v51, 0xffff0000, v38
	v_lshlrev_b32_e32 v54, 16, v39
	v_and_b32_e32 v55, 0xffff0000, v39
	v_pk_fma_f32 v[36:37], v[90:91], v[90:91], v[36:37]
	v_mul_f32_e32 v83, v94, v94
	v_mul_f32_e32 v39, v95, v95
	v_mul_f32_e32 v34, v96, v96
	v_mov_b32_e32 v38, v82
	v_and_b32_e32 v122, 0xffff0000, v46
	v_lshlrev_b32_e32 v84, 16, v47
	v_and_b32_e32 v85, 0xffff0000, v47
	v_lshlrev_b32_e32 v78, 16, v44
	v_and_b32_e32 v79, 0xffff0000, v44
	v_lshlrev_b32_e32 v80, 16, v45
	v_and_b32_e32 v81, 0xffff0000, v45
	v_lshlrev_b32_e32 v46, 16, v40
	v_and_b32_e32 v59, 0xffff0000, v40
	v_lshlrev_b32_e32 v44, 16, v41
	v_and_b32_e32 v45, 0xffff0000, v41
	v_pk_add_f32 v[36:37], v[36:37], v[36:37] op_sel_hi:[0,1]
	v_pk_fma_f32 v[40:41], v[96:97], v[96:97], v[34:35] op_sel_hi:[1,1,0]
	v_pk_add_f32 v[38:39], v[82:83], v[38:39]
	v_mul_f32_e32 v40, v122, v122
	v_mul_f32_e32 v34, v84, v84
	v_mul_f32_e32 v36, v85, v85
	v_mul_f32_e32 v60, v82, v82
	v_mov_b32_e32 v61, v39
	v_pk_add_f32 v[38:39], v[60:61], v[40:41]
	v_pk_add_f32 v[34:35], v[34:35], v[36:37]
	v_pk_mul_f32 v[36:37], v[76:77], v[76:77]
	v_pk_add_f32 v[34:35], v[38:39], v[34:35]
	v_pk_fma_f32 v[36:37], v[74:75], v[74:75], v[36:37]
	v_pk_add_f32 v[34:35], v[34:35], v[34:35] op_sel_hi:[0,1]
	v_mul_f32_e32 v47, v50, v50
	v_mul_f32_e32 v39, v51, v51
	v_mul_f32_e32 v34, v54, v54
	v_mov_b32_e32 v38, v46
	v_pk_add_f32 v[36:37], v[36:37], v[36:37] op_sel_hi:[0,1]
	v_pk_fma_f32 v[40:41], v[54:55], v[54:55], v[34:35] op_sel_hi:[1,1,0]
	v_pk_add_f32 v[38:39], v[46:47], v[38:39]
	v_mul_f32_e32 v40, v59, v59
	v_mul_f32_e32 v36, v44, v44
	v_mul_f32_e32 v34, v45, v45
	v_mul_f32_e32 v60, v46, v46
	v_mov_b32_e32 v61, v39
	v_pk_add_f32 v[38:39], v[60:61], v[40:41]
	v_pk_add_f32 v[34:35], v[36:37], v[34:35]
	v_mov_b32_e32 v60, v72
	v_pk_add_f32 v[34:35], v[38:39], v[34:35]
	v_mov_b32_e32 v61, v106
	v_add_f32_e32 v34, v34, v35
	v_mov_b32_e32 v124, v108
	v_mov_b32_e32 v125, v64
	v_mov_b32_e32 v106, v73
	v_mov_b32_e32 v64, v109
	s_waitcnt lgkmcnt(0)
	s_nop 1
	v_add_f32_dpp v34, v34, v34 quad_perm:[1,0,3,2] row_mask:0xf bank_mask:0xf
	v_mov_b32_e32 v83, v122
	s_mov_b32 s20, 0x18e00000
	s_nop 1
	v_add_f32_dpp v34, v34, v34 quad_perm:[2,3,0,1] row_mask:0xf bank_mask:0xf
	s_nop 1
	v_add_f32_dpp v34, v34, v34 row_half_mirror row_mask:0xf bank_mask:0xf
	s_nop 1
	v_add_f32_dpp v34, v34, v34 row_mirror row_mask:0xf bank_mask:0xf
	v_mov_b32_e32 v35, v34
	s_nop 1
	v_permlane16_swap_b32_e32 v34, v35
	v_add_f32_e32 v34, v34, v35
	v_mov_b32_e32 v35, v34
	s_nop 1
	v_permlane32_swap_b32_e32 v34, v35
	v_add_f32_e32 v34, v34, v35
	v_fmamk_f32 v34, v34, 0x3a000000, v236
	v_cmp_gt_f32_e32 vcc, s68, v34
	v_mul_f32_e32 v35, 0x4f800000, v34
	s_nop 0
	v_cndmask_b32_e32 v34, v34, v35, vcc
	v_sqrt_f32_e32 v35, v34
	s_nop 0
	v_add_u32_e32 v36, -1, v35
	v_fma_f32 v37, -v36, v35, v34
	v_cmp_ge_f32_e64 s[42:43], 0, v37
	v_add_u32_e32 v37, 1, v35
	s_nop 0
	v_cndmask_b32_e64 v36, v35, v36, s[42:43]
	v_fma_f32 v35, -v37, v35, v34
	v_cmp_lt_f32_e64 s[42:43], 0, v35
	s_nop 1
	v_cndmask_b32_e64 v35, v36, v37, s[42:43]
	v_mul_f32_e32 v36, 0x37800000, v35
	v_cndmask_b32_e32 v35, v35, v36, vcc
	v_cmp_class_f32_e32 vcc, v34, v234
	s_nop 1
	v_cndmask_b32_e32 v34, v35, v34, vcc
	v_div_scale_f32 v35, s[22:23], v34, v34, 1.0
	v_rcp_f32_e32 v36, v35
	s_nop 0
	v_fma_f32 v37, -v35, v36, 1.0
	v_fmac_f32_e32 v36, v37, v36
	v_div_scale_f32 v37, vcc, 1.0, v34, 1.0
	v_mul_f32_e32 v38, v37, v36
	v_fma_f32 v39, -v35, v38, v37
	v_fmac_f32_e32 v38, v39, v36
	v_fma_f32 v35, -v35, v38, v37
	v_div_fmas_f32 v35, v35, v36, v38
	v_div_fixup_f32 v58, v35, v34, 1.0
; __device__ __forceinline__ unsigned pk2(float lo, float hi) { return pg8::cvt_pk_bf16(lo, hi); }
; template <bool FINAL, bool DUMMY = false> __device__ __forceinline__ void norm_rows(const bfu* F, bfu* XB, const float* g1, float* RS, float* xout, int gw, int NGW, int lane, bfu* dummy = nullptr) {
;     ...
;         for (int k = 0; k < 8; ++k) { const f32x4 gg = ((const f32x4*)g1)[2 * lane + 128 * (k >> 1) + (k & 1)]; x[k] = x[k] + f[k] * rstd1 * gg; s2 += (x[k].x * x[k].x + x[k].y * x[k].y) + (x[k].z * x[k].z + x[k].w * x[k].w); }
;         if (FINAL) { f32x4* xo = (f32x4*)(xout + (size_t)m * DM);
; #pragma unroll
;             for (int k = 0; k < 8; ++k) __builtin_nontemporal_store(x[k], xo + 2 * lane + 128 * (k >> 1) + (k & 1));
;         } else {
;             v4u* xr = (v4u*)((DUMMY ? dummy : XB) + (size_t)m * DM) + lane;
; #pragma unroll
;             for (int j = 0; j < 4; ++j) { v4u w; w.x = pk2(x[2 * j].x, x[2 * j].y); w.y = pk2(x[2 * j].z, x[2 * j].w); w.z = pk2(x[2 * j + 1].x, x[2 * j + 1].y); w.w = pk2(x[2 * j + 1].z, x[2 * j + 1].w); xr[64 * j] = w; }
;             const float rstd2 = 1.f / sqrtf(wave_sum(s2) * (1.f / DM) + EPS);
;             if (lane == 0) (DUMMY ? (float*)dummy + (size_t)M * DM : RS)[m] = rstd2;
	v_pk_mul_f32 v[60:61], v[58:59], v[60:61] op_sel_hi:[0,1]
	v_pk_mul_f32 v[124:125], v[58:59], v[124:125] op_sel_hi:[0,1]
	v_pk_mul_f32 v[50:51], v[58:59], v[50:51] op_sel_hi:[0,1]
	v_pk_mul_f32 v[54:55], v[58:59], v[54:55] op_sel_hi:[0,1]
	v_pk_mul_f32 v[44:45], v[58:59], v[44:45] op_sel_hi:[0,1]
	v_pk_fma_f32 v[62:63], v[134:135], v[124:125], v[62:63]
	v_pk_fma_f32 v[60:61], v[132:133], v[60:61], v[114:115]
	v_pk_mul_f32 v[38:39], v[58:59], v[106:107] op_sel_hi:[0,1]
	v_pk_mul_f32 v[40:41], v[58:59], v[64:65] op_sel_hi:[0,1]
	v_pk_fma_f32 v[64:65], v[130:131], v[40:41], v[112:113]
	v_pk_fma_f32 v[72:73], v[128:129], v[38:39], v[110:111]
	v_mul_f32_e32 v35, v65, v65
	v_mul_f32_e32 v34, v73, v73
	v_fmac_f32_e32 v34, v72, v72
	v_fmac_f32_e32 v35, v64, v64
	v_add_f32_e32 v106, v34, v35
	v_mov_b32_e32 v110, v90
	v_mov_b32_e32 v111, v92
	v_mov_b32_e32 v92, v91
	v_pk_mul_f32 v[110:111], v[58:59], v[110:111] op_sel_hi:[0,1]
	v_pk_mul_f32 v[90:91], v[58:59], v[92:93] op_sel_hi:[0,1]
	v_mul_f32_e32 v108, v61, v61
	v_mul_f32_e32 v114, v63, v63
	v_fmac_f32_e32 v114, v62, v62
	v_fmac_f32_e32 v108, v60, v60
	v_pk_fma_f32 v[90:91], v[142:143], v[90:91], v[104:105]
	v_pk_fma_f32 v[92:93], v[140:141], v[110:111], v[102:103]
	v_mul_f32_e32 v39, v91, v91
	v_mul_f32_e32 v38, v93, v93
	v_fmac_f32_e32 v38, v92, v92
	v_fmac_f32_e32 v39, v90, v90
	v_add_f32_e32 v102, v38, v39
	v_pk_mul_f32 v[38:39], v[58:59], v[94:95] op_sel_hi:[0,1]
	v_pk_mul_f32 v[40:41], v[58:59], v[96:97] op_sel_hi:[0,1]
	v_pk_fma_f32 v[94:95], v[138:139], v[40:41], v[100:101]
	v_pk_fma_f32 v[96:97], v[136:137], v[38:39], v[98:99]
	v_mul_f32_e32 v35, v95, v95
	v_mul_f32_e32 v34, v97, v97
	v_fmac_f32_e32 v34, v96, v96
	v_fmac_f32_e32 v35, v94, v94
	v_add_f32_e32 v98, v34, v35
	v_pk_mul_f32 v[100:101], v[58:59], v[82:83] op_sel_hi:[0,1]
	v_pk_mul_f32 v[82:83], v[58:59], v[84:85] op_sel_hi:[0,1]
	v_pk_fma_f32 v[82:83], v[150:151], v[82:83], v[88:89]
	v_pk_fma_f32 v[84:85], v[148:149], v[100:101], v[86:87]
	v_mul_f32_e32 v39, v83, v83
	v_mul_f32_e32 v38, v85, v85
	v_fmac_f32_e32 v38, v84, v84
	v_fmac_f32_e32 v39, v82, v82
	v_add_f32_e32 v86, v38, v39
	v_mov_b32_e32 v38, v74
	v_mov_b32_e32 v39, v76
	v_mov_b32_e32 v76, v75
	v_pk_mul_f32 v[38:39], v[58:59], v[38:39] op_sel_hi:[0,1]
	v_pk_mul_f32 v[40:41], v[58:59], v[76:77] op_sel_hi:[0,1]
	v_pk_fma_f32 v[74:75], v[146:147], v[40:41], v[80:81]
	v_pk_fma_f32 v[76:77], v[144:145], v[38:39], v[78:79]
	v_mul_f32_e32 v35, v75, v75
	v_mul_f32_e32 v34, v77, v77
	v_fmac_f32_e32 v34, v76, v76
	v_fmac_f32_e32 v35, v74, v74
	v_add_f32_e32 v78, v34, v35
	v_pk_fma_f32 v[44:45], v[154:155], v[44:45], v[48:49]
	s_waitcnt vmcnt(0)
	v_pk_fma_f32 v[40:41], v[158:159], v[54:55], v[56:57]
	v_pk_fma_f32 v[38:39], v[156:157], v[50:51], v[52:53]
	v_mul_f32_e32 v50, v41, v41
	v_mul_f32_e32 v47, v39, v39
	v_fmac_f32_e32 v47, v38, v38
	v_fmac_f32_e32 v50, v40, v40
	v_add_f32_e32 v50, v47, v50
	v_mov_b32_e32 v47, v59
	v_pk_mul_f32 v[46:47], v[58:59], v[46:47] op_sel_hi:[0,1]
	v_pk_fma_f32 v[42:43], v[152:153], v[46:47], v[42:43]
	v_mul_f32_e32 v35, v45, v45
	v_mul_f32_e32 v34, v43, v43
	v_lshl_add_u64 v[46:47], s[36:37], 0, v[0:1]
	v_fmac_f32_e32 v34, v42, v42
	v_fmac_f32_e32 v35, v44, v44
	v_add_co_u32_e32 v46, vcc, s20, v46
	v_add_f32_e32 v48, v34, v35
	v_cvt_pk_bf16_f32 v34, v60, v61
	v_cvt_pk_bf16_f32 v35, v62, v63
	v_cvt_pk_bf16_f32 v36, v72, v73
	v_cvt_pk_bf16_f32 v37, v64, v65
	v_addc_co_u32_e32 v47, vcc, 0, v47, vcc
	global_store_dwordx4 v[46:47], v[34:37], off
	s_nop 1
	v_cvt_pk_bf16_f32 v34, v92, v93
	v_cvt_pk_bf16_f32 v35, v90, v91
	v_cvt_pk_bf16_f32 v36, v96, v97
	v_cvt_pk_bf16_f32 v37, v94, v95
	global_store_dwordx4 v[46:47], v[34:37], off offset:1024
	s_nop 1
	v_cvt_pk_bf16_f32 v34, v84, v85
	v_cvt_pk_bf16_f32 v35, v82, v83
	v_cvt_pk_bf16_f32 v36, v76, v77
	v_cvt_pk_bf16_f32 v37, v74, v75
	global_store_dwordx4 v[46:47], v[34:37], off offset:2048
	s_nop 1
	v_cvt_pk_bf16_f32 v34, v38, v39
	v_cvt_pk_bf16_f32 v35, v40, v41
	v_cvt_pk_bf16_f32 v36, v42, v43
	v_cvt_pk_bf16_f32 v37, v44, v45
	global_store_dwordx4 v[46:47], v[34:37], off offset:3072
	s_nop 1
	v_add_f32_e32 v34, v108, v114
	v_add_f32_e32 v34, v34, v106
	v_add_f32_e32 v34, v102, v34
	v_add_f32_e32 v34, v98, v34
	v_add_f32_e32 v34, v86, v34
	v_add_f32_e32 v34, v78, v34
	v_add_f32_e32 v34, v50, v34
	v_add_f32_e32 v34, v48, v34
	s_waitcnt lgkmcnt(0)
	s_nop 1
	v_add_f32_dpp v34, v34, v34 quad_perm:[1,0,3,2] row_mask:0xf bank_mask:0xf
	s_nop 1
	v_add_f32_dpp v34, v34, v34 quad_perm:[2,3,0,1] row_mask:0xf bank_mask:0xf
	s_nop 1
	v_add_f32_dpp v34, v34, v34 row_half_mirror row_mask:0xf bank_mask:0xf
	s_nop 1
	v_add_f32_dpp v34, v34, v34 row_mirror row_mask:0xf bank_mask:0xf
	v_mov_b32_e32 v35, v34
	s_nop 1
	v_permlane16_swap_b32_e32 v34, v35
	v_add_f32_e32 v34, v34, v35
	v_mov_b32_e32 v35, v34
	s_nop 1
	v_permlane32_swap_b32_e32 v34, v35
	v_add_f32_e32 v34, v34, v35
	s_and_saveexec_b64 s[34:35], s[40:41]
	s_cbranch_execz .LBB0_635
	s_waitcnt lgkmcnt(0)
	v_fmamk_f32 v34, v34, 0x3a000000, v236
	v_mul_f32_e32 v35, 0x4f800000, v34
	v_cmp_gt_f32_e32 vcc, s68, v34
	s_nop 1
	v_cndmask_b32_e32 v34, v34, v35, vcc
	v_sqrt_f32_e32 v35, v34
	s_nop 0
	v_add_u32_e32 v36, -1, v35
	v_fma_f32 v38, -v36, v35, v34
	v_add_u32_e32 v37, 1, v35
	v_cmp_ge_f32_e64 s[42:43], 0, v38
	s_nop 1
	v_cndmask_b32_e64 v36, v35, v36, s[42:43]
	v_fma_f32 v35, -v37, v35, v34
	v_cmp_lt_f32_e64 s[42:43], 0, v35
	s_nop 1
	v_cndmask_b32_e64 v35, v36, v37, s[42:43]
	v_mul_f32_e32 v36, 0x37800000, v35
	v_cndmask_b32_e32 v35, v35, v36, vcc
	v_cmp_class_f32_e32 vcc, v34, v234
	s_nop 1
	v_cndmask_b32_e32 v34, v35, v34, vcc
	v_div_scale_f32 v35, s[22:23], v34, v34, 1.0
	v_rcp_f32_e32 v36, v35
	s_nop 0
	v_fma_f32 v37, -v35, v36, 1.0
	v_fmac_f32_e32 v36, v37, v36
	v_div_scale_f32 v37, vcc, 1.0, v34, 1.0
	v_mul_f32_e32 v38, v37, v36
	v_fma_f32 v39, -v35, v38, v37
	v_fmac_f32_e32 v38, v39, v36
	v_fma_f32 v35, -v35, v38, v37
	v_div_fmas_f32 v35, v35, v36, v38
	v_div_fixup_f32 v34, v35, v34, 1.0
	global_store_dword v1, v34, s[44:45]
	s_branch .LBB0_635

; template <bool FINAL, bool DUMMY = false> __device__ __forceinline__ void norm_rows(const bfu* F, bfu* XB, const float* g1, float* RS, float* xout, int gw, int NGW, int lane, bfu* dummy = nullptr) {
;     ...
;         f32x4 f[8], x[8]; float s = 0.f;
; #pragma unroll
;         for (int j = 0; j < 4; ++j) {
;             f[2 * j] = (f32x4){bflo(fw[j].x), bfhi(fw[j].x), bflo(fw[j].y), bfhi(fw[j].y)}; f[2 * j + 1] = (f32x4){bflo(fw[j].z), bfhi(fw[j].z), bflo(fw[j].w), bfhi(fw[j].w)};
;             x[2 * j] = (f32x4){bflo(xw[j].x), bfhi(xw[j].x), bflo(xw[j].y), bfhi(xw[j].y)}; x[2 * j + 1] = (f32x4){bflo(xw[j].z), bfhi(xw[j].z), bflo(xw[j].w), bfhi(xw[j].w)}; }
;         const int mn = m + NGW;
;         if (mn < M) {
; #pragma unroll
;             for (int j = 0; j < 4; ++j) { fw[j] = __builtin_nontemporal_load((const v4u*)(F + (size_t)mn * DM) + lane + 64 * j); xw[j] = ((const v4u*)(XB + (size_t)mn * DM) + lane)[64 * j]; }
;         }
; #pragma unroll
;         for (int k = 0; k < 8; ++k) s += (f[k].x * f[k].x + f[k].y * f[k].y) + (f[k].z * f[k].z + f[k].w * f[k].w);
;         const float rstd1 = 1.f / sqrtf(wave_sum(s) * (1.f / DM) + EPS);
.LBB0_851:
	v_lshlrev_b32_e32 v73, 16, v64
	v_and_b32_e32 v107, 0xffff0000, v64
	v_and_b32_e32 v106, 0xffff0000, v62
	v_lshlrev_b32_e32 v109, 16, v65
	v_and_b32_e32 v65, 0xffff0000, v65
	v_and_b32_e32 v64, 0xffff0000, v63
	v_lshlrev_b32_e32 v72, 16, v62
	v_lshlrev_b32_e32 v108, 16, v63
	v_lshlrev_b32_e32 v94, 16, v56
	v_and_b32_e32 v95, 0xffff0000, v56
	v_lshlrev_b32_e32 v96, 16, v57
	v_and_b32_e32 v97, 0xffff0000, v57
	v_lshlrev_b32_e32 v98, 16, v52
	v_and_b32_e32 v99, 0xffff0000, v52
	v_lshlrev_b32_e32 v100, 16, v53
	v_and_b32_e32 v101, 0xffff0000, v53
	v_lshlrev_b32_e32 v75, 16, v49
	v_lshlrev_b32_e32 v74, 16, v48
	v_and_b32_e32 v77, 0xffff0000, v49
	v_and_b32_e32 v76, 0xffff0000, v48
	v_lshlrev_b32_e32 v86, 16, v42
	v_and_b32_e32 v87, 0xffff0000, v42
	v_lshlrev_b32_e32 v88, 16, v43
	v_and_b32_e32 v89, 0xffff0000, v43
	v_lshlrev_b32_e32 v52, 16, v34
	v_and_b32_e32 v53, 0xffff0000, v34
	v_lshlrev_b32_e32 v56, 16, v35
	v_and_b32_e32 v57, 0xffff0000, v35
	v_lshlrev_b32_e32 v42, 16, v36
	v_and_b32_e32 v43, 0xffff0000, v36
	v_lshlrev_b32_e32 v48, 16, v37
	v_and_b32_e32 v49, 0xffff0000, v37
	v_pk_mul_f32 v[34:35], v[106:107], v[106:107]
	v_pk_mul_f32 v[36:37], v[64:65], v[64:65]
	v_pk_fma_f32 v[34:35], v[72:73], v[72:73], v[34:35]
	v_pk_fma_f32 v[36:37], v[108:109], v[108:109], v[36:37]
	v_and_b32_e32 v93, 0xffff0000, v55
	v_and_b32_e32 v92, 0xffff0000, v54
	v_pk_add_f32 v[34:35], v[34:35], v[36:37]
	v_lshlrev_b32_e32 v91, 16, v55
	v_lshlrev_b32_e32 v90, 16, v54
	v_lshlrev_b32_e32 v82, 16, v46
	v_pk_add_f32 v[34:35], v[34:35], v[34:35] op_sel_hi:[0,1]
	v_pk_mul_f32 v[36:37], v[92:93], v[92:93]
	v_lshlrev_b32_e32 v102, 16, v50
	v_and_b32_e32 v103, 0xffff0000, v50
	v_lshlrev_b32_e32 v104, 16, v51
	v_and_b32_e32 v105, 0xffff0000, v51
	v_lshlrev_b32_e32 v50, 16, v38
	v_and_b32_e32 v51, 0xffff0000, v38
	v_lshlrev_b32_e32 v54, 16, v39
	v_and_b32_e32 v55, 0xffff0000, v39
	v_pk_fma_f32 v[36:37], v[90:91], v[90:91], v[36:37]
	v_mul_f32_e32 v83, v94, v94
	v_mul_f32_e32 v39, v95, v95
	v_mul_f32_e32 v34, v96, v96
	v_mov_b32_e32 v38, v82
	v_lshlrev_b32_e32 v62, 16, v59
	v_and_b32_e32 v63, 0xffff0000, v59
	v_and_b32_e32 v123, 0xffff0000, v46
	v_lshlrev_b32_e32 v84, 16, v47
	v_and_b32_e32 v85, 0xffff0000, v47
	v_lshlrev_b32_e32 v78, 16, v44
	v_and_b32_e32 v79, 0xffff0000, v44
	v_lshlrev_b32_e32 v80, 16, v45
	v_and_b32_e32 v81, 0xffff0000, v45
	v_lshlrev_b32_e32 v46, 16, v40
	v_and_b32_e32 v59, 0xffff0000, v40
	v_lshlrev_b32_e32 v44, 16, v41
	v_and_b32_e32 v45, 0xffff0000, v41
	v_pk_add_f32 v[36:37], v[36:37], v[36:37] op_sel_hi:[0,1]
	v_pk_fma_f32 v[40:41], v[96:97], v[96:97], v[34:35] op_sel_hi:[1,1,0]
	v_pk_add_f32 v[38:39], v[82:83], v[38:39]
	v_lshlrev_b32_e32 v110, 16, v60
	v_and_b32_e32 v111, 0xffff0000, v60
	v_lshlrev_b32_e32 v112, 16, v61
	v_and_b32_e32 v113, 0xffff0000, v61
	v_mul_f32_e32 v40, v123, v123
	v_mul_f32_e32 v34, v84, v84
	v_mul_f32_e32 v36, v85, v85
	v_mul_f32_e32 v60, v82, v82
	v_mov_b32_e32 v61, v39
	v_pk_add_f32 v[38:39], v[60:61], v[40:41]
	v_pk_add_f32 v[34:35], v[34:35], v[36:37]
	v_pk_mul_f32 v[36:37], v[76:77], v[76:77]
	v_pk_add_f32 v[34:35], v[38:39], v[34:35]
	v_pk_fma_f32 v[36:37], v[74:75], v[74:75], v[36:37]
	v_pk_add_f32 v[34:35], v[34:35], v[34:35] op_sel_hi:[0,1]
	v_mul_f32_e32 v47, v50, v50
	v_mul_f32_e32 v39, v51, v51
	v_mul_f32_e32 v34, v54, v54
	v_mov_b32_e32 v38, v46
	v_pk_add_f32 v[36:37], v[36:37], v[36:37] op_sel_hi:[0,1]
	v_pk_fma_f32 v[40:41], v[54:55], v[54:55], v[34:35] op_sel_hi:[1,1,0]
	v_pk_add_f32 v[38:39], v[46:47], v[38:39]
	v_mul_f32_e32 v40, v59, v59
	v_mul_f32_e32 v36, v44, v44
	v_mul_f32_e32 v34, v45, v45
	v_mul_f32_e32 v60, v46, v46
	v_mov_b32_e32 v61, v39
	v_pk_add_f32 v[38:39], v[60:61], v[40:41]
	v_pk_add_f32 v[34:35], v[36:37], v[34:35]
	v_lshlrev_b32_e32 v114, 16, v58
	v_pk_add_f32 v[34:35], v[38:39], v[34:35]
	v_and_b32_e32 v115, 0xffff0000, v58
	v_add_f32_e32 v34, v34, v35
	v_mov_b32_e32 v60, v72
	v_mov_b32_e32 v61, v106
	v_mov_b32_e32 v124, v108
	v_mov_b32_e32 v125, v64
	s_waitcnt lgkmcnt(0)
	s_nop 1
	v_add_f32_dpp v34, v34, v34 quad_perm:[1,0,3,2] row_mask:0xf bank_mask:0xf
	v_mov_b32_e32 v106, v73
	v_mov_b32_e32 v64, v109
	v_mov_b32_e32 v83, v123
	s_nop 1
	v_add_f32_dpp v34, v34, v34 quad_perm:[2,3,0,1] row_mask:0xf bank_mask:0xf
	s_nop 1
	v_add_f32_dpp v34, v34, v34 row_half_mirror row_mask:0xf bank_mask:0xf
	s_nop 1
	v_add_f32_dpp v34, v34, v34 row_mirror row_mask:0xf bank_mask:0xf
	v_mov_b32_e32 v35, v34
	s_nop 1
	v_permlane16_swap_b32_e32 v34, v35
	v_add_f32_e32 v34, v34, v35
	v_mov_b32_e32 v35, v34
	s_nop 1
	v_permlane32_swap_b32_e32 v34, v35
	v_add_f32_e32 v34, v34, v35
	v_fmamk_f32 v34, v34, 0x3a000000, v236
	v_cmp_gt_f32_e32 vcc, s68, v34
	v_mul_f32_e32 v35, 0x4f800000, v34
	s_nop 0
	v_cndmask_b32_e32 v34, v34, v35, vcc
	v_sqrt_f32_e32 v35, v34
	s_nop 0
	v_add_u32_e32 v36, -1, v35
	v_fma_f32 v37, -v36, v35, v34
	v_cmp_ge_f32_e64 s[40:41], 0, v37
	v_add_u32_e32 v37, 1, v35
	s_nop 0
	v_cndmask_b32_e64 v36, v35, v36, s[40:41]
	v_fma_f32 v35, -v37, v35, v34
	v_cmp_lt_f32_e64 s[40:41], 0, v35
	s_nop 1
	v_cndmask_b32_e64 v35, v36, v37, s[40:41]
	v_mul_f32_e32 v36, 0x37800000, v35
	v_cndmask_b32_e32 v35, v35, v36, vcc
	v_cmp_class_f32_e32 vcc, v34, v234
	s_nop 1
	v_cndmask_b32_e32 v34, v35, v34, vcc
	v_div_scale_f32 v35, s[22:23], v34, v34, 1.0
	v_rcp_f32_e32 v36, v35
	s_mov_b32 s22, 0x18e00000
	v_fma_f32 v37, -v35, v36, 1.0
	v_fmac_f32_e32 v36, v37, v36
	v_div_scale_f32 v37, vcc, 1.0, v34, 1.0
	v_mul_f32_e32 v38, v37, v36
	v_fma_f32 v39, -v35, v38, v37
	v_fmac_f32_e32 v38, v39, v36
	v_fma_f32 v35, -v35, v38, v37
	v_div_fmas_f32 v35, v35, v36, v38
	v_div_fixup_f32 v58, v35, v34, 1.0
; __device__ __forceinline__ unsigned pk2(float lo, float hi) { return pg8::cvt_pk_bf16(lo, hi); }
; template <bool FINAL, bool DUMMY = false> __device__ __forceinline__ void norm_rows(const bfu* F, bfu* XB, const float* g1, float* RS, float* xout, int gw, int NGW, int lane, bfu* dummy = nullptr) {
;     ...
;         for (int k = 0; k < 8; ++k) { const f32x4 gg = ((const f32x4*)g1)[2 * lane + 128 * (k >> 1) + (k & 1)]; x[k] = x[k] + f[k] * rstd1 * gg; s2 += (x[k].x * x[k].x + x[k].y * x[k].y) + (x[k].z * x[k].z + x[k].w * x[k].w); }
;         if (FINAL) { f32x4* xo = (f32x4*)(xout + (size_t)m * DM);
; #pragma unroll
;             for (int k = 0; k < 8; ++k) __builtin_nontemporal_store(x[k], xo + 2 * lane + 128 * (k >> 1) + (k & 1));
;         } else {
;             v4u* xr = (v4u*)((DUMMY ? dummy : XB) + (size_t)m * DM) + lane;
; #pragma unroll
;             for (int j = 0; j < 4; ++j) { v4u w; w.x = pk2(x[2 * j].x, x[2 * j].y); w.y = pk2(x[2 * j].z, x[2 * j].w); w.z = pk2(x[2 * j + 1].x, x[2 * j + 1].y); w.w = pk2(x[2 * j + 1].z, x[2 * j + 1].w); xr[64 * j] = w; }
;             const float rstd2 = 1.f / sqrtf(wave_sum(s2) * (1.f / DM) + EPS);
;             if (lane == 0) (DUMMY ? (float*)dummy + (size_t)M * DM : RS)[m] = rstd2;
	v_pk_mul_f32 v[60:61], v[58:59], v[60:61] op_sel_hi:[0,1]
	v_pk_mul_f32 v[124:125], v[58:59], v[124:125] op_sel_hi:[0,1]
	v_pk_mul_f32 v[50:51], v[58:59], v[50:51] op_sel_hi:[0,1]
	v_pk_mul_f32 v[54:55], v[58:59], v[54:55] op_sel_hi:[0,1]
	v_pk_mul_f32 v[44:45], v[58:59], v[44:45] op_sel_hi:[0,1]
	v_pk_fma_f32 v[62:63], v[134:135], v[124:125], v[62:63]
	v_pk_fma_f32 v[60:61], v[132:133], v[60:61], v[114:115]
	v_pk_mul_f32 v[38:39], v[58:59], v[106:107] op_sel_hi:[0,1]
	v_pk_mul_f32 v[40:41], v[58:59], v[64:65] op_sel_hi:[0,1]
	v_pk_fma_f32 v[64:65], v[130:131], v[40:41], v[112:113]
	v_pk_fma_f32 v[72:73], v[128:129], v[38:39], v[110:111]
	v_mul_f32_e32 v35, v65, v65
	v_mul_f32_e32 v34, v73, v73
	v_fmac_f32_e32 v34, v72, v72
	v_fmac_f32_e32 v35, v64, v64
	v_add_f32_e32 v106, v34, v35
	v_mov_b32_e32 v110, v90
	v_mov_b32_e32 v111, v92
	v_mov_b32_e32 v92, v91
	v_pk_mul_f32 v[110:111], v[58:59], v[110:111] op_sel_hi:[0,1]
	v_pk_mul_f32 v[90:91], v[58:59], v[92:93] op_sel_hi:[0,1]
	v_mul_f32_e32 v108, v61, v61
	v_mul_f32_e32 v114, v63, v63
	v_fmac_f32_e32 v114, v62, v62
	v_fmac_f32_e32 v108, v60, v60
	v_pk_fma_f32 v[90:91], v[142:143], v[90:91], v[104:105]
	v_pk_fma_f32 v[92:93], v[140:141], v[110:111], v[102:103]
	v_mul_f32_e32 v39, v91, v91
	v_mul_f32_e32 v38, v93, v93
	v_fmac_f32_e32 v38, v92, v92
	v_fmac_f32_e32 v39, v90, v90
	v_add_f32_e32 v102, v38, v39
	v_pk_mul_f32 v[38:39], v[58:59], v[94:95] op_sel_hi:[0,1]
	v_pk_mul_f32 v[40:41], v[58:59], v[96:97] op_sel_hi:[0,1]
	v_pk_fma_f32 v[94:95], v[138:139], v[40:41], v[100:101]
	v_pk_fma_f32 v[96:97], v[136:137], v[38:39], v[98:99]
	v_mul_f32_e32 v35, v95, v95
	v_mul_f32_e32 v34, v97, v97
	v_fmac_f32_e32 v34, v96, v96
	v_fmac_f32_e32 v35, v94, v94
	v_add_f32_e32 v98, v34, v35
	v_pk_mul_f32 v[100:101], v[58:59], v[82:83] op_sel_hi:[0,1]
	v_pk_mul_f32 v[82:83], v[58:59], v[84:85] op_sel_hi:[0,1]
	v_pk_fma_f32 v[82:83], v[150:151], v[82:83], v[88:89]
	v_pk_fma_f32 v[84:85], v[148:149], v[100:101], v[86:87]
	v_mul_f32_e32 v39, v83, v83
	v_mul_f32_e32 v38, v85, v85
	v_fmac_f32_e32 v38, v84, v84
	v_fmac_f32_e32 v39, v82, v82
	v_add_f32_e32 v86, v38, v39
	v_mov_b32_e32 v38, v74
	v_mov_b32_e32 v39, v76
	v_mov_b32_e32 v76, v75
	v_pk_mul_f32 v[38:39], v[58:59], v[38:39] op_sel_hi:[0,1]
	v_pk_mul_f32 v[40:41], v[58:59], v[76:77] op_sel_hi:[0,1]
	v_pk_fma_f32 v[74:75], v[146:147], v[40:41], v[80:81]
	v_pk_fma_f32 v[76:77], v[144:145], v[38:39], v[78:79]
	v_mul_f32_e32 v35, v75, v75
	v_mul_f32_e32 v34, v77, v77
	v_fmac_f32_e32 v34, v76, v76
	v_fmac_f32_e32 v35, v74, v74
	v_add_f32_e32 v78, v34, v35
	v_pk_fma_f32 v[44:45], v[154:155], v[44:45], v[48:49]
	s_waitcnt vmcnt(0)
	v_pk_fma_f32 v[40:41], v[158:159], v[54:55], v[56:57]
	v_pk_fma_f32 v[38:39], v[156:157], v[50:51], v[52:53]
	v_mul_f32_e32 v50, v41, v41
	v_mul_f32_e32 v47, v39, v39
	v_fmac_f32_e32 v47, v38, v38
	v_fmac_f32_e32 v50, v40, v40
	v_add_f32_e32 v50, v47, v50
	v_mov_b32_e32 v47, v59
	v_pk_mul_f32 v[46:47], v[58:59], v[46:47] op_sel_hi:[0,1]
	v_pk_fma_f32 v[42:43], v[152:153], v[46:47], v[42:43]
	v_mul_f32_e32 v35, v45, v45
	v_mul_f32_e32 v34, v43, v43
	v_lshl_add_u64 v[46:47], s[36:37], 0, v[0:1]
	v_fmac_f32_e32 v34, v42, v42
	v_fmac_f32_e32 v35, v44, v44
	v_add_co_u32_e32 v46, vcc, s22, v46
	v_add_f32_e32 v48, v34, v35
	v_cvt_pk_bf16_f32 v34, v60, v61
	v_cvt_pk_bf16_f32 v35, v62, v63
	v_cvt_pk_bf16_f32 v36, v72, v73
	v_cvt_pk_bf16_f32 v37, v64, v65
	v_addc_co_u32_e32 v47, vcc, 0, v47, vcc
	global_store_dwordx4 v[46:47], v[34:37], off
	s_nop 1
	v_cvt_pk_bf16_f32 v34, v92, v93
	v_cvt_pk_bf16_f32 v35, v90, v91
	v_cvt_pk_bf16_f32 v36, v96, v97
	v_cvt_pk_bf16_f32 v37, v94, v95
	global_store_dwordx4 v[46:47], v[34:37], off offset:1024
	s_nop 1
	v_cvt_pk_bf16_f32 v34, v84, v85
	v_cvt_pk_bf16_f32 v35, v82, v83
	v_cvt_pk_bf16_f32 v36, v76, v77
	v_cvt_pk_bf16_f32 v37, v74, v75
	global_store_dwordx4 v[46:47], v[34:37], off offset:2048
	s_nop 1
	v_cvt_pk_bf16_f32 v34, v38, v39
	v_cvt_pk_bf16_f32 v35, v40, v41
	v_cvt_pk_bf16_f32 v36, v42, v43
	v_cvt_pk_bf16_f32 v37, v44, v45
	global_store_dwordx4 v[46:47], v[34:37], off offset:3072
	s_nop 1
	v_add_f32_e32 v34, v108, v114
	v_add_f32_e32 v34, v34, v106
	v_add_f32_e32 v34, v102, v34
	v_add_f32_e32 v34, v98, v34
	v_add_f32_e32 v34, v86, v34
	v_add_f32_e32 v34, v78, v34
	v_add_f32_e32 v34, v50, v34
	v_add_f32_e32 v34, v48, v34
	s_waitcnt lgkmcnt(0)
	s_nop 1
	v_add_f32_dpp v34, v34, v34 quad_perm:[1,0,3,2] row_mask:0xf bank_mask:0xf
	s_nop 1
	v_add_f32_dpp v34, v34, v34 quad_perm:[2,3,0,1] row_mask:0xf bank_mask:0xf
	s_nop 1
	v_add_f32_dpp v34, v34, v34 row_half_mirror row_mask:0xf bank_mask:0xf
	s_nop 1
	v_add_f32_dpp v34, v34, v34 row_mirror row_mask:0xf bank_mask:0xf
	v_mov_b32_e32 v35, v34
	s_nop 1
	v_permlane16_swap_b32_e32 v34, v35
	v_add_f32_e32 v34, v34, v35
	v_mov_b32_e32 v35, v34
	s_nop 1
	v_permlane32_swap_b32_e32 v34, v35
	v_add_f32_e32 v34, v34, v35
	s_and_saveexec_b64 s[34:35], s[38:39]
	s_cbranch_execz .LBB0_848
	s_waitcnt lgkmcnt(0)
	v_fmamk_f32 v34, v34, 0x3a000000, v236
	v_mul_f32_e32 v35, 0x4f800000, v34
	v_cmp_gt_f32_e32 vcc, s68, v34
	s_nop 1
	v_cndmask_b32_e32 v34, v34, v35, vcc
	v_sqrt_f32_e32 v35, v34
	s_nop 0
	v_add_u32_e32 v36, -1, v35
	v_fma_f32 v38, -v36, v35, v34
	v_add_u32_e32 v37, 1, v35
	v_cmp_ge_f32_e64 s[40:41], 0, v38
	s_nop 1
	v_cndmask_b32_e64 v36, v35, v36, s[40:41]
	v_fma_f32 v35, -v37, v35, v34
	v_cmp_lt_f32_e64 s[40:41], 0, v35
	s_nop 1
	v_cndmask_b32_e64 v35, v36, v37, s[40:41]
	v_mul_f32_e32 v36, 0x37800000, v35
	v_cndmask_b32_e32 v35, v35, v36, vcc
	v_cmp_class_f32_e32 vcc, v34, v234
	s_nop 1
	v_cndmask_b32_e32 v34, v35, v34, vcc
	v_div_scale_f32 v35, s[22:23], v34, v34, 1.0
	v_rcp_f32_e32 v36, v35
	s_nop 0
	v_fma_f32 v37, -v35, v36, 1.0
	v_fmac_f32_e32 v36, v37, v36
	v_div_scale_f32 v37, vcc, 1.0, v34, 1.0
	v_mul_f32_e32 v38, v37, v36
	v_fma_f32 v39, -v35, v38, v37
	v_fmac_f32_e32 v38, v39, v36
	v_fma_f32 v35, -v35, v38, v37
	v_div_fmas_f32 v35, v35, v36, v38
	v_div_fixup_f32 v34, v35, v34, 1.0
	global_store_dword v1, v34, s[42:43]
	s_branch .LBB0_848

; template <bool FINAL, bool DUMMY = false> __device__ __forceinline__ void norm_rows(const bfu* F, bfu* XB, const float* g1, float* RS, float* xout, int gw, int NGW, int lane, bfu* dummy = nullptr) {
;     ...
;         f32x4 f[8], x[8]; float s = 0.f;
; #pragma unroll
;         for (int j = 0; j < 4; ++j) {
;             f[2 * j] = (f32x4){bflo(fw[j].x), bfhi(fw[j].x), bflo(fw[j].y), bfhi(fw[j].y)}; f[2 * j + 1] = (f32x4){bflo(fw[j].z), bfhi(fw[j].z), bflo(fw[j].w), bfhi(fw[j].w)};
;             x[2 * j] = (f32x4){bflo(xw[j].x), bfhi(xw[j].x), bflo(xw[j].y), bfhi(xw[j].y)}; x[2 * j + 1] = (f32x4){bflo(xw[j].z), bfhi(xw[j].z), bflo(xw[j].w), bfhi(xw[j].w)}; }
;         const int mn = m + NGW;
;         if (mn < M) {
; #pragma unroll
;             for (int j = 0; j < 4; ++j) { fw[j] = __builtin_nontemporal_load((const v4u*)(F + (size_t)mn * DM) + lane + 64 * j); xw[j] = ((const v4u*)(XB + (size_t)mn * DM) + lane)[64 * j]; }
;         }
; #pragma unroll
;         for (int k = 0; k < 8; ++k) s += (f[k].x * f[k].x + f[k].y * f[k].y) + (f[k].z * f[k].z + f[k].w * f[k].w);
;         const float rstd1 = 1.f / sqrtf(wave_sum(s) * (1.f / DM) + EPS);
.LBB0_857:
	v_and_b32_e32 v111, 0xffff0000, v64
	v_and_b32_e32 v110, 0xffff0000, v62
	v_and_b32_e32 v115, 0xffff0000, v65
	v_and_b32_e32 v114, 0xffff0000, v63
	v_lshlrev_b32_e32 v109, 16, v64
	v_lshlrev_b32_e32 v108, 16, v62
	v_lshlrev_b32_e32 v113, 16, v65
	v_lshlrev_b32_e32 v112, 16, v63
	v_lshlrev_b32_e32 v84, 16, v34
	v_and_b32_e32 v85, 0xffff0000, v34
	v_lshlrev_b32_e32 v88, 16, v35
	v_and_b32_e32 v89, 0xffff0000, v35
	v_lshlrev_b32_e32 v74, 16, v36
	v_and_b32_e32 v75, 0xffff0000, v36
	v_lshlrev_b32_e32 v80, 16, v37
	v_and_b32_e32 v81, 0xffff0000, v37
	v_pk_mul_f32 v[34:35], v[110:111], v[110:111]
	v_pk_mul_f32 v[36:37], v[114:115], v[114:115]
	v_pk_fma_f32 v[34:35], v[108:109], v[108:109], v[34:35]
	v_pk_fma_f32 v[36:37], v[112:113], v[112:113], v[36:37]
	v_and_b32_e32 v95, 0xffff0000, v55
	v_and_b32_e32 v94, 0xffff0000, v54
	v_pk_add_f32 v[34:35], v[34:35], v[36:37]
	v_lshlrev_b32_e32 v93, 16, v55
	v_lshlrev_b32_e32 v92, 16, v54
	v_lshlrev_b32_e32 v96, 16, v56
	v_and_b32_e32 v97, 0xffff0000, v56
	v_lshlrev_b32_e32 v98, 16, v57
	v_lshlrev_b32_e32 v102, 16, v50
	v_and_b32_e32 v103, 0xffff0000, v50
	v_lshlrev_b32_e32 v50, 16, v46
	v_pk_add_f32 v[34:35], v[34:35], v[34:35] op_sel_hi:[0,1]
	v_pk_mul_f32 v[36:37], v[94:95], v[94:95]
	v_and_b32_e32 v99, 0xffff0000, v57
	v_lshlrev_b32_e32 v106, 16, v51
	v_and_b32_e32 v107, 0xffff0000, v51
	v_lshlrev_b32_e32 v82, 16, v38
	v_and_b32_e32 v83, 0xffff0000, v38
	v_lshlrev_b32_e32 v86, 16, v39
	v_and_b32_e32 v87, 0xffff0000, v39
	v_pk_fma_f32 v[36:37], v[92:93], v[92:93], v[36:37]
	v_mul_f32_e32 v51, v96, v96
	v_mul_f32_e32 v39, v97, v97
	v_mul_f32_e32 v34, v98, v98
	v_mov_b32_e32 v38, v50
	v_lshlrev_b32_e32 v100, 16, v52
	v_and_b32_e32 v101, 0xffff0000, v52
	v_lshlrev_b32_e32 v104, 16, v53
	v_and_b32_e32 v105, 0xffff0000, v53
	v_and_b32_e32 v130, 0xffff0000, v46
	v_lshlrev_b32_e32 v52, 16, v47
	v_and_b32_e32 v53, 0xffff0000, v47
	v_lshlrev_b32_e32 v78, 16, v40
	v_and_b32_e32 v129, 0xffff0000, v40
	v_lshlrev_b32_e32 v76, 16, v41
	v_and_b32_e32 v77, 0xffff0000, v41
	v_pk_add_f32 v[36:37], v[36:37], v[36:37] op_sel_hi:[0,1]
	v_pk_fma_f32 v[40:41], v[98:99], v[98:99], v[34:35] op_sel_hi:[1,1,0]
	v_pk_add_f32 v[38:39], v[50:51], v[38:39]
	v_lshlrev_b32_e32 v62, 16, v42
	v_and_b32_e32 v63, 0xffff0000, v42
	v_lshlrev_b32_e32 v64, 16, v43
	v_and_b32_e32 v65, 0xffff0000, v43
	v_mul_f32_e32 v40, v130, v130
	v_mul_f32_e32 v34, v52, v52
	v_mul_f32_e32 v36, v53, v53
	v_mul_f32_e32 v42, v50, v50
	v_mov_b32_e32 v43, v39
	v_pk_add_f32 v[38:39], v[42:43], v[40:41]
	v_pk_add_f32 v[34:35], v[34:35], v[36:37]
	v_and_b32_e32 v57, 0xffff0000, v49
	v_and_b32_e32 v56, 0xffff0000, v48
	v_pk_add_f32 v[34:35], v[38:39], v[34:35]
	v_lshlrev_b32_e32 v55, 16, v49
	v_lshlrev_b32_e32 v54, 16, v48
	v_pk_add_f32 v[34:35], v[34:35], v[34:35] op_sel_hi:[0,1]
	v_pk_mul_f32 v[36:37], v[56:57], v[56:57]
	v_mul_f32_e32 v79, v82, v82
	v_pk_fma_f32 v[36:37], v[54:55], v[54:55], v[36:37]
	v_mul_f32_e32 v39, v83, v83
	v_mul_f32_e32 v34, v86, v86
	v_mov_b32_e32 v38, v78
	v_pk_add_f32 v[36:37], v[36:37], v[36:37] op_sel_hi:[0,1]
	v_pk_fma_f32 v[40:41], v[86:87], v[86:87], v[34:35] op_sel_hi:[1,1,0]
	v_pk_add_f32 v[38:39], v[78:79], v[38:39]
	v_mul_f32_e32 v40, v129, v129
	v_mul_f32_e32 v36, v76, v76
	v_mul_f32_e32 v34, v77, v77
	v_mul_f32_e32 v42, v78, v78
	v_mov_b32_e32 v43, v39
	v_pk_add_f32 v[38:39], v[42:43], v[40:41]
	v_pk_add_f32 v[34:35], v[36:37], v[34:35]
	v_lshlrev_b32_e32 v118, 16, v58
	v_pk_add_f32 v[34:35], v[38:39], v[34:35]
	v_and_b32_e32 v119, 0xffff0000, v58
	v_add_f32_e32 v34, v34, v35
	v_lshlrev_b32_e32 v122, 16, v59
	v_and_b32_e32 v123, 0xffff0000, v59
	v_lshlrev_b32_e32 v116, 16, v60
	v_and_b32_e32 v117, 0xffff0000, v60
	s_waitcnt lgkmcnt(0)
; template <bool FINAL, bool DUMMY = false> __device__ __forceinline__ void norm_rows(const bfu* F, bfu* XB, const float* g1, float* RS, float* xout, int gw, int NGW, int lane, bfu* dummy = nullptr) {
;     ...
;         const int mn = m + NGW;
;         if (mn < M) {
; #pragma unroll
;             for (int j = 0; j < 4; ++j) { fw[j] = __builtin_nontemporal_load((const v4u*)(F + (size_t)mn * DM) + lane + 64 * j); xw[j] = ((const v4u*)(XB + (size_t)mn * DM) + lane)[64 * j]; }
;         }
; #pragma unroll
;         for (int k = 0; k < 8; ++k) s += (f[k].x * f[k].x + f[k].y * f[k].y) + (f[k].z * f[k].z + f[k].w * f[k].w);
;         const float rstd1 = 1.f / sqrtf(wave_sum(s) * (1.f / DM) + EPS);
;         float s2 = 0.f;
; #pragma unroll
;         for (int k = 0; k < 8; ++k) { const f32x4 gg = ((const f32x4*)g1)[2 * lane + 128 * (k >> 1) + (k & 1)]; x[k] = x[k] + f[k] * rstd1 * gg; s2 += (x[k].x * x[k].x + x[k].y * x[k].y) + (x[k].z * x[k].z + x[k].w * x[k].w); }
;         if (FINAL) { f32x4* xo = (f32x4*)(xout + (size_t)m * DM);
; #pragma unroll
;             for (int k = 0; k < 8; ++k) __builtin_nontemporal_store(x[k], xo + 2 * lane + 128 * (k >> 1) + (k & 1));
	s_nop 1
	v_add_f32_dpp v34, v34, v34 quad_perm:[1,0,3,2] row_mask:0xf bank_mask:0xf
	v_lshlrev_b32_e32 v120, 16, v61
	v_and_b32_e32 v121, 0xffff0000, v61
	v_lshlrev_b32_e32 v58, 16, v44
	v_and_b32_e32 v59, 0xffff0000, v44
	s_nop 1
	v_add_f32_dpp v34, v34, v34 quad_perm:[2,3,0,1] row_mask:0xf bank_mask:0xf
	v_lshlrev_b32_e32 v60, 16, v45
	v_and_b32_e32 v61, 0xffff0000, v45
	v_mov_b32_e32 v42, v108
	v_mov_b32_e32 v43, v110
	s_nop 1
	v_add_f32_dpp v34, v34, v34 row_half_mirror row_mask:0xf bank_mask:0xf
	v_mov_b32_e32 v44, v112
	v_mov_b32_e32 v45, v114
	v_mov_b32_e32 v110, v109
	v_mov_b32_e32 v114, v113
	s_nop 1
	v_add_f32_dpp v34, v34, v34 row_mirror row_mask:0xf bank_mask:0xf
	v_mov_b32_e32 v109, v94
	v_mov_b32_e32 v94, v93
	v_mov_b32_e32 v108, v92
	v_mov_b32_e32 v51, v130
	v_mov_b32_e32 v35, v34
	s_nop 1
	v_permlane16_swap_b32_e32 v34, v35
	v_add_f32_e32 v34, v34, v35
	v_mov_b32_e32 v79, v129
	s_add_u32 s36, s36, s24
	s_addc_u32 s37, s37, s25
	s_add_u32 s40, s40, s24
	v_mov_b32_e32 v35, v34
	s_nop 1
	v_permlane32_swap_b32_e32 v34, v35
	v_add_f32_e32 v34, v34, v35
	v_fmamk_f32 v34, v34, 0x3a000000, v236
	v_cmp_gt_f32_e32 vcc, s68, v34
	v_mul_f32_e32 v35, 0x4f800000, v34
	s_addc_u32 s41, s41, s25
	v_cndmask_b32_e32 v34, v34, v35, vcc
	v_sqrt_f32_e32 v35, v34
	s_nop 0
	v_add_u32_e32 v36, -1, v35
	v_fma_f32 v37, -v36, v35, v34
	v_cmp_ge_f32_e64 s[38:39], 0, v37
	v_add_u32_e32 v37, 1, v35
	s_nop 0
	v_cndmask_b32_e64 v36, v35, v36, s[38:39]
	v_fma_f32 v35, -v37, v35, v34
	v_cmp_lt_f32_e64 s[38:39], 0, v35
	s_nop 1
	v_cndmask_b32_e64 v35, v36, v37, s[38:39]
	v_mul_f32_e32 v36, 0x37800000, v35
	v_cndmask_b32_e32 v35, v35, v36, vcc
	v_cmp_class_f32_e32 vcc, v34, v234
	s_nop 1
	v_cndmask_b32_e32 v34, v35, v34, vcc
	v_div_scale_f32 v35, s[22:23], v34, v34, 1.0
	v_rcp_f32_e32 v36, v35
	v_readlane_b32 s22, v255, 45
	v_readlane_b32 s23, v255, 46
	v_fma_f32 v37, -v35, v36, 1.0
	v_fmac_f32_e32 v36, v37, v36
	v_div_scale_f32 v37, vcc, 1.0, v34, 1.0
	v_mul_f32_e32 v38, v37, v36
	v_fma_f32 v39, -v35, v38, v37
	v_fmac_f32_e32 v38, v39, v36
	v_fma_f32 v35, -v35, v38, v37
	v_div_fmas_f32 v35, v35, v36, v38
	v_div_fixup_f32 v90, v35, v34, 1.0
	global_load_dwordx4 v[38:41], v[66:67], off offset:16
	global_load_dwordx4 v[34:37], v[66:67], off
	v_pk_mul_f32 v[42:43], v[90:91], v[42:43] op_sel_hi:[0,1]
	v_pk_mul_f32 v[44:45], v[90:91], v[44:45] op_sel_hi:[0,1]
	v_pk_mul_f32 v[92:93], v[90:91], v[94:95] op_sel_hi:[0,1]
	v_pk_mul_f32 v[94:95], v[90:91], v[98:99] op_sel_hi:[0,1]
	v_pk_mul_f32 v[50:51], v[90:91], v[50:51] op_sel_hi:[0,1]
	v_pk_mul_f32 v[52:53], v[90:91], v[52:53] op_sel_hi:[0,1]
	v_pk_mul_f32 v[108:109], v[90:91], v[108:109] op_sel_hi:[0,1]
	v_pk_mul_f32 v[82:83], v[90:91], v[82:83] op_sel_hi:[0,1]
	v_pk_mul_f32 v[86:87], v[90:91], v[86:87] op_sel_hi:[0,1]
	v_pk_mul_f32 v[78:79], v[90:91], v[78:79] op_sel_hi:[0,1]
	v_pk_mul_f32 v[76:77], v[90:91], v[76:77] op_sel_hi:[0,1]
	s_and_b64 vcc, exec, s[42:43]
	s_waitcnt vmcnt(0)
	v_pk_fma_f32 v[36:37], v[36:37], v[44:45], v[122:123]
	v_pk_fma_f32 v[34:35], v[34:35], v[42:43], v[118:119]
	v_pk_mul_f32 v[42:43], v[90:91], v[110:111] op_sel_hi:[0,1]
	v_pk_mul_f32 v[44:45], v[90:91], v[114:115] op_sel_hi:[0,1]
	v_pk_fma_f32 v[40:41], v[40:41], v[44:45], v[120:121]
	v_pk_fma_f32 v[38:39], v[38:39], v[42:43], v[116:117]
	global_load_dwordx4 v[42:45], v[66:67], off offset:2064
	global_load_dwordx4 v[46:49], v[66:67], off offset:2048
	s_waitcnt vmcnt(1)
	v_pk_fma_f32 v[44:45], v[44:45], v[94:95], v[104:105]
	s_waitcnt vmcnt(0)
	v_pk_fma_f32 v[48:49], v[48:49], v[92:93], v[106:107]
	v_pk_mul_f32 v[92:93], v[90:91], v[96:97] op_sel_hi:[0,1]
	v_pk_fma_f32 v[42:43], v[42:43], v[92:93], v[100:101]
	global_load_dwordx4 v[92:95], v[68:69], off offset:16
	global_load_dwordx4 v[96:99], v[68:69], off
	v_pk_fma_f32 v[46:47], v[46:47], v[108:109], v[102:103]
	s_waitcnt vmcnt(0)
	v_pk_fma_f32 v[50:51], v[96:97], v[50:51], v[62:63]
	v_mov_b32_e32 v62, v54
	v_mov_b32_e32 v63, v56
	v_mov_b32_e32 v56, v55
	v_pk_mul_f32 v[62:63], v[90:91], v[62:63] op_sel_hi:[0,1]
	v_pk_mul_f32 v[54:55], v[90:91], v[56:57] op_sel_hi:[0,1]
	v_pk_fma_f32 v[52:53], v[98:99], v[52:53], v[64:65]
	v_pk_fma_f32 v[56:57], v[94:95], v[54:55], v[60:61]
	v_pk_fma_f32 v[54:55], v[92:93], v[62:63], v[58:59]
	global_load_dwordx4 v[58:61], v[70:71], off offset:16
	global_load_dwordx4 v[62:65], v[70:71], off
	s_waitcnt vmcnt(1)
	v_pk_fma_f32 v[60:61], v[60:61], v[76:77], v[80:81]
	s_waitcnt vmcnt(0)
	v_pk_fma_f32 v[64:65], v[64:65], v[86:87], v[88:89]
	v_pk_fma_f32 v[62:63], v[62:63], v[82:83], v[84:85]
	v_pk_fma_f32 v[58:59], v[58:59], v[78:79], v[74:75]
	global_store_dwordx4 v[72:73], v[34:37], off offset:-4096 nt
	global_store_dwordx4 v[72:73], v[38:41], off offset:-4080 nt
	global_store_dwordx4 v[72:73], v[46:49], off offset:-2048 nt
	global_store_dwordx4 v[72:73], v[42:45], off offset:-2032 nt
	global_store_dwordx4 v[72:73], v[50:53], off nt
	global_store_dwordx4 v[72:73], v[54:57], off offset:16 nt
	global_store_dwordx4 v[72:73], v[62:65], off offset:2048 nt
	global_store_dwordx4 v[72:73], v[58:61], off offset:2064 nt
	v_mov_b64_e32 v[52:53], v[12:13]
	v_mov_b64_e32 v[44:45], v[20:21]
	v_mov_b64_e32 v[60:61], v[4:5]
	v_mov_b64_e32 v[36:37], v[24:25]
	v_mov_b64_e32 v[64:65], v[8:9]
	v_mov_b64_e32 v[56:57], v[16:17]
	v_mov_b64_e32 v[48:49], v[28:29]
	v_mov_b64_e32 v[40:41], v[32:33]
	v_lshl_add_u64 v[72:73], v[72:73], 0, s[22:23]
	v_mov_b64_e32 v[58:59], v[2:3]
	v_mov_b64_e32 v[50:51], v[10:11]
	v_mov_b64_e32 v[42:43], v[18:19]
	v_mov_b64_e32 v[34:35], v[22:23]
	v_mov_b64_e32 v[62:63], v[6:7]
	v_mov_b64_e32 v[54:55], v[14:15]
	v_mov_b64_e32 v[46:47], v[26:27]
	v_mov_b64_e32 v[38:39], v[30:31]
	s_cbranch_vccnz .LBB0_860
